# Signal the s_barrier that ends each 32-MFMA burst one MFMA early in all GEMM main loops (the burst touches no LDS) to hide part of the barrier release latency
# speedup vs baseline: 1.0085x; 1.0085x over previous
; #define PG8_STAGE(bufoff, gbase, voff) do { _Pragma("unroll") for (int _i = 0; _i < 2; ++_i) \
;         __builtin_amdgcn_global_load_lds((const unsigned*)((const char*)(gbase) + (voff)[_i]), (PG8_LAS unsigned*)(lds + (bufoff) + ldsw + _i * 8192), 16, 0, 0); } while (0)
; #define PG8_LDA(dst, b, h) do { _Pragma("unroll") for (int m = 0; m < 4; ++m) _Pragma("unroll") for (int k = 0; k < 2; ++k) dst[m][k] = *(const PG8_LAS bf16x8*)(lds + PG8_SA(b, h) + aoff + m * 2048 + k * 1024); } while (0)
; #define PG8_LDB(dst, b, h) do { _Pragma("unroll") for (int n = 0; n < 2; ++n) _Pragma("unroll") for (int k = 0; k < 2; ++k) dst[n][k] = *(const PG8_LAS bf16x8*)(lds + PG8_SB(b, h) + boff + n * 2048 + k * 1024); } while (0)
; #define PG8_MMA(ai, bj, At, Bt) do { __builtin_amdgcn_s_setprio(1); _Pragma("unroll") for (int m = 0; m < 4; ++m) _Pragma("unroll") for (int n = 0; n < 2; ++n) _Pragma("unroll") for (int k = 0; k < 2; ++k) \
;         acc[ai][bj][m][n] = __builtin_amdgcn_mfma_f32_16x16x32_bf16(Bt[n][k], At[m][k], acc[ai][bj][m][n], 0, 0, 0); __builtin_amdgcn_s_setprio(0); } while (0)
; #define PG8_WAIT_V(n) asm volatile("s_waitcnt vmcnt(" #n ")" ::: "memory")
; #define PG8_WAIT_L(n) asm volatile("s_waitcnt lgkmcnt(" #n ")" ::: "memory")
; #define PG8_BAR __builtin_amdgcn_s_barrier()
; #define PG8_SCHED __builtin_amdgcn_sched_barrier(0)
; template <class Epi, class Sched, bool ALIGN_EPI = false, bool SP2 = false>
; __device__ __forceinline__ void gemm_phase(PG8_LAS unsigned char* lds, const Gemm g, const Sched& S, const Epi& E) {
;     ...
;             PG8_LDB(B0, 0, 0); PG8_LDB(B1, 0, 1); PG8_SCHED; PG8_LDA(At, 0, 0); PG8_STAGE(PG8_SA(1, 1), a1 + hstep, voffA);
;             PG8_WAIT_V(8); PG8_WAIT_L(0); PG8_BAR; PG8_MMA(0, 0, At, B0); PG8_MMA(0, 1, At, B1); PG8_BAR; PG8_SCHED;
;             PG8_LDA(At, 0, 1); PG8_STAGE(PG8_SB(0, 0), b2, voffB); PG8_STAGE(PG8_SB(0, 1), b2 + hstep, voffB); PG8_STAGE(PG8_SA(0, 0), a2, voffA);
;             PG8_WAIT_V(8); PG8_WAIT_L(0); PG8_BAR; PG8_MMA(1, 0, At, B0); PG8_MMA(1, 1, At, B1); PG8_BAR; PG8_SCHED;
.LBB0_200:
	ds_read_b128 v[148:151], v164
	ds_read_b128 v[152:155], v164 offset:1024
	ds_read_b128 v[156:159], v164 offset:2048
	ds_read_b128 v[168:171], v164 offset:3072
	ds_read_b128 v[172:175], v165
	ds_read_b128 v[176:179], v165 offset:1024
	ds_read_b128 v[180:183], v165 offset:2048
	ds_read_b128 v[184:187], v165 offset:3072
	s_add_u32 s52, s70, 0xfff80080
	s_addc_u32 s53, s71, -1
	s_cmp_eq_u32 s93, 28
	s_cselect_b32 s75, s39, s53
	s_cselect_b32 s74, s69, s52
	s_cselect_b32 s73, s35, s92
	s_cselect_b32 s72, s90, s91
	v_lshl_add_u64 v[220:221], s[70:71], 0, v[138:139]
	s_add_i32 m0, s33, 0xc000
	ds_read_b128 v[188:191], v166
	ds_read_b128 v[192:195], v166 offset:1024
	ds_read_b128 v[196:199], v166 offset:2048
	ds_read_b128 v[200:203], v166 offset:3072
	ds_read_b128 v[204:207], v166 offset:4096
	ds_read_b128 v[208:211], v166 offset:5120
	ds_read_b128 v[212:215], v166 offset:6144
	ds_read_b128 v[216:219], v166 offset:7168
	global_load_lds_dwordx4 v[220:221], off
	v_lshl_add_u64 v[220:221], s[70:71], 0, v[140:141]
	s_add_i32 m0, s33, 0xe000
	s_nop 0
	global_load_lds_dwordx4 v[220:221], off
	s_waitcnt vmcnt(8)
	s_waitcnt lgkmcnt(0)
	s_barrier
	s_setprio 1
	s_waitcnt lgkmcnt(0)
	v_mfma_f32_16x16x32_bf16 v[124:127], v[148:151], v[188:191], v[124:127]
	v_mfma_f32_16x16x32_bf16 v[120:123], v[156:159], v[188:191], v[120:123]
	v_mfma_f32_16x16x32_bf16 v[116:119], v[148:151], v[196:199], v[116:119]
	v_mfma_f32_16x16x32_bf16 v[108:111], v[156:159], v[196:199], v[108:111]
	v_mfma_f32_16x16x32_bf16 v[100:103], v[148:151], v[204:207], v[100:103]
	v_mfma_f32_16x16x32_bf16 v[92:95], v[156:159], v[204:207], v[92:95]
	v_mfma_f32_16x16x32_bf16 v[84:87], v[148:151], v[212:215], v[84:87]
	v_mfma_f32_16x16x32_bf16 v[76:79], v[156:159], v[212:215], v[76:79]
	v_mfma_f32_16x16x32_bf16 v[124:127], v[152:155], v[192:195], v[124:127]
	v_mfma_f32_16x16x32_bf16 v[120:123], v[168:171], v[192:195], v[120:123]
	v_mfma_f32_16x16x32_bf16 v[116:119], v[152:155], v[200:203], v[116:119]
	v_mfma_f32_16x16x32_bf16 v[108:111], v[168:171], v[200:203], v[108:111]
	v_mfma_f32_16x16x32_bf16 v[100:103], v[152:155], v[208:211], v[100:103]
	v_mfma_f32_16x16x32_bf16 v[92:95], v[168:171], v[208:211], v[92:95]
	v_mfma_f32_16x16x32_bf16 v[84:87], v[152:155], v[216:219], v[84:87]
	v_mfma_f32_16x16x32_bf16 v[76:79], v[168:171], v[216:219], v[76:79]
	s_setprio 0
	s_setprio 1
	v_mfma_f32_16x16x32_bf16 v[112:115], v[172:175], v[188:191], v[112:115]
	v_mfma_f32_16x16x32_bf16 v[104:107], v[180:183], v[188:191], v[104:107]
	v_mfma_f32_16x16x32_bf16 v[96:99], v[172:175], v[196:199], v[96:99]
	v_mfma_f32_16x16x32_bf16 v[88:91], v[180:183], v[196:199], v[88:91]
	v_mfma_f32_16x16x32_bf16 v[80:83], v[172:175], v[204:207], v[80:83]
	v_mfma_f32_16x16x32_bf16 v[72:75], v[180:183], v[204:207], v[72:75]
	v_mfma_f32_16x16x32_bf16 v[68:71], v[172:175], v[212:215], v[68:71]
	v_mfma_f32_16x16x32_bf16 v[64:67], v[180:183], v[212:215], v[64:67]
	v_mfma_f32_16x16x32_bf16 v[112:115], v[176:179], v[192:195], v[112:115]
	v_mfma_f32_16x16x32_bf16 v[104:107], v[184:187], v[192:195], v[104:107]
	v_mfma_f32_16x16x32_bf16 v[96:99], v[176:179], v[200:203], v[96:99]
	v_mfma_f32_16x16x32_bf16 v[88:91], v[184:187], v[200:203], v[88:91]
	v_mfma_f32_16x16x32_bf16 v[80:83], v[176:179], v[208:211], v[80:83]
	v_mfma_f32_16x16x32_bf16 v[72:75], v[184:187], v[208:211], v[72:75]
	v_mfma_f32_16x16x32_bf16 v[68:71], v[176:179], v[216:219], v[68:71]
	s_barrier
	v_mfma_f32_16x16x32_bf16 v[64:67], v[184:187], v[216:219], v[64:67]
	s_setprio 0
	s_add_i32 s52, s84, s3
	v_lshl_add_u64 v[220:221], s[72:73], 0, v[132:133]
	s_mov_b32 m0, s52
	ds_read_b128 v[188:191], v166 offset:16384
	ds_read_b128 v[192:195], v166 offset:17408
	ds_read_b128 v[196:199], v166 offset:18432
	ds_read_b128 v[200:203], v166 offset:19456
	ds_read_b128 v[204:207], v166 offset:20480
	ds_read_b128 v[208:211], v166 offset:21504
	ds_read_b128 v[212:215], v166 offset:22528
	ds_read_b128 v[216:219], v166 offset:23552
	global_load_lds_dwordx4 v[220:221], off
	s_add_i32 m0, s52, 0x2000
	s_add_u32 s96, s72, 0x80000
	v_lshl_add_u64 v[222:223], s[72:73], 0, v[128:129]
	s_addc_u32 s97, s73, 0
	s_add_i32 s52, s85, s3
	global_load_lds_dwordx4 v[222:223], off
	v_lshl_add_u64 v[224:225], s[96:97], 0, v[132:133]
	s_mov_b32 m0, s52
	v_lshl_add_u64 v[226:227], s[74:75], 0, v[130:131]
	global_load_lds_dwordx4 v[224:225], off
	v_lshl_add_u64 v[224:225], s[96:97], 0, v[128:129]
	s_add_i32 m0, s52, 0x2000
	s_nop 0
	global_load_lds_dwordx4 v[224:225], off
	v_lshl_add_u64 v[224:225], s[74:75], 0, v[134:135]
	s_mov_b32 m0, s33
	s_nop 0
	global_load_lds_dwordx4 v[224:225], off
	s_mov_b32 m0, s76
	s_nop 0
	global_load_lds_dwordx4 v[226:227], off
	s_waitcnt vmcnt(8)
	s_waitcnt lgkmcnt(0)
	s_barrier
; #define PG8_STAGE(bufoff, gbase, voff) do { _Pragma("unroll") for (int _i = 0; _i < 2; ++_i) \
;         __builtin_amdgcn_global_load_lds((const unsigned*)((const char*)(gbase) + (voff)[_i]), (PG8_LAS unsigned*)(lds + (bufoff) + ldsw + _i * 8192), 16, 0, 0); } while (0)
; #define PG8_LDA(dst, b, h) do { _Pragma("unroll") for (int m = 0; m < 4; ++m) _Pragma("unroll") for (int k = 0; k < 2; ++k) dst[m][k] = *(const PG8_LAS bf16x8*)(lds + PG8_SA(b, h) + aoff + m * 2048 + k * 1024); } while (0)
; #define PG8_LDB(dst, b, h) do { _Pragma("unroll") for (int n = 0; n < 2; ++n) _Pragma("unroll") for (int k = 0; k < 2; ++k) dst[n][k] = *(const PG8_LAS bf16x8*)(lds + PG8_SB(b, h) + boff + n * 2048 + k * 1024); } while (0)
; #define PG8_MMA(ai, bj, At, Bt) do { __builtin_amdgcn_s_setprio(1); _Pragma("unroll") for (int m = 0; m < 4; ++m) _Pragma("unroll") for (int n = 0; n < 2; ++n) _Pragma("unroll") for (int k = 0; k < 2; ++k) \
;         acc[ai][bj][m][n] = __builtin_amdgcn_mfma_f32_16x16x32_bf16(Bt[n][k], At[m][k], acc[ai][bj][m][n], 0, 0, 0); __builtin_amdgcn_s_setprio(0); } while (0)
; #define PG8_WAIT_V(n) asm volatile("s_waitcnt vmcnt(" #n ")" ::: "memory")
; #define PG8_WAIT_L(n) asm volatile("s_waitcnt lgkmcnt(" #n ")" ::: "memory")
; #define PG8_BAR __builtin_amdgcn_s_barrier()
; #define PG8_SCHED __builtin_amdgcn_sched_barrier(0)
; template <class Epi, class Sched, bool ALIGN_EPI = false, bool SP2 = false>
; __device__ __forceinline__ void gemm_phase(PG8_LAS unsigned char* lds, const Gemm g, const Sched& S, const Epi& E) {
;     ...
;             PG8_WAIT_V(8); PG8_WAIT_L(0); PG8_BAR; PG8_MMA(1, 0, At, B0); PG8_MMA(1, 1, At, B1); PG8_BAR; PG8_SCHED;
;             PG8_LDB(B0, 1, 0); PG8_LDB(B1, 1, 1); PG8_SCHED; PG8_LDA(At, 1, 0); PG8_STAGE(PG8_SA(0, 1), a2 + hstep, voffA);
;             PG8_WAIT_V(8); PG8_WAIT_L(0); PG8_BAR; PG8_MMA(0, 0, At, B0); PG8_MMA(0, 1, At, B1); PG8_BAR; PG8_SCHED;
;             PG8_LDA(At, 1, 1); PG8_STAGE(PG8_SB(1, 0), b3, voffB); PG8_STAGE(PG8_SB(1, 1), b3 + hstep, voffB); PG8_STAGE(PG8_SA(1, 0), a3, voffA);
	s_setprio 1
	s_waitcnt lgkmcnt(0)
	v_mfma_f32_16x16x32_bf16 v[60:63], v[148:151], v[188:191], v[60:63]
	v_mfma_f32_16x16x32_bf16 v[56:59], v[156:159], v[188:191], v[56:59]
	v_mfma_f32_16x16x32_bf16 v[52:55], v[148:151], v[196:199], v[52:55]
	v_mfma_f32_16x16x32_bf16 v[44:47], v[156:159], v[196:199], v[44:47]
	v_mfma_f32_16x16x32_bf16 v[36:39], v[148:151], v[204:207], v[36:39]
	v_mfma_f32_16x16x32_bf16 v[28:31], v[156:159], v[204:207], v[28:31]
	v_mfma_f32_16x16x32_bf16 v[20:23], v[148:151], v[212:215], v[20:23]
	v_mfma_f32_16x16x32_bf16 v[12:15], v[156:159], v[212:215], v[12:15]
	v_mfma_f32_16x16x32_bf16 v[60:63], v[152:155], v[192:195], v[60:63]
	v_mfma_f32_16x16x32_bf16 v[56:59], v[168:171], v[192:195], v[56:59]
	v_mfma_f32_16x16x32_bf16 v[52:55], v[152:155], v[200:203], v[52:55]
	v_mfma_f32_16x16x32_bf16 v[44:47], v[168:171], v[200:203], v[44:47]
	v_mfma_f32_16x16x32_bf16 v[36:39], v[152:155], v[208:211], v[36:39]
	v_mfma_f32_16x16x32_bf16 v[28:31], v[168:171], v[208:211], v[28:31]
	v_mfma_f32_16x16x32_bf16 v[20:23], v[152:155], v[216:219], v[20:23]
	v_mfma_f32_16x16x32_bf16 v[12:15], v[168:171], v[216:219], v[12:15]
	s_setprio 0
	s_setprio 1
	v_mfma_f32_16x16x32_bf16 v[48:51], v[172:175], v[188:191], v[48:51]
	v_mfma_f32_16x16x32_bf16 v[40:43], v[180:183], v[188:191], v[40:43]
	v_mfma_f32_16x16x32_bf16 v[32:35], v[172:175], v[196:199], v[32:35]
	v_mfma_f32_16x16x32_bf16 v[24:27], v[180:183], v[196:199], v[24:27]
	v_mfma_f32_16x16x32_bf16 v[16:19], v[172:175], v[204:207], v[16:19]
	v_mfma_f32_16x16x32_bf16 v[8:11], v[180:183], v[204:207], v[8:11]
	v_mfma_f32_16x16x32_bf16 v[4:7], v[172:175], v[212:215], v[4:7]
	v_mfma_f32_16x16x32_bf16 v[0:3], v[180:183], v[212:215], v[0:3]
	v_mfma_f32_16x16x32_bf16 v[48:51], v[176:179], v[192:195], v[48:51]
	v_mfma_f32_16x16x32_bf16 v[40:43], v[184:187], v[192:195], v[40:43]
	v_mfma_f32_16x16x32_bf16 v[32:35], v[176:179], v[200:203], v[32:35]
	v_mfma_f32_16x16x32_bf16 v[24:27], v[184:187], v[200:203], v[24:27]
	v_mfma_f32_16x16x32_bf16 v[16:19], v[176:179], v[208:211], v[16:19]
	v_mfma_f32_16x16x32_bf16 v[8:11], v[184:187], v[208:211], v[8:11]
	v_mfma_f32_16x16x32_bf16 v[4:7], v[176:179], v[216:219], v[4:7]
	s_barrier
	v_mfma_f32_16x16x32_bf16 v[0:3], v[184:187], v[216:219], v[0:3]
	s_setprio 0
	s_add_i32 s52, 0, 0x18000
	v_add_u32_e32 v136, s52, v161
	s_add_i32 s53, 0, 0x1c000
	ds_read_b128 v[148:151], v136
	ds_read_b128 v[152:155], v136 offset:1024
	ds_read_b128 v[156:159], v136 offset:2048
	ds_read_b128 v[168:171], v136 offset:3072
	v_add_u32_e32 v136, s53, v161
	ds_read_b128 v[172:175], v136
	ds_read_b128 v[176:179], v136 offset:1024
	ds_read_b128 v[180:183], v136 offset:2048
	ds_read_b128 v[184:187], v136 offset:3072
	s_add_u32 s74, s74, 0x80000
	s_addc_u32 s75, s75, 0
	s_mov_b32 m0, s77
	v_lshl_add_u64 v[228:229], s[74:75], 0, v[134:135]
	ds_read_b128 v[188:191], v166 offset:32768
	ds_read_b128 v[192:195], v166 offset:33792
	ds_read_b128 v[196:199], v166 offset:34816
	ds_read_b128 v[200:203], v166 offset:35840
	ds_read_b128 v[204:207], v166 offset:36864
	ds_read_b128 v[208:211], v166 offset:37888
	ds_read_b128 v[212:215], v166 offset:38912
	ds_read_b128 v[216:219], v166 offset:39936
	global_load_lds_dwordx4 v[228:229], off
	v_lshl_add_u64 v[228:229], s[74:75], 0, v[130:131]
	s_mov_b32 m0, s78
	s_nop 0
	global_load_lds_dwordx4 v[228:229], off
	s_waitcnt vmcnt(8)
	s_waitcnt lgkmcnt(0)
	s_barrier
	s_setprio 1
	s_waitcnt lgkmcnt(0)
	v_mfma_f32_16x16x32_bf16 v[124:127], v[148:151], v[188:191], v[124:127]
	v_mfma_f32_16x16x32_bf16 v[120:123], v[156:159], v[188:191], v[120:123]
	v_mfma_f32_16x16x32_bf16 v[116:119], v[148:151], v[196:199], v[116:119]
	v_mfma_f32_16x16x32_bf16 v[108:111], v[156:159], v[196:199], v[108:111]
	v_mfma_f32_16x16x32_bf16 v[100:103], v[148:151], v[204:207], v[100:103]
	v_mfma_f32_16x16x32_bf16 v[92:95], v[156:159], v[204:207], v[92:95]
	v_mfma_f32_16x16x32_bf16 v[84:87], v[148:151], v[212:215], v[84:87]
	v_mfma_f32_16x16x32_bf16 v[76:79], v[156:159], v[212:215], v[76:79]
	v_mfma_f32_16x16x32_bf16 v[124:127], v[152:155], v[192:195], v[124:127]
	v_mfma_f32_16x16x32_bf16 v[120:123], v[168:171], v[192:195], v[120:123]
	v_mfma_f32_16x16x32_bf16 v[116:119], v[152:155], v[200:203], v[116:119]
	v_mfma_f32_16x16x32_bf16 v[108:111], v[168:171], v[200:203], v[108:111]
	v_mfma_f32_16x16x32_bf16 v[100:103], v[152:155], v[208:211], v[100:103]
	v_mfma_f32_16x16x32_bf16 v[92:95], v[168:171], v[208:211], v[92:95]
	v_mfma_f32_16x16x32_bf16 v[84:87], v[152:155], v[216:219], v[84:87]
	v_mfma_f32_16x16x32_bf16 v[76:79], v[168:171], v[216:219], v[76:79]
	s_setprio 0
	s_setprio 1
	v_mfma_f32_16x16x32_bf16 v[112:115], v[172:175], v[188:191], v[112:115]
	v_mfma_f32_16x16x32_bf16 v[104:107], v[180:183], v[188:191], v[104:107]
	v_mfma_f32_16x16x32_bf16 v[96:99], v[172:175], v[196:199], v[96:99]
	v_mfma_f32_16x16x32_bf16 v[88:91], v[180:183], v[196:199], v[88:91]
	v_mfma_f32_16x16x32_bf16 v[80:83], v[172:175], v[204:207], v[80:83]
	v_mfma_f32_16x16x32_bf16 v[72:75], v[180:183], v[204:207], v[72:75]
	v_mfma_f32_16x16x32_bf16 v[68:71], v[172:175], v[212:215], v[68:71]
	v_mfma_f32_16x16x32_bf16 v[64:67], v[180:183], v[212:215], v[64:67]
	v_mfma_f32_16x16x32_bf16 v[112:115], v[176:179], v[192:195], v[112:115]
	v_mfma_f32_16x16x32_bf16 v[104:107], v[184:187], v[192:195], v[104:107]
	v_mfma_f32_16x16x32_bf16 v[96:99], v[176:179], v[200:203], v[96:99]
	v_mfma_f32_16x16x32_bf16 v[88:91], v[184:187], v[200:203], v[88:91]
	v_mfma_f32_16x16x32_bf16 v[80:83], v[176:179], v[208:211], v[80:83]
	v_mfma_f32_16x16x32_bf16 v[72:75], v[184:187], v[208:211], v[72:75]
	v_mfma_f32_16x16x32_bf16 v[68:71], v[176:179], v[216:219], v[68:71]
	s_barrier
; #define PG8_STAGE(bufoff, gbase, voff) do { _Pragma("unroll") for (int _i = 0; _i < 2; ++_i) \
;         __builtin_amdgcn_global_load_lds((const unsigned*)((const char*)(gbase) + (voff)[_i]), (PG8_LAS unsigned*)(lds + (bufoff) + ldsw + _i * 8192), 16, 0, 0); } while (0)
; #define PG8_LDA(dst, b, h) do { _Pragma("unroll") for (int m = 0; m < 4; ++m) _Pragma("unroll") for (int k = 0; k < 2; ++k) dst[m][k] = *(const PG8_LAS bf16x8*)(lds + PG8_SA(b, h) + aoff + m * 2048 + k * 1024); } while (0)
; #define PG8_MMA(ai, bj, At, Bt) do { __builtin_amdgcn_s_setprio(1); _Pragma("unroll") for (int m = 0; m < 4; ++m) _Pragma("unroll") for (int n = 0; n < 2; ++n) _Pragma("unroll") for (int k = 0; k < 2; ++k) \
;         acc[ai][bj][m][n] = __builtin_amdgcn_mfma_f32_16x16x32_bf16(Bt[n][k], At[m][k], acc[ai][bj][m][n], 0, 0, 0); __builtin_amdgcn_s_setprio(0); } while (0)
; #define PG8_WAIT_V(n) asm volatile("s_waitcnt vmcnt(" #n ")" ::: "memory")
; #define PG8_WAIT_L(n) asm volatile("s_waitcnt lgkmcnt(" #n ")" ::: "memory")
; #define PG8_BAR __builtin_amdgcn_s_barrier()
; #define PG8_SCHED __builtin_amdgcn_sched_barrier(0)
; template <class Epi, class Sched, bool ALIGN_EPI = false, bool SP2 = false>
; __device__ __forceinline__ void gemm_phase(PG8_LAS unsigned char* lds, const Gemm g, const Sched& S, const Epi& E) {
;     ...
;             PG8_LDA(At, 1, 1); PG8_STAGE(PG8_SB(1, 0), b3, voffB); PG8_STAGE(PG8_SB(1, 1), b3 + hstep, voffB); PG8_STAGE(PG8_SA(1, 0), a3, voffA);
;             PG8_WAIT_V(8); PG8_WAIT_L(0); PG8_BAR; PG8_MMA(1, 0, At, B0); PG8_MMA(1, 1, At, B1); PG8_BAR; PG8_SCHED;
	v_mfma_f32_16x16x32_bf16 v[64:67], v[184:187], v[216:219], v[64:67]
	s_setprio 0
	s_add_i32 s52, s52, s3
	v_lshl_add_u64 v[220:221], v[220:221], 0, s[12:13]
	s_mov_b32 m0, s52
	ds_read_b128 v[188:191], v166 offset:49152
	ds_read_b128 v[192:195], v166 offset:50176
	ds_read_b128 v[196:199], v166 offset:51200
	ds_read_b128 v[200:203], v166 offset:52224
	ds_read_b128 v[204:207], v166 offset:53248
	ds_read_b128 v[208:211], v166 offset:54272
	ds_read_b128 v[212:215], v166 offset:55296
	ds_read_b128 v[216:219], v166 offset:56320
	global_load_lds_dwordx4 v[220:221], off
	s_add_i32 m0, s52, 0x2000
	s_add_u32 s72, s72, 0x80080
	v_lshl_add_u64 v[220:221], v[222:223], 0, s[12:13]
	s_addc_u32 s73, s73, 0
	s_add_i32 s52, s53, s3
	global_load_lds_dwordx4 v[220:221], off
	v_lshl_add_u64 v[220:221], s[72:73], 0, v[132:133]
	s_mov_b32 m0, s52
	s_nop 0
	global_load_lds_dwordx4 v[220:221], off
	v_lshl_add_u64 v[220:221], s[72:73], 0, v[128:129]
	s_add_i32 m0, s52, 0x2000
	s_nop 0
	global_load_lds_dwordx4 v[220:221], off
	v_lshl_add_u64 v[220:221], v[224:225], 0, s[12:13]
	s_mov_b32 m0, s80
	s_nop 0
	global_load_lds_dwordx4 v[220:221], off
	v_lshl_add_u64 v[220:221], v[226:227], 0, s[12:13]
	s_mov_b32 m0, s81
	s_nop 0
	global_load_lds_dwordx4 v[220:221], off
	s_waitcnt vmcnt(8)
	s_waitcnt lgkmcnt(0)
	s_barrier
	s_setprio 1
	s_waitcnt lgkmcnt(0)
	v_mfma_f32_16x16x32_bf16 v[60:63], v[148:151], v[188:191], v[60:63]
	v_mfma_f32_16x16x32_bf16 v[56:59], v[156:159], v[188:191], v[56:59]
	v_mfma_f32_16x16x32_bf16 v[52:55], v[148:151], v[196:199], v[52:55]
	v_mfma_f32_16x16x32_bf16 v[44:47], v[156:159], v[196:199], v[44:47]
	v_mfma_f32_16x16x32_bf16 v[36:39], v[148:151], v[204:207], v[36:39]
	v_mfma_f32_16x16x32_bf16 v[28:31], v[156:159], v[204:207], v[28:31]
	v_mfma_f32_16x16x32_bf16 v[20:23], v[148:151], v[212:215], v[20:23]
	v_mfma_f32_16x16x32_bf16 v[12:15], v[156:159], v[212:215], v[12:15]
	v_mfma_f32_16x16x32_bf16 v[60:63], v[152:155], v[192:195], v[60:63]
	v_mfma_f32_16x16x32_bf16 v[56:59], v[168:171], v[192:195], v[56:59]
	v_mfma_f32_16x16x32_bf16 v[52:55], v[152:155], v[200:203], v[52:55]
	v_mfma_f32_16x16x32_bf16 v[44:47], v[168:171], v[200:203], v[44:47]
	v_mfma_f32_16x16x32_bf16 v[36:39], v[152:155], v[208:211], v[36:39]
	v_mfma_f32_16x16x32_bf16 v[28:31], v[168:171], v[208:211], v[28:31]
	v_mfma_f32_16x16x32_bf16 v[20:23], v[152:155], v[216:219], v[20:23]
	v_mfma_f32_16x16x32_bf16 v[12:15], v[168:171], v[216:219], v[12:15]
	s_setprio 0
	s_setprio 1
	v_mfma_f32_16x16x32_bf16 v[48:51], v[172:175], v[188:191], v[48:51]
	v_mfma_f32_16x16x32_bf16 v[40:43], v[180:183], v[188:191], v[40:43]
	v_mfma_f32_16x16x32_bf16 v[32:35], v[172:175], v[196:199], v[32:35]
	v_mfma_f32_16x16x32_bf16 v[24:27], v[180:183], v[196:199], v[24:27]
	v_mfma_f32_16x16x32_bf16 v[16:19], v[172:175], v[204:207], v[16:19]
	v_mfma_f32_16x16x32_bf16 v[8:11], v[180:183], v[204:207], v[8:11]
	v_mfma_f32_16x16x32_bf16 v[4:7], v[172:175], v[212:215], v[4:7]
	v_mfma_f32_16x16x32_bf16 v[0:3], v[180:183], v[212:215], v[0:3]
	v_mfma_f32_16x16x32_bf16 v[48:51], v[176:179], v[192:195], v[48:51]
	v_mfma_f32_16x16x32_bf16 v[40:43], v[184:187], v[192:195], v[40:43]
	v_mfma_f32_16x16x32_bf16 v[32:35], v[176:179], v[200:203], v[32:35]
	v_mfma_f32_16x16x32_bf16 v[24:27], v[184:187], v[200:203], v[24:27]
	v_mfma_f32_16x16x32_bf16 v[16:19], v[176:179], v[208:211], v[16:19]
	v_mfma_f32_16x16x32_bf16 v[8:11], v[184:187], v[208:211], v[8:11]
	v_mfma_f32_16x16x32_bf16 v[4:7], v[176:179], v[216:219], v[4:7]
	s_barrier
	v_mfma_f32_16x16x32_bf16 v[0:3], v[184:187], v[216:219], v[0:3]
	s_setprio 0
	s_add_i32 s93, s93, 2
	s_add_u32 s70, s70, 0x100
	s_addc_u32 s71, s71, 0
	s_add_u32 s91, s91, 0x100
	s_addc_u32 s92, s92, 0
	s_cmp_gt_u32 s93, 29
	s_cbranch_scc0 .LBB0_200
	s_and_b64 vcc, exec, s[14:15]
	s_cbranch_vccz .LBB0_203
	s_barrier

; #define PG8_STAGE(bufoff, gbase, voff) do { _Pragma("unroll") for (int _i = 0; _i < 2; ++_i) \
;         __builtin_amdgcn_global_load_lds((const unsigned*)((const char*)(gbase) + (voff)[_i]), (PG8_LAS unsigned*)(lds + (bufoff) + ldsw + _i * 8192), 16, 0, 0); } while (0)
; #define PG8_LDA(dst, b, h) do { _Pragma("unroll") for (int m = 0; m < 4; ++m) _Pragma("unroll") for (int k = 0; k < 2; ++k) dst[m][k] = *(const PG8_LAS bf16x8*)(lds + PG8_SA(b, h) + aoff + m * 2048 + k * 1024); } while (0)
; #define PG8_LDB(dst, b, h) do { _Pragma("unroll") for (int n = 0; n < 2; ++n) _Pragma("unroll") for (int k = 0; k < 2; ++k) dst[n][k] = *(const PG8_LAS bf16x8*)(lds + PG8_SB(b, h) + boff + n * 2048 + k * 1024); } while (0)
; #define PG8_MMA(ai, bj, At, Bt) do { __builtin_amdgcn_s_setprio(1); _Pragma("unroll") for (int m = 0; m < 4; ++m) _Pragma("unroll") for (int n = 0; n < 2; ++n) _Pragma("unroll") for (int k = 0; k < 2; ++k) \
;         acc[ai][bj][m][n] = __builtin_amdgcn_mfma_f32_16x16x32_bf16(Bt[n][k], At[m][k], acc[ai][bj][m][n], 0, 0, 0); __builtin_amdgcn_s_setprio(0); } while (0)
; #define PG8_WAIT_V(n) asm volatile("s_waitcnt vmcnt(" #n ")" ::: "memory")
; #define PG8_WAIT_L(n) asm volatile("s_waitcnt lgkmcnt(" #n ")" ::: "memory")
; #define PG8_BAR __builtin_amdgcn_s_barrier()
; #define PG8_SCHED __builtin_amdgcn_sched_barrier(0)
; template <class Epi, class Sched, bool ALIGN_EPI = false, bool SP2 = false>
; __device__ __forceinline__ void gemm_phase(PG8_LAS unsigned char* lds, const Gemm g, const Sched& S, const Epi& E) {
;     ...
;             PG8_LDB(B0, 0, 0); PG8_LDB(B1, 0, 1); PG8_SCHED; PG8_LDA(At, 0, 0); PG8_STAGE(PG8_SA(1, 1), a1 + hstep, voffA);
;             PG8_WAIT_V(8); PG8_WAIT_L(0); PG8_BAR; PG8_MMA(0, 0, At, B0); PG8_MMA(0, 1, At, B1); PG8_BAR; PG8_SCHED;
;             PG8_LDA(At, 0, 1); PG8_STAGE(PG8_SB(0, 0), b2, voffB); PG8_STAGE(PG8_SB(0, 1), b2 + hstep, voffB); PG8_STAGE(PG8_SA(0, 0), a2, voffA);
;             PG8_WAIT_V(8); PG8_WAIT_L(0); PG8_BAR; PG8_MMA(1, 0, At, B0); PG8_MMA(1, 1, At, B1); PG8_BAR; PG8_SCHED;
.LBB0_374:
	ds_read_b128 v[128:131], v230
	ds_read_b128 v[132:135], v230 offset:1024
	ds_read_b128 v[158:161], v230 offset:2048
	ds_read_b128 v[162:165], v230 offset:3072
	ds_read_b128 v[166:169], v231
	ds_read_b128 v[170:173], v231 offset:1024
	ds_read_b128 v[174:177], v231 offset:2048
	ds_read_b128 v[178:181], v231 offset:3072
	s_add_u32 s52, s76, 0xfff80080
	s_addc_u32 s53, s77, -1
	s_cmp_eq_u32 vcc_hi, 28
	s_cselect_b32 s81, s11, s53
	s_cselect_b32 s80, s55, s52
	s_cselect_b32 s79, s51, vcc_lo
	s_cselect_b32 s78, s73, s75
	v_lshl_add_u64 v[214:215], s[76:77], 0, v[150:151]
	s_add_i32 m0, s28, 0xc000
	ds_read_b128 v[182:185], v232
	ds_read_b128 v[186:189], v232 offset:1024
	ds_read_b128 v[190:193], v232 offset:2048
	ds_read_b128 v[194:197], v232 offset:3072
	ds_read_b128 v[198:201], v232 offset:4096
	ds_read_b128 v[202:205], v232 offset:5120
	ds_read_b128 v[206:209], v232 offset:6144
	ds_read_b128 v[210:213], v232 offset:7168
	global_load_lds_dwordx4 v[214:215], off
	v_lshl_add_u64 v[214:215], s[76:77], 0, v[152:153]
	s_add_i32 m0, s28, 0xe000
	s_nop 0
	global_load_lds_dwordx4 v[214:215], off
	s_waitcnt vmcnt(8)
	s_waitcnt lgkmcnt(0)
	s_barrier
	s_setprio 1
	s_waitcnt lgkmcnt(0)
	v_mfma_f32_16x16x32_bf16 v[124:127], v[128:131], v[182:185], v[124:127]
	v_mfma_f32_16x16x32_bf16 v[120:123], v[158:161], v[182:185], v[120:123]
	v_mfma_f32_16x16x32_bf16 v[116:119], v[128:131], v[190:193], v[116:119]
	v_mfma_f32_16x16x32_bf16 v[112:115], v[158:161], v[190:193], v[112:115]
	v_mfma_f32_16x16x32_bf16 v[108:111], v[128:131], v[198:201], v[108:111]
	v_mfma_f32_16x16x32_bf16 v[104:107], v[158:161], v[198:201], v[104:107]
	v_mfma_f32_16x16x32_bf16 v[100:103], v[128:131], v[206:209], v[100:103]
	v_mfma_f32_16x16x32_bf16 v[96:99], v[158:161], v[206:209], v[96:99]
	v_mfma_f32_16x16x32_bf16 v[124:127], v[132:135], v[186:189], v[124:127]
	v_mfma_f32_16x16x32_bf16 v[120:123], v[162:165], v[186:189], v[120:123]
	v_mfma_f32_16x16x32_bf16 v[116:119], v[132:135], v[194:197], v[116:119]
	v_mfma_f32_16x16x32_bf16 v[112:115], v[162:165], v[194:197], v[112:115]
	v_mfma_f32_16x16x32_bf16 v[108:111], v[132:135], v[202:205], v[108:111]
	v_mfma_f32_16x16x32_bf16 v[104:107], v[162:165], v[202:205], v[104:107]
	v_mfma_f32_16x16x32_bf16 v[100:103], v[132:135], v[210:213], v[100:103]
	v_mfma_f32_16x16x32_bf16 v[96:99], v[162:165], v[210:213], v[96:99]
	s_setprio 0
	s_setprio 1
	v_mfma_f32_16x16x32_bf16 v[60:63], v[166:169], v[182:185], v[60:63]
	v_mfma_f32_16x16x32_bf16 v[56:59], v[174:177], v[182:185], v[56:59]
	v_mfma_f32_16x16x32_bf16 v[52:55], v[166:169], v[190:193], v[52:55]
	v_mfma_f32_16x16x32_bf16 v[48:51], v[174:177], v[190:193], v[48:51]
	v_mfma_f32_16x16x32_bf16 v[44:47], v[166:169], v[198:201], v[44:47]
	v_mfma_f32_16x16x32_bf16 v[40:43], v[174:177], v[198:201], v[40:43]
	v_mfma_f32_16x16x32_bf16 v[36:39], v[166:169], v[206:209], v[36:39]
	v_mfma_f32_16x16x32_bf16 v[32:35], v[174:177], v[206:209], v[32:35]
	v_mfma_f32_16x16x32_bf16 v[60:63], v[170:173], v[186:189], v[60:63]
	v_mfma_f32_16x16x32_bf16 v[56:59], v[178:181], v[186:189], v[56:59]
	v_mfma_f32_16x16x32_bf16 v[52:55], v[170:173], v[194:197], v[52:55]
	v_mfma_f32_16x16x32_bf16 v[48:51], v[178:181], v[194:197], v[48:51]
	v_mfma_f32_16x16x32_bf16 v[44:47], v[170:173], v[202:205], v[44:47]
	v_mfma_f32_16x16x32_bf16 v[40:43], v[178:181], v[202:205], v[40:43]
	v_mfma_f32_16x16x32_bf16 v[36:39], v[170:173], v[210:213], v[36:39]
	s_barrier
	v_mfma_f32_16x16x32_bf16 v[32:35], v[178:181], v[210:213], v[32:35]
	s_setprio 0
	s_add_i32 s52, s93, s3
	v_lshl_add_u64 v[214:215], s[78:79], 0, v[138:139]
	s_mov_b32 m0, s52
	ds_read_b128 v[182:185], v232 offset:16384
	ds_read_b128 v[186:189], v232 offset:17408
	ds_read_b128 v[190:193], v232 offset:18432
	ds_read_b128 v[194:197], v232 offset:19456
	ds_read_b128 v[198:201], v232 offset:20480
	ds_read_b128 v[202:205], v232 offset:21504
	ds_read_b128 v[206:209], v232 offset:22528
	ds_read_b128 v[210:213], v232 offset:23552
	global_load_lds_dwordx4 v[214:215], off
	s_add_i32 m0, s52, 0x2000
	s_add_u32 s52, s78, 0x80000
	v_lshl_add_u64 v[216:217], s[78:79], 0, v[142:143]
	s_addc_u32 s53, s79, 0
	s_add_i32 s56, s10, s3
	global_load_lds_dwordx4 v[216:217], off
	v_lshl_add_u64 v[218:219], s[52:53], 0, v[138:139]
	s_mov_b32 m0, s56
	v_lshl_add_u64 v[220:221], s[80:81], 0, v[140:141]
	global_load_lds_dwordx4 v[218:219], off
	v_lshl_add_u64 v[218:219], s[52:53], 0, v[142:143]
	s_add_i32 m0, s56, 0x2000
	s_nop 0
	global_load_lds_dwordx4 v[218:219], off
	v_lshl_add_u64 v[218:219], s[80:81], 0, v[136:137]
	s_mov_b32 m0, s28
	s_nop 0
	global_load_lds_dwordx4 v[218:219], off
	s_mov_b32 m0, s29
	s_nop 0
	global_load_lds_dwordx4 v[220:221], off
	s_waitcnt vmcnt(8)
	s_waitcnt lgkmcnt(0)
	s_barrier
; #define PG8_STAGE(bufoff, gbase, voff) do { _Pragma("unroll") for (int _i = 0; _i < 2; ++_i) \
;         __builtin_amdgcn_global_load_lds((const unsigned*)((const char*)(gbase) + (voff)[_i]), (PG8_LAS unsigned*)(lds + (bufoff) + ldsw + _i * 8192), 16, 0, 0); } while (0)
; #define PG8_LDA(dst, b, h) do { _Pragma("unroll") for (int m = 0; m < 4; ++m) _Pragma("unroll") for (int k = 0; k < 2; ++k) dst[m][k] = *(const PG8_LAS bf16x8*)(lds + PG8_SA(b, h) + aoff + m * 2048 + k * 1024); } while (0)
; #define PG8_LDB(dst, b, h) do { _Pragma("unroll") for (int n = 0; n < 2; ++n) _Pragma("unroll") for (int k = 0; k < 2; ++k) dst[n][k] = *(const PG8_LAS bf16x8*)(lds + PG8_SB(b, h) + boff + n * 2048 + k * 1024); } while (0)
; #define PG8_MMA(ai, bj, At, Bt) do { __builtin_amdgcn_s_setprio(1); _Pragma("unroll") for (int m = 0; m < 4; ++m) _Pragma("unroll") for (int n = 0; n < 2; ++n) _Pragma("unroll") for (int k = 0; k < 2; ++k) \
;         acc[ai][bj][m][n] = __builtin_amdgcn_mfma_f32_16x16x32_bf16(Bt[n][k], At[m][k], acc[ai][bj][m][n], 0, 0, 0); __builtin_amdgcn_s_setprio(0); } while (0)
; #define PG8_WAIT_V(n) asm volatile("s_waitcnt vmcnt(" #n ")" ::: "memory")
; #define PG8_WAIT_L(n) asm volatile("s_waitcnt lgkmcnt(" #n ")" ::: "memory")
; #define PG8_BAR __builtin_amdgcn_s_barrier()
; #define PG8_SCHED __builtin_amdgcn_sched_barrier(0)
; template <class Epi, class Sched, bool ALIGN_EPI = false, bool SP2 = false>
; __device__ __forceinline__ void gemm_phase(PG8_LAS unsigned char* lds, const Gemm g, const Sched& S, const Epi& E) {
;     ...
;             PG8_WAIT_V(8); PG8_WAIT_L(0); PG8_BAR; PG8_MMA(1, 0, At, B0); PG8_MMA(1, 1, At, B1); PG8_BAR; PG8_SCHED;
;             PG8_LDB(B0, 1, 0); PG8_LDB(B1, 1, 1); PG8_SCHED; PG8_LDA(At, 1, 0); PG8_STAGE(PG8_SA(0, 1), a2 + hstep, voffA);
;             PG8_WAIT_V(8); PG8_WAIT_L(0); PG8_BAR; PG8_MMA(0, 0, At, B0); PG8_MMA(0, 1, At, B1); PG8_BAR; PG8_SCHED;
;             PG8_LDA(At, 1, 1); PG8_STAGE(PG8_SB(1, 0), b3, voffB); PG8_STAGE(PG8_SB(1, 1), b3 + hstep, voffB); PG8_STAGE(PG8_SA(1, 0), a3, voffA);
	s_setprio 1
	s_waitcnt lgkmcnt(0)
	v_mfma_f32_16x16x32_bf16 v[92:95], v[128:131], v[182:185], v[92:95]
	v_mfma_f32_16x16x32_bf16 v[88:91], v[158:161], v[182:185], v[88:91]
	v_mfma_f32_16x16x32_bf16 v[84:87], v[128:131], v[190:193], v[84:87]
	v_mfma_f32_16x16x32_bf16 v[80:83], v[158:161], v[190:193], v[80:83]
	v_mfma_f32_16x16x32_bf16 v[76:79], v[128:131], v[198:201], v[76:79]
	v_mfma_f32_16x16x32_bf16 v[72:75], v[158:161], v[198:201], v[72:75]
	v_mfma_f32_16x16x32_bf16 v[68:71], v[128:131], v[206:209], v[68:71]
	v_mfma_f32_16x16x32_bf16 v[64:67], v[158:161], v[206:209], v[64:67]
	v_mfma_f32_16x16x32_bf16 v[92:95], v[132:135], v[186:189], v[92:95]
	v_mfma_f32_16x16x32_bf16 v[88:91], v[162:165], v[186:189], v[88:91]
	v_mfma_f32_16x16x32_bf16 v[84:87], v[132:135], v[194:197], v[84:87]
	v_mfma_f32_16x16x32_bf16 v[80:83], v[162:165], v[194:197], v[80:83]
	v_mfma_f32_16x16x32_bf16 v[76:79], v[132:135], v[202:205], v[76:79]
	v_mfma_f32_16x16x32_bf16 v[72:75], v[162:165], v[202:205], v[72:75]
	v_mfma_f32_16x16x32_bf16 v[68:71], v[132:135], v[210:213], v[68:71]
	v_mfma_f32_16x16x32_bf16 v[64:67], v[162:165], v[210:213], v[64:67]
	s_setprio 0
	s_setprio 1
	v_mfma_f32_16x16x32_bf16 v[28:31], v[166:169], v[182:185], v[28:31]
	v_mfma_f32_16x16x32_bf16 v[24:27], v[174:177], v[182:185], v[24:27]
	v_mfma_f32_16x16x32_bf16 v[20:23], v[166:169], v[190:193], v[20:23]
	v_mfma_f32_16x16x32_bf16 v[16:19], v[174:177], v[190:193], v[16:19]
	v_mfma_f32_16x16x32_bf16 v[12:15], v[166:169], v[198:201], v[12:15]
	v_mfma_f32_16x16x32_bf16 v[8:11], v[174:177], v[198:201], v[8:11]
	v_mfma_f32_16x16x32_bf16 v[4:7], v[166:169], v[206:209], v[4:7]
	v_mfma_f32_16x16x32_bf16 v[0:3], v[174:177], v[206:209], v[0:3]
	v_mfma_f32_16x16x32_bf16 v[28:31], v[170:173], v[186:189], v[28:31]
	v_mfma_f32_16x16x32_bf16 v[24:27], v[178:181], v[186:189], v[24:27]
	v_mfma_f32_16x16x32_bf16 v[20:23], v[170:173], v[194:197], v[20:23]
	v_mfma_f32_16x16x32_bf16 v[16:19], v[178:181], v[194:197], v[16:19]
	v_mfma_f32_16x16x32_bf16 v[12:15], v[170:173], v[202:205], v[12:15]
	v_mfma_f32_16x16x32_bf16 v[8:11], v[178:181], v[202:205], v[8:11]
	v_mfma_f32_16x16x32_bf16 v[4:7], v[170:173], v[210:213], v[4:7]
	s_barrier
	v_mfma_f32_16x16x32_bf16 v[0:3], v[178:181], v[210:213], v[0:3]
	s_setprio 0
	s_add_i32 s56, 0, 0x18000
	s_add_i32 s57, 0, 0x1c000
	v_add_u32_e32 v162, s56, v228
	v_add_u32_e32 v178, s57, v228
	ds_read_b128 v[128:131], v162
	ds_read_b128 v[132:135], v162 offset:1024
	ds_read_b128 v[158:161], v162 offset:2048
	ds_read_b128 v[162:165], v162 offset:3072
	ds_read_b128 v[166:169], v178
	ds_read_b128 v[170:173], v178 offset:1024
	ds_read_b128 v[174:177], v178 offset:2048
	ds_read_b128 v[178:181], v178 offset:3072
	s_add_u32 s52, s80, 0x80000
	s_addc_u32 s53, s81, 0
	s_mov_b32 m0, s33
	v_lshl_add_u64 v[234:235], s[52:53], 0, v[136:137]
	ds_read_b128 v[182:185], v232 offset:32768
	ds_read_b128 v[186:189], v232 offset:33792
	ds_read_b128 v[190:193], v232 offset:34816
	ds_read_b128 v[194:197], v232 offset:35840
	ds_read_b128 v[198:201], v232 offset:36864
	ds_read_b128 v[202:205], v232 offset:37888
	ds_read_b128 v[206:209], v232 offset:38912
	ds_read_b128 v[210:213], v232 offset:39936
	global_load_lds_dwordx4 v[234:235], off
	v_lshl_add_u64 v[234:235], s[52:53], 0, v[140:141]
	s_mov_b32 m0, s38
	s_nop 0
	global_load_lds_dwordx4 v[234:235], off
	s_waitcnt vmcnt(8)
	s_waitcnt lgkmcnt(0)
	s_barrier
	s_setprio 1
	s_waitcnt lgkmcnt(0)
	v_mfma_f32_16x16x32_bf16 v[124:127], v[128:131], v[182:185], v[124:127]
	v_mfma_f32_16x16x32_bf16 v[120:123], v[158:161], v[182:185], v[120:123]
	v_mfma_f32_16x16x32_bf16 v[116:119], v[128:131], v[190:193], v[116:119]
	v_mfma_f32_16x16x32_bf16 v[112:115], v[158:161], v[190:193], v[112:115]
	v_mfma_f32_16x16x32_bf16 v[108:111], v[128:131], v[198:201], v[108:111]
	v_mfma_f32_16x16x32_bf16 v[104:107], v[158:161], v[198:201], v[104:107]
	v_mfma_f32_16x16x32_bf16 v[100:103], v[128:131], v[206:209], v[100:103]
	v_mfma_f32_16x16x32_bf16 v[96:99], v[158:161], v[206:209], v[96:99]
	v_mfma_f32_16x16x32_bf16 v[124:127], v[132:135], v[186:189], v[124:127]
	v_mfma_f32_16x16x32_bf16 v[120:123], v[162:165], v[186:189], v[120:123]
	v_mfma_f32_16x16x32_bf16 v[116:119], v[132:135], v[194:197], v[116:119]
	v_mfma_f32_16x16x32_bf16 v[112:115], v[162:165], v[194:197], v[112:115]
	v_mfma_f32_16x16x32_bf16 v[108:111], v[132:135], v[202:205], v[108:111]
	v_mfma_f32_16x16x32_bf16 v[104:107], v[162:165], v[202:205], v[104:107]
	v_mfma_f32_16x16x32_bf16 v[100:103], v[132:135], v[210:213], v[100:103]
	v_mfma_f32_16x16x32_bf16 v[96:99], v[162:165], v[210:213], v[96:99]
	s_setprio 0
	s_setprio 1
	v_mfma_f32_16x16x32_bf16 v[60:63], v[166:169], v[182:185], v[60:63]
	v_mfma_f32_16x16x32_bf16 v[56:59], v[174:177], v[182:185], v[56:59]
	v_mfma_f32_16x16x32_bf16 v[52:55], v[166:169], v[190:193], v[52:55]
	v_mfma_f32_16x16x32_bf16 v[48:51], v[174:177], v[190:193], v[48:51]
	v_mfma_f32_16x16x32_bf16 v[44:47], v[166:169], v[198:201], v[44:47]
	v_mfma_f32_16x16x32_bf16 v[40:43], v[174:177], v[198:201], v[40:43]
	v_mfma_f32_16x16x32_bf16 v[36:39], v[166:169], v[206:209], v[36:39]
	v_mfma_f32_16x16x32_bf16 v[32:35], v[174:177], v[206:209], v[32:35]
	v_mfma_f32_16x16x32_bf16 v[60:63], v[170:173], v[186:189], v[60:63]
	v_mfma_f32_16x16x32_bf16 v[56:59], v[178:181], v[186:189], v[56:59]
	v_mfma_f32_16x16x32_bf16 v[52:55], v[170:173], v[194:197], v[52:55]
	v_mfma_f32_16x16x32_bf16 v[48:51], v[178:181], v[194:197], v[48:51]
	v_mfma_f32_16x16x32_bf16 v[44:47], v[170:173], v[202:205], v[44:47]
	v_mfma_f32_16x16x32_bf16 v[40:43], v[178:181], v[202:205], v[40:43]
	v_mfma_f32_16x16x32_bf16 v[36:39], v[170:173], v[210:213], v[36:39]
	s_barrier
; #define PG8_STAGE(bufoff, gbase, voff) do { _Pragma("unroll") for (int _i = 0; _i < 2; ++_i) \
;         __builtin_amdgcn_global_load_lds((const unsigned*)((const char*)(gbase) + (voff)[_i]), (PG8_LAS unsigned*)(lds + (bufoff) + ldsw + _i * 8192), 16, 0, 0); } while (0)
; #define PG8_LDA(dst, b, h) do { _Pragma("unroll") for (int m = 0; m < 4; ++m) _Pragma("unroll") for (int k = 0; k < 2; ++k) dst[m][k] = *(const PG8_LAS bf16x8*)(lds + PG8_SA(b, h) + aoff + m * 2048 + k * 1024); } while (0)
; #define PG8_MMA(ai, bj, At, Bt) do { __builtin_amdgcn_s_setprio(1); _Pragma("unroll") for (int m = 0; m < 4; ++m) _Pragma("unroll") for (int n = 0; n < 2; ++n) _Pragma("unroll") for (int k = 0; k < 2; ++k) \
;         acc[ai][bj][m][n] = __builtin_amdgcn_mfma_f32_16x16x32_bf16(Bt[n][k], At[m][k], acc[ai][bj][m][n], 0, 0, 0); __builtin_amdgcn_s_setprio(0); } while (0)
; #define PG8_WAIT_V(n) asm volatile("s_waitcnt vmcnt(" #n ")" ::: "memory")
; #define PG8_WAIT_L(n) asm volatile("s_waitcnt lgkmcnt(" #n ")" ::: "memory")
; #define PG8_BAR __builtin_amdgcn_s_barrier()
; #define PG8_SCHED __builtin_amdgcn_sched_barrier(0)
; template <class Epi, class Sched, bool ALIGN_EPI = false, bool SP2 = false>
; __device__ __forceinline__ void gemm_phase(PG8_LAS unsigned char* lds, const Gemm g, const Sched& S, const Epi& E) {
;     ...
;             PG8_LDA(At, 1, 1); PG8_STAGE(PG8_SB(1, 0), b3, voffB); PG8_STAGE(PG8_SB(1, 1), b3 + hstep, voffB); PG8_STAGE(PG8_SA(1, 0), a3, voffA);
;             PG8_WAIT_V(8); PG8_WAIT_L(0); PG8_BAR; PG8_MMA(1, 0, At, B0); PG8_MMA(1, 1, At, B1); PG8_BAR; PG8_SCHED;
	v_mfma_f32_16x16x32_bf16 v[32:35], v[178:181], v[210:213], v[32:35]
	s_setprio 0
	s_add_i32 s52, s56, s3
	v_lshl_add_u64 v[214:215], v[214:215], 0, s[14:15]
	s_mov_b32 m0, s52
	ds_read_b128 v[182:185], v232 offset:49152
	ds_read_b128 v[186:189], v232 offset:50176
	ds_read_b128 v[190:193], v232 offset:51200
	ds_read_b128 v[194:197], v232 offset:52224
	ds_read_b128 v[198:201], v232 offset:53248
	ds_read_b128 v[202:205], v232 offset:54272
	ds_read_b128 v[206:209], v232 offset:55296
	ds_read_b128 v[210:213], v232 offset:56320
	global_load_lds_dwordx4 v[214:215], off
	s_add_i32 m0, s52, 0x2000
	s_add_u32 s52, s78, 0x80080
	v_lshl_add_u64 v[214:215], v[216:217], 0, s[14:15]
	s_addc_u32 s53, s79, 0
	s_add_i32 s56, s57, s3
	global_load_lds_dwordx4 v[214:215], off
	v_lshl_add_u64 v[214:215], s[52:53], 0, v[138:139]
	s_mov_b32 m0, s56
	s_nop 0
	global_load_lds_dwordx4 v[214:215], off
	v_lshl_add_u64 v[214:215], s[52:53], 0, v[142:143]
	s_add_i32 m0, s56, 0x2000
	s_nop 0
	global_load_lds_dwordx4 v[214:215], off
	v_lshl_add_u64 v[214:215], v[218:219], 0, s[14:15]
	s_mov_b32 m0, s88
	s_nop 0
	global_load_lds_dwordx4 v[214:215], off
	v_lshl_add_u64 v[214:215], v[220:221], 0, s[14:15]
	s_mov_b32 m0, s89
	s_nop 0
	global_load_lds_dwordx4 v[214:215], off
	s_waitcnt vmcnt(8)
	s_waitcnt lgkmcnt(0)
	s_barrier
	s_setprio 1
	s_waitcnt lgkmcnt(0)
	v_mfma_f32_16x16x32_bf16 v[92:95], v[128:131], v[182:185], v[92:95]
	v_mfma_f32_16x16x32_bf16 v[88:91], v[158:161], v[182:185], v[88:91]
	v_mfma_f32_16x16x32_bf16 v[84:87], v[128:131], v[190:193], v[84:87]
	v_mfma_f32_16x16x32_bf16 v[80:83], v[158:161], v[190:193], v[80:83]
	v_mfma_f32_16x16x32_bf16 v[76:79], v[128:131], v[198:201], v[76:79]
	v_mfma_f32_16x16x32_bf16 v[72:75], v[158:161], v[198:201], v[72:75]
	v_mfma_f32_16x16x32_bf16 v[68:71], v[128:131], v[206:209], v[68:71]
	v_mfma_f32_16x16x32_bf16 v[64:67], v[158:161], v[206:209], v[64:67]
	v_mfma_f32_16x16x32_bf16 v[92:95], v[132:135], v[186:189], v[92:95]
	v_mfma_f32_16x16x32_bf16 v[88:91], v[162:165], v[186:189], v[88:91]
	v_mfma_f32_16x16x32_bf16 v[84:87], v[132:135], v[194:197], v[84:87]
	v_mfma_f32_16x16x32_bf16 v[80:83], v[162:165], v[194:197], v[80:83]
	v_mfma_f32_16x16x32_bf16 v[76:79], v[132:135], v[202:205], v[76:79]
	v_mfma_f32_16x16x32_bf16 v[72:75], v[162:165], v[202:205], v[72:75]
	v_mfma_f32_16x16x32_bf16 v[68:71], v[132:135], v[210:213], v[68:71]
	v_mfma_f32_16x16x32_bf16 v[64:67], v[162:165], v[210:213], v[64:67]
	s_setprio 0
	s_setprio 1
	v_mfma_f32_16x16x32_bf16 v[28:31], v[166:169], v[182:185], v[28:31]
	v_mfma_f32_16x16x32_bf16 v[24:27], v[174:177], v[182:185], v[24:27]
	v_mfma_f32_16x16x32_bf16 v[20:23], v[166:169], v[190:193], v[20:23]
	v_mfma_f32_16x16x32_bf16 v[16:19], v[174:177], v[190:193], v[16:19]
	v_mfma_f32_16x16x32_bf16 v[12:15], v[166:169], v[198:201], v[12:15]
	v_mfma_f32_16x16x32_bf16 v[8:11], v[174:177], v[198:201], v[8:11]
	v_mfma_f32_16x16x32_bf16 v[4:7], v[166:169], v[206:209], v[4:7]
	v_mfma_f32_16x16x32_bf16 v[0:3], v[174:177], v[206:209], v[0:3]
	v_mfma_f32_16x16x32_bf16 v[28:31], v[170:173], v[186:189], v[28:31]
	v_mfma_f32_16x16x32_bf16 v[24:27], v[178:181], v[186:189], v[24:27]
	v_mfma_f32_16x16x32_bf16 v[20:23], v[170:173], v[194:197], v[20:23]
	v_mfma_f32_16x16x32_bf16 v[16:19], v[178:181], v[194:197], v[16:19]
	v_mfma_f32_16x16x32_bf16 v[12:15], v[170:173], v[202:205], v[12:15]
	v_mfma_f32_16x16x32_bf16 v[8:11], v[178:181], v[202:205], v[8:11]
	v_mfma_f32_16x16x32_bf16 v[4:7], v[170:173], v[210:213], v[4:7]
	s_barrier
	v_mfma_f32_16x16x32_bf16 v[0:3], v[178:181], v[210:213], v[0:3]
	s_setprio 0
	s_add_i32 vcc_hi, vcc_hi, 2
	s_add_u32 s76, s76, 0x100
	s_addc_u32 s77, s77, 0
	s_add_u32 s75, s75, 0x100
	s_addc_u32 vcc_lo, vcc_lo, 0
	s_cmp_gt_u32 vcc_hi, 29
	s_cbranch_scc0 .LBB0_374
	s_and_b64 vcc, exec, s[48:49]
	s_cbranch_vccz .LBB0_377
	s_barrier

; #define PG8_STAGE(bufoff, gbase, voff) do { _Pragma("unroll") for (int _i = 0; _i < 2; ++_i) \
;         __builtin_amdgcn_global_load_lds((const unsigned*)((const char*)(gbase) + (voff)[_i]), (PG8_LAS unsigned*)(lds + (bufoff) + ldsw + _i * 8192), 16, 0, 0); } while (0)
; #define PG8_LDA(dst, b, h) do { _Pragma("unroll") for (int m = 0; m < 4; ++m) _Pragma("unroll") for (int k = 0; k < 2; ++k) dst[m][k] = *(const PG8_LAS bf16x8*)(lds + PG8_SA(b, h) + aoff + m * 2048 + k * 1024); } while (0)
; #define PG8_LDB(dst, b, h) do { _Pragma("unroll") for (int n = 0; n < 2; ++n) _Pragma("unroll") for (int k = 0; k < 2; ++k) dst[n][k] = *(const PG8_LAS bf16x8*)(lds + PG8_SB(b, h) + boff + n * 2048 + k * 1024); } while (0)
; #define PG8_MMA(ai, bj, At, Bt) do { __builtin_amdgcn_s_setprio(1); _Pragma("unroll") for (int m = 0; m < 4; ++m) _Pragma("unroll") for (int n = 0; n < 2; ++n) _Pragma("unroll") for (int k = 0; k < 2; ++k) \
;         acc[ai][bj][m][n] = __builtin_amdgcn_mfma_f32_16x16x32_bf16(Bt[n][k], At[m][k], acc[ai][bj][m][n], 0, 0, 0); __builtin_amdgcn_s_setprio(0); } while (0)
; #define PG8_WAIT_V(n) asm volatile("s_waitcnt vmcnt(" #n ")" ::: "memory")
; #define PG8_WAIT_L(n) asm volatile("s_waitcnt lgkmcnt(" #n ")" ::: "memory")
; #define PG8_BAR __builtin_amdgcn_s_barrier()
; #define PG8_SCHED __builtin_amdgcn_sched_barrier(0)
; template <class Epi, class Sched, bool ALIGN_EPI = false, bool SP2 = false>
; __device__ __forceinline__ void gemm_phase(PG8_LAS unsigned char* lds, const Gemm g, const Sched& S, const Epi& E) {
;     ...
;             PG8_LDB(B0, 0, 0); PG8_LDB(B1, 0, 1); PG8_SCHED; PG8_LDA(At, 0, 0); PG8_STAGE(PG8_SA(1, 1), a1 + hstep, voffA);
;             PG8_WAIT_V(8); PG8_WAIT_L(0); PG8_BAR; PG8_MMA(0, 0, At, B0); PG8_MMA(0, 1, At, B1); PG8_BAR; PG8_SCHED;
;             PG8_LDA(At, 0, 1); PG8_STAGE(PG8_SB(0, 0), b2, voffB); PG8_STAGE(PG8_SB(0, 1), b2 + hstep, voffB); PG8_STAGE(PG8_SA(0, 0), a2, voffA);
;             PG8_WAIT_V(8); PG8_WAIT_L(0); PG8_BAR; PG8_MMA(1, 0, At, B0); PG8_MMA(1, 1, At, B1); PG8_BAR; PG8_SCHED;
.LBB0_410:
	ds_read_b128 v[166:169], v145
	ds_read_b128 v[170:173], v145 offset:1024
	ds_read_b128 v[174:177], v145 offset:2048
	ds_read_b128 v[178:181], v145 offset:3072
	ds_read_b128 v[182:185], v149
	ds_read_b128 v[186:189], v149 offset:1024
	ds_read_b128 v[190:193], v149 offset:2048
	ds_read_b128 v[194:197], v149 offset:3072
	s_add_u32 s52, s74, 0xfff80080
	s_addc_u32 s53, s75, -1
	s_cmp_eq_u32 s51, 4
	s_cselect_b32 s79, s55, s53
	s_cselect_b32 s78, s54, s52
	s_cselect_b32 s77, s69, s49
	s_cselect_b32 s76, s68, s37
	s_mov_b32 m0, s80
	v_lshl_add_u64 v[230:231], s[74:75], 0, v[160:161]
	ds_read_b128 v[198:201], v164
	ds_read_b128 v[202:205], v164 offset:1024
	ds_read_b128 v[206:209], v164 offset:2048
	ds_read_b128 v[210:213], v164 offset:3072
	ds_read_b128 v[214:217], v164 offset:4096
	ds_read_b128 v[218:221], v164 offset:5120
	ds_read_b128 v[222:225], v164 offset:6144
	ds_read_b128 v[226:229], v164 offset:7168
	global_load_lds_dwordx4 v[230:231], off
	v_lshl_add_u64 v[230:231], s[74:75], 0, v[162:163]
	s_mov_b32 m0, s81
	s_nop 0
	global_load_lds_dwordx4 v[230:231], off
	s_waitcnt vmcnt(8)
	s_waitcnt lgkmcnt(0)
	s_barrier
	s_setprio 1
	s_waitcnt lgkmcnt(0)
	v_mfma_f32_16x16x32_bf16 v[124:127], v[166:169], v[198:201], v[124:127]
	v_mfma_f32_16x16x32_bf16 v[120:123], v[174:177], v[198:201], v[120:123]
	v_mfma_f32_16x16x32_bf16 v[116:119], v[166:169], v[206:209], v[116:119]
	v_mfma_f32_16x16x32_bf16 v[108:111], v[174:177], v[206:209], v[108:111]
	v_mfma_f32_16x16x32_bf16 v[100:103], v[166:169], v[214:217], v[100:103]
	v_mfma_f32_16x16x32_bf16 v[92:95], v[174:177], v[214:217], v[92:95]
	v_mfma_f32_16x16x32_bf16 v[84:87], v[166:169], v[222:225], v[84:87]
	v_mfma_f32_16x16x32_bf16 v[76:79], v[174:177], v[222:225], v[76:79]
	v_mfma_f32_16x16x32_bf16 v[124:127], v[170:173], v[202:205], v[124:127]
	v_mfma_f32_16x16x32_bf16 v[120:123], v[178:181], v[202:205], v[120:123]
	v_mfma_f32_16x16x32_bf16 v[116:119], v[170:173], v[210:213], v[116:119]
	v_mfma_f32_16x16x32_bf16 v[108:111], v[178:181], v[210:213], v[108:111]
	v_mfma_f32_16x16x32_bf16 v[100:103], v[170:173], v[218:221], v[100:103]
	v_mfma_f32_16x16x32_bf16 v[92:95], v[178:181], v[218:221], v[92:95]
	v_mfma_f32_16x16x32_bf16 v[84:87], v[170:173], v[226:229], v[84:87]
	v_mfma_f32_16x16x32_bf16 v[76:79], v[178:181], v[226:229], v[76:79]
	s_setprio 0
	s_setprio 1
	v_mfma_f32_16x16x32_bf16 v[112:115], v[182:185], v[198:201], v[112:115]
	v_mfma_f32_16x16x32_bf16 v[104:107], v[190:193], v[198:201], v[104:107]
	v_mfma_f32_16x16x32_bf16 v[96:99], v[182:185], v[206:209], v[96:99]
	v_mfma_f32_16x16x32_bf16 v[88:91], v[190:193], v[206:209], v[88:91]
	v_mfma_f32_16x16x32_bf16 v[80:83], v[182:185], v[214:217], v[80:83]
	v_mfma_f32_16x16x32_bf16 v[72:75], v[190:193], v[214:217], v[72:75]
	v_mfma_f32_16x16x32_bf16 v[68:71], v[182:185], v[222:225], v[68:71]
	v_mfma_f32_16x16x32_bf16 v[64:67], v[190:193], v[222:225], v[64:67]
	v_mfma_f32_16x16x32_bf16 v[112:115], v[186:189], v[202:205], v[112:115]
	v_mfma_f32_16x16x32_bf16 v[104:107], v[194:197], v[202:205], v[104:107]
	v_mfma_f32_16x16x32_bf16 v[96:99], v[186:189], v[210:213], v[96:99]
	v_mfma_f32_16x16x32_bf16 v[88:91], v[194:197], v[210:213], v[88:91]
	v_mfma_f32_16x16x32_bf16 v[80:83], v[186:189], v[218:221], v[80:83]
	v_mfma_f32_16x16x32_bf16 v[72:75], v[194:197], v[218:221], v[72:75]
	v_mfma_f32_16x16x32_bf16 v[68:71], v[186:189], v[226:229], v[68:71]
	s_barrier
	v_mfma_f32_16x16x32_bf16 v[64:67], v[194:197], v[226:229], v[64:67]
	s_setprio 0
	s_mov_b32 m0, s84
	v_lshl_add_u64 v[230:231], s[76:77], 0, v[138:139]
	s_add_u32 s52, s76, 0x80000
	ds_read_b128 v[198:201], v164 offset:16384
	ds_read_b128 v[202:205], v164 offset:17408
	ds_read_b128 v[206:209], v164 offset:18432
	ds_read_b128 v[210:213], v164 offset:19456
	ds_read_b128 v[214:217], v164 offset:20480
	ds_read_b128 v[218:221], v164 offset:21504
	ds_read_b128 v[222:225], v164 offset:22528
	ds_read_b128 v[226:229], v164 offset:23552
	global_load_lds_dwordx4 v[230:231], off
	v_lshl_add_u64 v[232:233], s[76:77], 0, v[142:143]
	s_mov_b32 m0, s85
	s_addc_u32 s53, s77, 0
	global_load_lds_dwordx4 v[232:233], off
	v_lshl_add_u64 v[234:235], s[52:53], 0, v[138:139]
	s_mov_b32 m0, s86
	v_lshl_add_u64 v[236:237], s[78:79], 0, v[140:141]
	global_load_lds_dwordx4 v[234:235], off
	v_lshl_add_u64 v[234:235], s[52:53], 0, v[142:143]
	s_mov_b32 m0, s87
	s_nop 0
	global_load_lds_dwordx4 v[234:235], off
	v_lshl_add_u64 v[234:235], s[78:79], 0, v[136:137]
	s_mov_b32 m0, s10
	s_nop 0
	global_load_lds_dwordx4 v[234:235], off
	s_mov_b32 m0, s11
	s_nop 0
	global_load_lds_dwordx4 v[236:237], off
	s_waitcnt vmcnt(8)
	s_waitcnt lgkmcnt(0)
	s_barrier
; #define PG8_STAGE(bufoff, gbase, voff) do { _Pragma("unroll") for (int _i = 0; _i < 2; ++_i) \
;         __builtin_amdgcn_global_load_lds((const unsigned*)((const char*)(gbase) + (voff)[_i]), (PG8_LAS unsigned*)(lds + (bufoff) + ldsw + _i * 8192), 16, 0, 0); } while (0)
; #define PG8_LDA(dst, b, h) do { _Pragma("unroll") for (int m = 0; m < 4; ++m) _Pragma("unroll") for (int k = 0; k < 2; ++k) dst[m][k] = *(const PG8_LAS bf16x8*)(lds + PG8_SA(b, h) + aoff + m * 2048 + k * 1024); } while (0)
; #define PG8_LDB(dst, b, h) do { _Pragma("unroll") for (int n = 0; n < 2; ++n) _Pragma("unroll") for (int k = 0; k < 2; ++k) dst[n][k] = *(const PG8_LAS bf16x8*)(lds + PG8_SB(b, h) + boff + n * 2048 + k * 1024); } while (0)
; #define PG8_MMA(ai, bj, At, Bt) do { __builtin_amdgcn_s_setprio(1); _Pragma("unroll") for (int m = 0; m < 4; ++m) _Pragma("unroll") for (int n = 0; n < 2; ++n) _Pragma("unroll") for (int k = 0; k < 2; ++k) \
;         acc[ai][bj][m][n] = __builtin_amdgcn_mfma_f32_16x16x32_bf16(Bt[n][k], At[m][k], acc[ai][bj][m][n], 0, 0, 0); __builtin_amdgcn_s_setprio(0); } while (0)
; #define PG8_WAIT_V(n) asm volatile("s_waitcnt vmcnt(" #n ")" ::: "memory")
; #define PG8_WAIT_L(n) asm volatile("s_waitcnt lgkmcnt(" #n ")" ::: "memory")
; #define PG8_BAR __builtin_amdgcn_s_barrier()
; #define PG8_SCHED __builtin_amdgcn_sched_barrier(0)
; template <class Epi, class Sched, bool ALIGN_EPI = false, bool SP2 = false>
; __device__ __forceinline__ void gemm_phase(PG8_LAS unsigned char* lds, const Gemm g, const Sched& S, const Epi& E) {
;     ...
;             PG8_WAIT_V(8); PG8_WAIT_L(0); PG8_BAR; PG8_MMA(1, 0, At, B0); PG8_MMA(1, 1, At, B1); PG8_BAR; PG8_SCHED;
;             PG8_LDB(B0, 1, 0); PG8_LDB(B1, 1, 1); PG8_SCHED; PG8_LDA(At, 1, 0); PG8_STAGE(PG8_SA(0, 1), a2 + hstep, voffA);
;             PG8_WAIT_V(8); PG8_WAIT_L(0); PG8_BAR; PG8_MMA(0, 0, At, B0); PG8_MMA(0, 1, At, B1); PG8_BAR; PG8_SCHED;
;             PG8_LDA(At, 1, 1); PG8_STAGE(PG8_SB(1, 0), b3, voffB); PG8_STAGE(PG8_SB(1, 1), b3 + hstep, voffB); PG8_STAGE(PG8_SA(1, 0), a3, voffA);
	s_setprio 1
	s_waitcnt lgkmcnt(0)
	v_mfma_f32_16x16x32_bf16 v[60:63], v[166:169], v[198:201], v[60:63]
	v_mfma_f32_16x16x32_bf16 v[56:59], v[174:177], v[198:201], v[56:59]
	v_mfma_f32_16x16x32_bf16 v[52:55], v[166:169], v[206:209], v[52:55]
	v_mfma_f32_16x16x32_bf16 v[44:47], v[174:177], v[206:209], v[44:47]
	v_mfma_f32_16x16x32_bf16 v[36:39], v[166:169], v[214:217], v[36:39]
	v_mfma_f32_16x16x32_bf16 v[28:31], v[174:177], v[214:217], v[28:31]
	v_mfma_f32_16x16x32_bf16 v[20:23], v[166:169], v[222:225], v[20:23]
	v_mfma_f32_16x16x32_bf16 v[12:15], v[174:177], v[222:225], v[12:15]
	v_mfma_f32_16x16x32_bf16 v[60:63], v[170:173], v[202:205], v[60:63]
	v_mfma_f32_16x16x32_bf16 v[56:59], v[178:181], v[202:205], v[56:59]
	v_mfma_f32_16x16x32_bf16 v[52:55], v[170:173], v[210:213], v[52:55]
	v_mfma_f32_16x16x32_bf16 v[44:47], v[178:181], v[210:213], v[44:47]
	v_mfma_f32_16x16x32_bf16 v[36:39], v[170:173], v[218:221], v[36:39]
	v_mfma_f32_16x16x32_bf16 v[28:31], v[178:181], v[218:221], v[28:31]
	v_mfma_f32_16x16x32_bf16 v[20:23], v[170:173], v[226:229], v[20:23]
	v_mfma_f32_16x16x32_bf16 v[12:15], v[178:181], v[226:229], v[12:15]
	s_setprio 0
	s_setprio 1
	v_mfma_f32_16x16x32_bf16 v[48:51], v[182:185], v[198:201], v[48:51]
	v_mfma_f32_16x16x32_bf16 v[40:43], v[190:193], v[198:201], v[40:43]
	v_mfma_f32_16x16x32_bf16 v[32:35], v[182:185], v[206:209], v[32:35]
	v_mfma_f32_16x16x32_bf16 v[24:27], v[190:193], v[206:209], v[24:27]
	v_mfma_f32_16x16x32_bf16 v[16:19], v[182:185], v[214:217], v[16:19]
	v_mfma_f32_16x16x32_bf16 v[8:11], v[190:193], v[214:217], v[8:11]
	v_mfma_f32_16x16x32_bf16 v[4:7], v[182:185], v[222:225], v[4:7]
	v_mfma_f32_16x16x32_bf16 v[0:3], v[190:193], v[222:225], v[0:3]
	v_mfma_f32_16x16x32_bf16 v[48:51], v[186:189], v[202:205], v[48:51]
	v_mfma_f32_16x16x32_bf16 v[40:43], v[194:197], v[202:205], v[40:43]
	v_mfma_f32_16x16x32_bf16 v[32:35], v[186:189], v[210:213], v[32:35]
	v_mfma_f32_16x16x32_bf16 v[24:27], v[194:197], v[210:213], v[24:27]
	v_mfma_f32_16x16x32_bf16 v[16:19], v[186:189], v[218:221], v[16:19]
	v_mfma_f32_16x16x32_bf16 v[8:11], v[194:197], v[218:221], v[8:11]
	v_mfma_f32_16x16x32_bf16 v[4:7], v[186:189], v[226:229], v[4:7]
	s_barrier
	v_mfma_f32_16x16x32_bf16 v[0:3], v[194:197], v[226:229], v[0:3]
	s_setprio 0
	ds_read_b128 v[166:169], v148
	ds_read_b128 v[170:173], v148 offset:1024
	ds_read_b128 v[174:177], v148 offset:2048
	ds_read_b128 v[178:181], v148 offset:3072
	ds_read_b128 v[182:185], v165
	ds_read_b128 v[186:189], v165 offset:1024
	ds_read_b128 v[190:193], v165 offset:2048
	ds_read_b128 v[194:197], v165 offset:3072
	s_add_u32 s52, s78, 0x80000
	s_addc_u32 s53, s79, 0
	s_mov_b32 m0, s28
	v_lshl_add_u64 v[238:239], s[52:53], 0, v[136:137]
	ds_read_b128 v[198:201], v164 offset:32768
	ds_read_b128 v[202:205], v164 offset:33792
	ds_read_b128 v[206:209], v164 offset:34816
	ds_read_b128 v[210:213], v164 offset:35840
	ds_read_b128 v[214:217], v164 offset:36864
	ds_read_b128 v[218:221], v164 offset:37888
	ds_read_b128 v[222:225], v164 offset:38912
	ds_read_b128 v[226:229], v164 offset:39936
	global_load_lds_dwordx4 v[238:239], off
	v_lshl_add_u64 v[238:239], s[52:53], 0, v[140:141]
	s_mov_b32 m0, s29
	s_nop 0
	global_load_lds_dwordx4 v[238:239], off
	s_waitcnt vmcnt(8)
	s_waitcnt lgkmcnt(0)
	s_barrier
	s_setprio 1
	s_waitcnt lgkmcnt(0)
	v_mfma_f32_16x16x32_bf16 v[124:127], v[166:169], v[198:201], v[124:127]
	v_mfma_f32_16x16x32_bf16 v[120:123], v[174:177], v[198:201], v[120:123]
	v_mfma_f32_16x16x32_bf16 v[116:119], v[166:169], v[206:209], v[116:119]
	v_mfma_f32_16x16x32_bf16 v[108:111], v[174:177], v[206:209], v[108:111]
	v_mfma_f32_16x16x32_bf16 v[100:103], v[166:169], v[214:217], v[100:103]
	v_mfma_f32_16x16x32_bf16 v[92:95], v[174:177], v[214:217], v[92:95]
	v_mfma_f32_16x16x32_bf16 v[84:87], v[166:169], v[222:225], v[84:87]
	v_mfma_f32_16x16x32_bf16 v[76:79], v[174:177], v[222:225], v[76:79]
	v_mfma_f32_16x16x32_bf16 v[124:127], v[170:173], v[202:205], v[124:127]
	v_mfma_f32_16x16x32_bf16 v[120:123], v[178:181], v[202:205], v[120:123]
	v_mfma_f32_16x16x32_bf16 v[116:119], v[170:173], v[210:213], v[116:119]
	v_mfma_f32_16x16x32_bf16 v[108:111], v[178:181], v[210:213], v[108:111]
	v_mfma_f32_16x16x32_bf16 v[100:103], v[170:173], v[218:221], v[100:103]
	v_mfma_f32_16x16x32_bf16 v[92:95], v[178:181], v[218:221], v[92:95]
	v_mfma_f32_16x16x32_bf16 v[84:87], v[170:173], v[226:229], v[84:87]
	v_mfma_f32_16x16x32_bf16 v[76:79], v[178:181], v[226:229], v[76:79]
	s_setprio 0
	s_setprio 1
	v_mfma_f32_16x16x32_bf16 v[112:115], v[182:185], v[198:201], v[112:115]
	v_mfma_f32_16x16x32_bf16 v[104:107], v[190:193], v[198:201], v[104:107]
	v_mfma_f32_16x16x32_bf16 v[96:99], v[182:185], v[206:209], v[96:99]
	v_mfma_f32_16x16x32_bf16 v[88:91], v[190:193], v[206:209], v[88:91]
	v_mfma_f32_16x16x32_bf16 v[80:83], v[182:185], v[214:217], v[80:83]
	v_mfma_f32_16x16x32_bf16 v[72:75], v[190:193], v[214:217], v[72:75]
	v_mfma_f32_16x16x32_bf16 v[68:71], v[182:185], v[222:225], v[68:71]
	v_mfma_f32_16x16x32_bf16 v[64:67], v[190:193], v[222:225], v[64:67]
	v_mfma_f32_16x16x32_bf16 v[112:115], v[186:189], v[202:205], v[112:115]
	v_mfma_f32_16x16x32_bf16 v[104:107], v[194:197], v[202:205], v[104:107]
	v_mfma_f32_16x16x32_bf16 v[96:99], v[186:189], v[210:213], v[96:99]
	v_mfma_f32_16x16x32_bf16 v[88:91], v[194:197], v[210:213], v[88:91]
	v_mfma_f32_16x16x32_bf16 v[80:83], v[186:189], v[218:221], v[80:83]
	v_mfma_f32_16x16x32_bf16 v[72:75], v[194:197], v[218:221], v[72:75]
	v_mfma_f32_16x16x32_bf16 v[68:71], v[186:189], v[226:229], v[68:71]
	s_barrier
; #define PG8_STAGE(bufoff, gbase, voff) do { _Pragma("unroll") for (int _i = 0; _i < 2; ++_i) \
;         __builtin_amdgcn_global_load_lds((const unsigned*)((const char*)(gbase) + (voff)[_i]), (PG8_LAS unsigned*)(lds + (bufoff) + ldsw + _i * 8192), 16, 0, 0); } while (0)
; #define PG8_LDA(dst, b, h) do { _Pragma("unroll") for (int m = 0; m < 4; ++m) _Pragma("unroll") for (int k = 0; k < 2; ++k) dst[m][k] = *(const PG8_LAS bf16x8*)(lds + PG8_SA(b, h) + aoff + m * 2048 + k * 1024); } while (0)
; #define PG8_MMA(ai, bj, At, Bt) do { __builtin_amdgcn_s_setprio(1); _Pragma("unroll") for (int m = 0; m < 4; ++m) _Pragma("unroll") for (int n = 0; n < 2; ++n) _Pragma("unroll") for (int k = 0; k < 2; ++k) \
;         acc[ai][bj][m][n] = __builtin_amdgcn_mfma_f32_16x16x32_bf16(Bt[n][k], At[m][k], acc[ai][bj][m][n], 0, 0, 0); __builtin_amdgcn_s_setprio(0); } while (0)
; #define PG8_WAIT_V(n) asm volatile("s_waitcnt vmcnt(" #n ")" ::: "memory")
; #define PG8_WAIT_L(n) asm volatile("s_waitcnt lgkmcnt(" #n ")" ::: "memory")
; #define PG8_BAR __builtin_amdgcn_s_barrier()
; #define PG8_SCHED __builtin_amdgcn_sched_barrier(0)
; template <class Epi, class Sched, bool ALIGN_EPI = false, bool SP2 = false>
; __device__ __forceinline__ void gemm_phase(PG8_LAS unsigned char* lds, const Gemm g, const Sched& S, const Epi& E) {
;     ...
;             PG8_WAIT_V(8); PG8_WAIT_L(0); PG8_BAR; PG8_MMA(0, 0, At, B0); PG8_MMA(0, 1, At, B1); PG8_BAR; PG8_SCHED;
;             PG8_LDA(At, 1, 1); PG8_STAGE(PG8_SB(1, 0), b3, voffB); PG8_STAGE(PG8_SB(1, 1), b3 + hstep, voffB); PG8_STAGE(PG8_SA(1, 0), a3, voffA);
;             PG8_WAIT_V(8); PG8_WAIT_L(0); PG8_BAR; PG8_MMA(1, 0, At, B0); PG8_MMA(1, 1, At, B1); PG8_BAR; PG8_SCHED;
;     ...
;         if constexpr (ALIGN_EPI) { if (wr == 0) PG8_BAR; }
	v_mfma_f32_16x16x32_bf16 v[64:67], v[194:197], v[226:229], v[64:67]
	s_setprio 0
	s_mov_b32 m0, s89
	v_lshl_add_u64 v[230:231], v[230:231], 0, s[12:13]
	ds_read_b128 v[198:201], v164 offset:49152
	ds_read_b128 v[202:205], v164 offset:50176
	ds_read_b128 v[206:209], v164 offset:51200
	ds_read_b128 v[210:213], v164 offset:52224
	ds_read_b128 v[214:217], v164 offset:53248
	ds_read_b128 v[218:221], v164 offset:54272
	ds_read_b128 v[222:225], v164 offset:55296
	ds_read_b128 v[226:229], v164 offset:56320
	global_load_lds_dwordx4 v[230:231], off
	s_add_i32 m0, s89, 0x2000
	s_add_u32 s52, s76, 0x80080
	v_lshl_add_u64 v[230:231], v[232:233], 0, s[12:13]
	s_addc_u32 s53, s77, 0
	s_add_i32 s56, s88, s3
	global_load_lds_dwordx4 v[230:231], off
	v_lshl_add_u64 v[230:231], s[52:53], 0, v[138:139]
	s_mov_b32 m0, s56
	s_nop 0
	global_load_lds_dwordx4 v[230:231], off
	v_lshl_add_u64 v[230:231], s[52:53], 0, v[142:143]
	s_add_i32 m0, s56, 0x2000
	s_nop 0
	global_load_lds_dwordx4 v[230:231], off
	v_lshl_add_u64 v[230:231], v[234:235], 0, s[12:13]
	s_mov_b32 m0, s38
	s_nop 0
	global_load_lds_dwordx4 v[230:231], off
	v_lshl_add_u64 v[230:231], v[236:237], 0, s[12:13]
	s_mov_b32 m0, s39
	s_nop 0
	global_load_lds_dwordx4 v[230:231], off
	s_waitcnt vmcnt(8)
	s_waitcnt lgkmcnt(0)
	s_barrier
	s_setprio 1
	s_waitcnt lgkmcnt(0)
	v_mfma_f32_16x16x32_bf16 v[60:63], v[166:169], v[198:201], v[60:63]
	v_mfma_f32_16x16x32_bf16 v[56:59], v[174:177], v[198:201], v[56:59]
	v_mfma_f32_16x16x32_bf16 v[52:55], v[166:169], v[206:209], v[52:55]
	v_mfma_f32_16x16x32_bf16 v[44:47], v[174:177], v[206:209], v[44:47]
	v_mfma_f32_16x16x32_bf16 v[36:39], v[166:169], v[214:217], v[36:39]
	v_mfma_f32_16x16x32_bf16 v[28:31], v[174:177], v[214:217], v[28:31]
	v_mfma_f32_16x16x32_bf16 v[20:23], v[166:169], v[222:225], v[20:23]
	v_mfma_f32_16x16x32_bf16 v[12:15], v[174:177], v[222:225], v[12:15]
	v_mfma_f32_16x16x32_bf16 v[60:63], v[170:173], v[202:205], v[60:63]
	v_mfma_f32_16x16x32_bf16 v[56:59], v[178:181], v[202:205], v[56:59]
	v_mfma_f32_16x16x32_bf16 v[52:55], v[170:173], v[210:213], v[52:55]
	v_mfma_f32_16x16x32_bf16 v[44:47], v[178:181], v[210:213], v[44:47]
	v_mfma_f32_16x16x32_bf16 v[36:39], v[170:173], v[218:221], v[36:39]
	v_mfma_f32_16x16x32_bf16 v[28:31], v[178:181], v[218:221], v[28:31]
	v_mfma_f32_16x16x32_bf16 v[20:23], v[170:173], v[226:229], v[20:23]
	v_mfma_f32_16x16x32_bf16 v[12:15], v[178:181], v[226:229], v[12:15]
	s_setprio 0
	s_setprio 1
	v_mfma_f32_16x16x32_bf16 v[48:51], v[182:185], v[198:201], v[48:51]
	v_mfma_f32_16x16x32_bf16 v[40:43], v[190:193], v[198:201], v[40:43]
	v_mfma_f32_16x16x32_bf16 v[32:35], v[182:185], v[206:209], v[32:35]
	v_mfma_f32_16x16x32_bf16 v[24:27], v[190:193], v[206:209], v[24:27]
	v_mfma_f32_16x16x32_bf16 v[16:19], v[182:185], v[214:217], v[16:19]
	v_mfma_f32_16x16x32_bf16 v[8:11], v[190:193], v[214:217], v[8:11]
	v_mfma_f32_16x16x32_bf16 v[4:7], v[182:185], v[222:225], v[4:7]
	v_mfma_f32_16x16x32_bf16 v[0:3], v[190:193], v[222:225], v[0:3]
	v_mfma_f32_16x16x32_bf16 v[48:51], v[186:189], v[202:205], v[48:51]
	v_mfma_f32_16x16x32_bf16 v[40:43], v[194:197], v[202:205], v[40:43]
	v_mfma_f32_16x16x32_bf16 v[32:35], v[186:189], v[210:213], v[32:35]
	v_mfma_f32_16x16x32_bf16 v[24:27], v[194:197], v[210:213], v[24:27]
	v_mfma_f32_16x16x32_bf16 v[16:19], v[186:189], v[218:221], v[16:19]
	v_mfma_f32_16x16x32_bf16 v[8:11], v[194:197], v[218:221], v[8:11]
	v_mfma_f32_16x16x32_bf16 v[4:7], v[186:189], v[226:229], v[4:7]
	s_barrier
	v_mfma_f32_16x16x32_bf16 v[0:3], v[194:197], v[226:229], v[0:3]
	s_setprio 0
	s_add_i32 s51, s51, 2
	s_add_u32 s74, s74, 0x100
	s_addc_u32 s75, s75, 0
	s_add_u32 s37, s37, 0x100
	s_addc_u32 s49, s49, 0
	s_cmp_gt_u32 s51, 5
	s_cbranch_scc0 .LBB0_410
	s_and_b64 vcc, exec, s[14:15]
	s_cbranch_vccz .LBB0_413
	s_barrier

; #define PG8_STAGE(bufoff, gbase, voff) do { _Pragma("unroll") for (int _i = 0; _i < 2; ++_i) \
;         __builtin_amdgcn_global_load_lds((const unsigned*)((const char*)(gbase) + (voff)[_i]), (PG8_LAS unsigned*)(lds + (bufoff) + ldsw + _i * 8192), 16, 0, 0); } while (0)
; #define PG8_LDA(dst, b, h) do { _Pragma("unroll") for (int m = 0; m < 4; ++m) _Pragma("unroll") for (int k = 0; k < 2; ++k) dst[m][k] = *(const PG8_LAS bf16x8*)(lds + PG8_SA(b, h) + aoff + m * 2048 + k * 1024); } while (0)
; #define PG8_LDB(dst, b, h) do { _Pragma("unroll") for (int n = 0; n < 2; ++n) _Pragma("unroll") for (int k = 0; k < 2; ++k) dst[n][k] = *(const PG8_LAS bf16x8*)(lds + PG8_SB(b, h) + boff + n * 2048 + k * 1024); } while (0)
; #define PG8_MMA(ai, bj, At, Bt) do { __builtin_amdgcn_s_setprio(1); _Pragma("unroll") for (int m = 0; m < 4; ++m) _Pragma("unroll") for (int n = 0; n < 2; ++n) _Pragma("unroll") for (int k = 0; k < 2; ++k) \
;         acc[ai][bj][m][n] = __builtin_amdgcn_mfma_f32_16x16x32_bf16(Bt[n][k], At[m][k], acc[ai][bj][m][n], 0, 0, 0); __builtin_amdgcn_s_setprio(0); } while (0)
; #define PG8_WAIT_V(n) asm volatile("s_waitcnt vmcnt(" #n ")" ::: "memory")
; #define PG8_WAIT_L(n) asm volatile("s_waitcnt lgkmcnt(" #n ")" ::: "memory")
; #define PG8_BAR __builtin_amdgcn_s_barrier()
; #define PG8_SCHED __builtin_amdgcn_sched_barrier(0)
; template <class Epi, class Sched, bool ALIGN_EPI = false, bool SP2 = false>
; __device__ __forceinline__ void gemm_phase(PG8_LAS unsigned char* lds, const Gemm g, const Sched& S, const Epi& E) {
;     ...
;             const char* a1 = cA + (size_t)(t + 1) * kstep;
;             const char* a2 = last ? nA : cA + (size_t)(t + 2) * kstep; const char* b2 = last ? nB : cB + (size_t)(t + 2) * kstep;
;             const char* a3 = a2 + kstep; const char* b3 = b2 + kstep;
;             if constexpr (SP2) {
;             PG8_LDB(B0, 0, 0); PG8_LDB(B1, 0, 1); PG8_SCHED; PG8_LDA(At, 0, 0); PG8_STAGE(PG8_SA(1, 1), a1 + hstep, voffA);
;             PG8_WAIT_V(8); PG8_WAIT_L(0); PG8_BAR; PG8_MMA(0, 0, At, B0); PG8_MMA(0, 1, At, B1); PG8_BAR; PG8_SCHED;
;             PG8_LDA(At, 0, 1); PG8_STAGE(PG8_SB(0, 0), b2, voffB); PG8_STAGE(PG8_SB(0, 1), b2 + hstep, voffB); PG8_STAGE(PG8_SA(0, 0), a2, voffA);
;             PG8_WAIT_V(8); PG8_WAIT_L(0); PG8_BAR; PG8_MMA(1, 0, At, B0); PG8_MMA(1, 1, At, B1); PG8_BAR; PG8_SCHED;
.LBB0_545:
	ds_read_b128 v[112:115], v174
	ds_read_b128 v[116:119], v174 offset:1024
	ds_read_b128 v[120:123], v174 offset:2048
	ds_read_b128 v[124:127], v174 offset:3072
	ds_read_b128 v[164:167], v175
	ds_read_b128 v[168:171], v175 offset:1024
	ds_read_b128 v[178:181], v175 offset:2048
	ds_read_b128 v[182:185], v175 offset:3072
	s_add_u32 s52, s68, 0xfff80080
	s_addc_u32 s53, s69, -1
	s_cmp_eq_u32 s88, 28
	s_cselect_b32 s73, s41, s53
	s_cselect_b32 s72, s84, s52
	s_cselect_b32 s71, s37, s87
	s_cselect_b32 s70, s85, s86
	v_lshl_add_u64 v[218:219], s[68:69], 0, v[156:157]
	s_add_i32 m0, s39, 0xc000
	ds_read_b128 v[186:189], v176
	ds_read_b128 v[190:193], v176 offset:1024
	ds_read_b128 v[194:197], v176 offset:2048
	ds_read_b128 v[198:201], v176 offset:3072
	ds_read_b128 v[202:205], v176 offset:4096
	ds_read_b128 v[206:209], v176 offset:5120
	ds_read_b128 v[210:213], v176 offset:6144
	ds_read_b128 v[214:217], v176 offset:7168
	global_load_lds_dwordx4 v[218:219], off
	v_lshl_add_u64 v[218:219], s[68:69], 0, v[158:159]
	s_add_i32 m0, s39, 0xe000
	s_nop 0
	global_load_lds_dwordx4 v[218:219], off
	s_waitcnt vmcnt(8)
	s_waitcnt lgkmcnt(0)
	s_barrier
	s_setprio 1
	s_waitcnt lgkmcnt(0)
	v_mfma_f32_16x16x32_bf16 v[140:143], v[112:115], v[186:189], v[140:143]
	v_mfma_f32_16x16x32_bf16 v[136:139], v[120:123], v[186:189], v[136:139]
	v_mfma_f32_16x16x32_bf16 v[108:111], v[112:115], v[194:197], v[108:111]
	v_mfma_f32_16x16x32_bf16 v[104:107], v[120:123], v[194:197], v[104:107]
	v_mfma_f32_16x16x32_bf16 v[92:95], v[112:115], v[202:205], v[92:95]
	v_mfma_f32_16x16x32_bf16 v[88:91], v[120:123], v[202:205], v[88:91]
	v_mfma_f32_16x16x32_bf16 v[76:79], v[112:115], v[210:213], v[76:79]
	v_mfma_f32_16x16x32_bf16 v[72:75], v[120:123], v[210:213], v[72:75]
	v_mfma_f32_16x16x32_bf16 v[140:143], v[116:119], v[190:193], v[140:143]
	v_mfma_f32_16x16x32_bf16 v[136:139], v[124:127], v[190:193], v[136:139]
	v_mfma_f32_16x16x32_bf16 v[108:111], v[116:119], v[198:201], v[108:111]
	v_mfma_f32_16x16x32_bf16 v[104:107], v[124:127], v[198:201], v[104:107]
	v_mfma_f32_16x16x32_bf16 v[92:95], v[116:119], v[206:209], v[92:95]
	v_mfma_f32_16x16x32_bf16 v[88:91], v[124:127], v[206:209], v[88:91]
	v_mfma_f32_16x16x32_bf16 v[76:79], v[116:119], v[214:217], v[76:79]
	v_mfma_f32_16x16x32_bf16 v[72:75], v[124:127], v[214:217], v[72:75]
	s_setprio 0
	s_setprio 1
	v_mfma_f32_16x16x32_bf16 v[132:135], v[164:167], v[186:189], v[132:135]
	v_mfma_f32_16x16x32_bf16 v[128:131], v[178:181], v[186:189], v[128:131]
	v_mfma_f32_16x16x32_bf16 v[100:103], v[164:167], v[194:197], v[100:103]
	v_mfma_f32_16x16x32_bf16 v[96:99], v[178:181], v[194:197], v[96:99]
	v_mfma_f32_16x16x32_bf16 v[84:87], v[164:167], v[202:205], v[84:87]
	v_mfma_f32_16x16x32_bf16 v[80:83], v[178:181], v[202:205], v[80:83]
	v_mfma_f32_16x16x32_bf16 v[68:71], v[164:167], v[210:213], v[68:71]
	v_mfma_f32_16x16x32_bf16 v[64:67], v[178:181], v[210:213], v[64:67]
	v_mfma_f32_16x16x32_bf16 v[132:135], v[168:171], v[190:193], v[132:135]
	v_mfma_f32_16x16x32_bf16 v[128:131], v[182:185], v[190:193], v[128:131]
	v_mfma_f32_16x16x32_bf16 v[100:103], v[168:171], v[198:201], v[100:103]
	v_mfma_f32_16x16x32_bf16 v[96:99], v[182:185], v[198:201], v[96:99]
	v_mfma_f32_16x16x32_bf16 v[84:87], v[168:171], v[206:209], v[84:87]
	v_mfma_f32_16x16x32_bf16 v[80:83], v[182:185], v[206:209], v[80:83]
	v_mfma_f32_16x16x32_bf16 v[68:71], v[168:171], v[214:217], v[68:71]
	s_barrier
	v_mfma_f32_16x16x32_bf16 v[64:67], v[182:185], v[214:217], v[64:67]
	s_setprio 0
	s_add_i32 s52, s81, s29
	v_lshl_add_u64 v[218:219], s[70:71], 0, v[152:153]
	s_mov_b32 m0, s52
	ds_read_b128 v[186:189], v176 offset:16384
	ds_read_b128 v[190:193], v176 offset:17408
	ds_read_b128 v[194:197], v176 offset:18432
	ds_read_b128 v[198:201], v176 offset:19456
	ds_read_b128 v[202:205], v176 offset:20480
	ds_read_b128 v[206:209], v176 offset:21504
	ds_read_b128 v[210:213], v176 offset:22528
	ds_read_b128 v[214:217], v176 offset:23552
	global_load_lds_dwordx4 v[218:219], off
	s_add_i32 m0, s52, 0x2000
	s_add_u32 s52, s70, 0x80000
	v_lshl_add_u64 v[220:221], s[70:71], 0, v[148:149]
	s_addc_u32 s53, s71, 0
	s_add_i32 s56, s82, s29
	global_load_lds_dwordx4 v[220:221], off
	v_lshl_add_u64 v[222:223], s[52:53], 0, v[152:153]
	s_mov_b32 m0, s56
	v_lshl_add_u64 v[224:225], s[72:73], 0, v[150:151]
	global_load_lds_dwordx4 v[222:223], off
	v_lshl_add_u64 v[222:223], s[52:53], 0, v[148:149]
	s_add_i32 m0, s56, 0x2000
	s_nop 0
	global_load_lds_dwordx4 v[222:223], off
	v_lshl_add_u64 v[222:223], s[72:73], 0, v[154:155]
	s_mov_b32 m0, s39
	s_nop 0
	global_load_lds_dwordx4 v[222:223], off
	s_mov_b32 m0, s55
	s_nop 0
	global_load_lds_dwordx4 v[224:225], off
	s_waitcnt vmcnt(8)
	s_waitcnt lgkmcnt(0)
	s_barrier
; #define PG8_STAGE(bufoff, gbase, voff) do { _Pragma("unroll") for (int _i = 0; _i < 2; ++_i) \
;         __builtin_amdgcn_global_load_lds((const unsigned*)((const char*)(gbase) + (voff)[_i]), (PG8_LAS unsigned*)(lds + (bufoff) + ldsw + _i * 8192), 16, 0, 0); } while (0)
; #define PG8_LDA(dst, b, h) do { _Pragma("unroll") for (int m = 0; m < 4; ++m) _Pragma("unroll") for (int k = 0; k < 2; ++k) dst[m][k] = *(const PG8_LAS bf16x8*)(lds + PG8_SA(b, h) + aoff + m * 2048 + k * 1024); } while (0)
; #define PG8_LDB(dst, b, h) do { _Pragma("unroll") for (int n = 0; n < 2; ++n) _Pragma("unroll") for (int k = 0; k < 2; ++k) dst[n][k] = *(const PG8_LAS bf16x8*)(lds + PG8_SB(b, h) + boff + n * 2048 + k * 1024); } while (0)
; #define PG8_MMA(ai, bj, At, Bt) do { __builtin_amdgcn_s_setprio(1); _Pragma("unroll") for (int m = 0; m < 4; ++m) _Pragma("unroll") for (int n = 0; n < 2; ++n) _Pragma("unroll") for (int k = 0; k < 2; ++k) \
;         acc[ai][bj][m][n] = __builtin_amdgcn_mfma_f32_16x16x32_bf16(Bt[n][k], At[m][k], acc[ai][bj][m][n], 0, 0, 0); __builtin_amdgcn_s_setprio(0); } while (0)
; #define PG8_WAIT_V(n) asm volatile("s_waitcnt vmcnt(" #n ")" ::: "memory")
; #define PG8_WAIT_L(n) asm volatile("s_waitcnt lgkmcnt(" #n ")" ::: "memory")
; #define PG8_BAR __builtin_amdgcn_s_barrier()
; #define PG8_SCHED __builtin_amdgcn_sched_barrier(0)
; template <class Epi, class Sched, bool ALIGN_EPI = false, bool SP2 = false>
; __device__ __forceinline__ void gemm_phase(PG8_LAS unsigned char* lds, const Gemm g, const Sched& S, const Epi& E) {
;     ...
;             PG8_WAIT_V(8); PG8_WAIT_L(0); PG8_BAR; PG8_MMA(1, 0, At, B0); PG8_MMA(1, 1, At, B1); PG8_BAR; PG8_SCHED;
;             PG8_LDB(B0, 1, 0); PG8_LDB(B1, 1, 1); PG8_SCHED; PG8_LDA(At, 1, 0); PG8_STAGE(PG8_SA(0, 1), a2 + hstep, voffA);
;             PG8_WAIT_V(8); PG8_WAIT_L(0); PG8_BAR; PG8_MMA(0, 0, At, B0); PG8_MMA(0, 1, At, B1); PG8_BAR; PG8_SCHED;
	s_setprio 1
	s_waitcnt lgkmcnt(0)
	v_mfma_f32_16x16x32_bf16 v[60:63], v[112:115], v[186:189], v[60:63]
	v_mfma_f32_16x16x32_bf16 v[56:59], v[120:123], v[186:189], v[56:59]
	v_mfma_f32_16x16x32_bf16 v[44:47], v[112:115], v[194:197], v[44:47]
	v_mfma_f32_16x16x32_bf16 v[40:43], v[120:123], v[194:197], v[40:43]
	v_mfma_f32_16x16x32_bf16 v[28:31], v[112:115], v[202:205], v[28:31]
	v_mfma_f32_16x16x32_bf16 v[24:27], v[120:123], v[202:205], v[24:27]
	v_mfma_f32_16x16x32_bf16 v[12:15], v[112:115], v[210:213], v[12:15]
	v_mfma_f32_16x16x32_bf16 v[8:11], v[120:123], v[210:213], v[8:11]
	v_mfma_f32_16x16x32_bf16 v[60:63], v[116:119], v[190:193], v[60:63]
	v_mfma_f32_16x16x32_bf16 v[56:59], v[124:127], v[190:193], v[56:59]
	v_mfma_f32_16x16x32_bf16 v[44:47], v[116:119], v[198:201], v[44:47]
	v_mfma_f32_16x16x32_bf16 v[40:43], v[124:127], v[198:201], v[40:43]
	v_mfma_f32_16x16x32_bf16 v[28:31], v[116:119], v[206:209], v[28:31]
	v_mfma_f32_16x16x32_bf16 v[24:27], v[124:127], v[206:209], v[24:27]
	v_mfma_f32_16x16x32_bf16 v[12:15], v[116:119], v[214:217], v[12:15]
	v_mfma_f32_16x16x32_bf16 v[8:11], v[124:127], v[214:217], v[8:11]
	s_setprio 0
	s_setprio 1
	v_mfma_f32_16x16x32_bf16 v[52:55], v[164:167], v[186:189], v[52:55]
	v_mfma_f32_16x16x32_bf16 v[48:51], v[178:181], v[186:189], v[48:51]
	v_mfma_f32_16x16x32_bf16 v[36:39], v[164:167], v[194:197], v[36:39]
	v_mfma_f32_16x16x32_bf16 v[32:35], v[178:181], v[194:197], v[32:35]
	v_mfma_f32_16x16x32_bf16 v[20:23], v[164:167], v[202:205], v[20:23]
	v_mfma_f32_16x16x32_bf16 v[16:19], v[178:181], v[202:205], v[16:19]
	v_mfma_f32_16x16x32_bf16 v[4:7], v[164:167], v[210:213], v[4:7]
	v_mfma_f32_16x16x32_bf16 v[0:3], v[178:181], v[210:213], v[0:3]
	v_mfma_f32_16x16x32_bf16 v[52:55], v[168:171], v[190:193], v[52:55]
	v_mfma_f32_16x16x32_bf16 v[48:51], v[182:185], v[190:193], v[48:51]
	v_mfma_f32_16x16x32_bf16 v[36:39], v[168:171], v[198:201], v[36:39]
	v_mfma_f32_16x16x32_bf16 v[32:35], v[182:185], v[198:201], v[32:35]
	v_mfma_f32_16x16x32_bf16 v[20:23], v[168:171], v[206:209], v[20:23]
	v_mfma_f32_16x16x32_bf16 v[16:19], v[182:185], v[206:209], v[16:19]
	v_mfma_f32_16x16x32_bf16 v[4:7], v[168:171], v[214:217], v[4:7]
	s_barrier
	v_mfma_f32_16x16x32_bf16 v[0:3], v[182:185], v[214:217], v[0:3]
	s_setprio 0
	s_add_i32 s56, 0, 0x18000
	s_add_i32 s57, 0, 0x1c000
	v_add_u32_e32 v124, s56, v172
	v_add_u32_e32 v177, s57, v172
	ds_read_b128 v[112:115], v124
	ds_read_b128 v[116:119], v124 offset:1024
	ds_read_b128 v[120:123], v124 offset:2048
	ds_read_b128 v[124:127], v124 offset:3072
	ds_read_b128 v[164:167], v177
	ds_read_b128 v[168:171], v177 offset:1024
	ds_read_b128 v[178:181], v177 offset:2048
	ds_read_b128 v[182:185], v177 offset:3072
	s_add_u32 s52, s72, 0x80000
	s_addc_u32 s53, s73, 0
	s_mov_b32 m0, s74
	v_lshl_add_u64 v[226:227], s[52:53], 0, v[154:155]
	ds_read_b128 v[186:189], v176 offset:32768
	ds_read_b128 v[190:193], v176 offset:33792
	ds_read_b128 v[194:197], v176 offset:34816
	ds_read_b128 v[198:201], v176 offset:35840
	ds_read_b128 v[202:205], v176 offset:36864
	ds_read_b128 v[206:209], v176 offset:37888
	ds_read_b128 v[210:213], v176 offset:38912
	ds_read_b128 v[214:217], v176 offset:39936
	global_load_lds_dwordx4 v[226:227], off
	v_lshl_add_u64 v[226:227], s[52:53], 0, v[150:151]
	s_mov_b32 m0, s75
	s_nop 0
	global_load_lds_dwordx4 v[226:227], off
	s_waitcnt vmcnt(8)
	s_waitcnt lgkmcnt(0)
	s_barrier
	s_setprio 1
	s_waitcnt lgkmcnt(0)
	v_mfma_f32_16x16x32_bf16 v[140:143], v[112:115], v[186:189], v[140:143]
	v_mfma_f32_16x16x32_bf16 v[136:139], v[120:123], v[186:189], v[136:139]
	v_mfma_f32_16x16x32_bf16 v[108:111], v[112:115], v[194:197], v[108:111]
	v_mfma_f32_16x16x32_bf16 v[104:107], v[120:123], v[194:197], v[104:107]
	v_mfma_f32_16x16x32_bf16 v[92:95], v[112:115], v[202:205], v[92:95]
	v_mfma_f32_16x16x32_bf16 v[88:91], v[120:123], v[202:205], v[88:91]
	v_mfma_f32_16x16x32_bf16 v[76:79], v[112:115], v[210:213], v[76:79]
	v_mfma_f32_16x16x32_bf16 v[72:75], v[120:123], v[210:213], v[72:75]
	v_mfma_f32_16x16x32_bf16 v[140:143], v[116:119], v[190:193], v[140:143]
	v_mfma_f32_16x16x32_bf16 v[136:139], v[124:127], v[190:193], v[136:139]
	v_mfma_f32_16x16x32_bf16 v[108:111], v[116:119], v[198:201], v[108:111]
	v_mfma_f32_16x16x32_bf16 v[104:107], v[124:127], v[198:201], v[104:107]
	v_mfma_f32_16x16x32_bf16 v[92:95], v[116:119], v[206:209], v[92:95]
	v_mfma_f32_16x16x32_bf16 v[88:91], v[124:127], v[206:209], v[88:91]
	v_mfma_f32_16x16x32_bf16 v[76:79], v[116:119], v[214:217], v[76:79]
	v_mfma_f32_16x16x32_bf16 v[72:75], v[124:127], v[214:217], v[72:75]
	s_setprio 0
	s_setprio 1
	v_mfma_f32_16x16x32_bf16 v[132:135], v[164:167], v[186:189], v[132:135]
	v_mfma_f32_16x16x32_bf16 v[128:131], v[178:181], v[186:189], v[128:131]
	v_mfma_f32_16x16x32_bf16 v[100:103], v[164:167], v[194:197], v[100:103]
	v_mfma_f32_16x16x32_bf16 v[96:99], v[178:181], v[194:197], v[96:99]
	v_mfma_f32_16x16x32_bf16 v[84:87], v[164:167], v[202:205], v[84:87]
	v_mfma_f32_16x16x32_bf16 v[80:83], v[178:181], v[202:205], v[80:83]
	v_mfma_f32_16x16x32_bf16 v[68:71], v[164:167], v[210:213], v[68:71]
	v_mfma_f32_16x16x32_bf16 v[64:67], v[178:181], v[210:213], v[64:67]
	v_mfma_f32_16x16x32_bf16 v[132:135], v[168:171], v[190:193], v[132:135]
	v_mfma_f32_16x16x32_bf16 v[128:131], v[182:185], v[190:193], v[128:131]
	v_mfma_f32_16x16x32_bf16 v[100:103], v[168:171], v[198:201], v[100:103]
	v_mfma_f32_16x16x32_bf16 v[96:99], v[182:185], v[198:201], v[96:99]
	v_mfma_f32_16x16x32_bf16 v[84:87], v[168:171], v[206:209], v[84:87]
	v_mfma_f32_16x16x32_bf16 v[80:83], v[182:185], v[206:209], v[80:83]
	v_mfma_f32_16x16x32_bf16 v[68:71], v[168:171], v[214:217], v[68:71]
	s_barrier
; #define PG8_STAGE(bufoff, gbase, voff) do { _Pragma("unroll") for (int _i = 0; _i < 2; ++_i) \
;         __builtin_amdgcn_global_load_lds((const unsigned*)((const char*)(gbase) + (voff)[_i]), (PG8_LAS unsigned*)(lds + (bufoff) + ldsw + _i * 8192), 16, 0, 0); } while (0)
; #define PG8_LDA(dst, b, h) do { _Pragma("unroll") for (int m = 0; m < 4; ++m) _Pragma("unroll") for (int k = 0; k < 2; ++k) dst[m][k] = *(const PG8_LAS bf16x8*)(lds + PG8_SA(b, h) + aoff + m * 2048 + k * 1024); } while (0)
; #define PG8_MMA(ai, bj, At, Bt) do { __builtin_amdgcn_s_setprio(1); _Pragma("unroll") for (int m = 0; m < 4; ++m) _Pragma("unroll") for (int n = 0; n < 2; ++n) _Pragma("unroll") for (int k = 0; k < 2; ++k) \
;         acc[ai][bj][m][n] = __builtin_amdgcn_mfma_f32_16x16x32_bf16(Bt[n][k], At[m][k], acc[ai][bj][m][n], 0, 0, 0); __builtin_amdgcn_s_setprio(0); } while (0)
; #define PG8_WAIT_V(n) asm volatile("s_waitcnt vmcnt(" #n ")" ::: "memory")
; #define PG8_WAIT_L(n) asm volatile("s_waitcnt lgkmcnt(" #n ")" ::: "memory")
; #define PG8_BAR __builtin_amdgcn_s_barrier()
; #define PG8_SCHED __builtin_amdgcn_sched_barrier(0)
; template <class Epi, class Sched, bool ALIGN_EPI = false, bool SP2 = false>
; __device__ __forceinline__ void gemm_phase(PG8_LAS unsigned char* lds, const Gemm g, const Sched& S, const Epi& E) {
;     ...
;             PG8_WAIT_V(8); PG8_WAIT_L(0); PG8_BAR; PG8_MMA(0, 0, At, B0); PG8_MMA(0, 1, At, B1); PG8_BAR; PG8_SCHED;
;             PG8_LDA(At, 1, 1); PG8_STAGE(PG8_SB(1, 0), b3, voffB); PG8_STAGE(PG8_SB(1, 1), b3 + hstep, voffB); PG8_STAGE(PG8_SA(1, 0), a3, voffA);
;             PG8_WAIT_V(8); PG8_WAIT_L(0); PG8_BAR; PG8_MMA(1, 0, At, B0); PG8_MMA(1, 1, At, B1); PG8_BAR; PG8_SCHED;
;     ...
;         if constexpr (ALIGN_EPI) { if (wr == 0) PG8_BAR; }
	v_mfma_f32_16x16x32_bf16 v[64:67], v[182:185], v[214:217], v[64:67]
	s_setprio 0
	s_add_i32 s52, s56, s29
	v_lshl_add_u64 v[218:219], v[218:219], 0, s[12:13]
	s_mov_b32 m0, s52
	ds_read_b128 v[186:189], v176 offset:49152
	ds_read_b128 v[190:193], v176 offset:50176
	ds_read_b128 v[194:197], v176 offset:51200
	ds_read_b128 v[198:201], v176 offset:52224
	ds_read_b128 v[202:205], v176 offset:53248
	ds_read_b128 v[206:209], v176 offset:54272
	ds_read_b128 v[210:213], v176 offset:55296
	ds_read_b128 v[214:217], v176 offset:56320
	global_load_lds_dwordx4 v[218:219], off
	s_add_i32 m0, s52, 0x2000
	s_add_u32 s52, s70, 0x80080
	v_lshl_add_u64 v[218:219], v[220:221], 0, s[12:13]
	s_addc_u32 s53, s71, 0
	s_add_i32 s56, s57, s29
	global_load_lds_dwordx4 v[218:219], off
	v_lshl_add_u64 v[218:219], s[52:53], 0, v[152:153]
	s_mov_b32 m0, s56
	s_nop 0
	global_load_lds_dwordx4 v[218:219], off
	v_lshl_add_u64 v[218:219], s[52:53], 0, v[148:149]
	s_add_i32 m0, s56, 0x2000
	s_nop 0
	global_load_lds_dwordx4 v[218:219], off
	v_lshl_add_u64 v[218:219], v[222:223], 0, s[12:13]
	s_mov_b32 m0, s77
	s_nop 0
	global_load_lds_dwordx4 v[218:219], off
	v_lshl_add_u64 v[218:219], v[224:225], 0, s[12:13]
	s_mov_b32 m0, s78
	s_nop 0
	global_load_lds_dwordx4 v[218:219], off
	s_waitcnt vmcnt(8)
	s_waitcnt lgkmcnt(0)
	s_barrier
	s_setprio 1
	s_waitcnt lgkmcnt(0)
	v_mfma_f32_16x16x32_bf16 v[60:63], v[112:115], v[186:189], v[60:63]
	v_mfma_f32_16x16x32_bf16 v[56:59], v[120:123], v[186:189], v[56:59]
	v_mfma_f32_16x16x32_bf16 v[44:47], v[112:115], v[194:197], v[44:47]
	v_mfma_f32_16x16x32_bf16 v[40:43], v[120:123], v[194:197], v[40:43]
	v_mfma_f32_16x16x32_bf16 v[28:31], v[112:115], v[202:205], v[28:31]
	v_mfma_f32_16x16x32_bf16 v[24:27], v[120:123], v[202:205], v[24:27]
	v_mfma_f32_16x16x32_bf16 v[12:15], v[112:115], v[210:213], v[12:15]
	v_mfma_f32_16x16x32_bf16 v[8:11], v[120:123], v[210:213], v[8:11]
	v_mfma_f32_16x16x32_bf16 v[60:63], v[116:119], v[190:193], v[60:63]
	v_mfma_f32_16x16x32_bf16 v[56:59], v[124:127], v[190:193], v[56:59]
	v_mfma_f32_16x16x32_bf16 v[44:47], v[116:119], v[198:201], v[44:47]
	v_mfma_f32_16x16x32_bf16 v[40:43], v[124:127], v[198:201], v[40:43]
	v_mfma_f32_16x16x32_bf16 v[28:31], v[116:119], v[206:209], v[28:31]
	v_mfma_f32_16x16x32_bf16 v[24:27], v[124:127], v[206:209], v[24:27]
	v_mfma_f32_16x16x32_bf16 v[12:15], v[116:119], v[214:217], v[12:15]
	v_mfma_f32_16x16x32_bf16 v[8:11], v[124:127], v[214:217], v[8:11]
	s_setprio 0
	s_setprio 1
	v_mfma_f32_16x16x32_bf16 v[52:55], v[164:167], v[186:189], v[52:55]
	v_mfma_f32_16x16x32_bf16 v[48:51], v[178:181], v[186:189], v[48:51]
	v_mfma_f32_16x16x32_bf16 v[36:39], v[164:167], v[194:197], v[36:39]
	v_mfma_f32_16x16x32_bf16 v[32:35], v[178:181], v[194:197], v[32:35]
	v_mfma_f32_16x16x32_bf16 v[20:23], v[164:167], v[202:205], v[20:23]
	v_mfma_f32_16x16x32_bf16 v[16:19], v[178:181], v[202:205], v[16:19]
	v_mfma_f32_16x16x32_bf16 v[4:7], v[164:167], v[210:213], v[4:7]
	v_mfma_f32_16x16x32_bf16 v[0:3], v[178:181], v[210:213], v[0:3]
	v_mfma_f32_16x16x32_bf16 v[52:55], v[168:171], v[190:193], v[52:55]
	v_mfma_f32_16x16x32_bf16 v[48:51], v[182:185], v[190:193], v[48:51]
	v_mfma_f32_16x16x32_bf16 v[36:39], v[168:171], v[198:201], v[36:39]
	v_mfma_f32_16x16x32_bf16 v[32:35], v[182:185], v[198:201], v[32:35]
	v_mfma_f32_16x16x32_bf16 v[20:23], v[168:171], v[206:209], v[20:23]
	v_mfma_f32_16x16x32_bf16 v[16:19], v[182:185], v[206:209], v[16:19]
	v_mfma_f32_16x16x32_bf16 v[4:7], v[168:171], v[214:217], v[4:7]
	s_barrier
	v_mfma_f32_16x16x32_bf16 v[0:3], v[182:185], v[214:217], v[0:3]
	s_setprio 0
	s_add_i32 s88, s88, 2
	s_add_u32 s68, s68, 0x100
	s_addc_u32 s69, s69, 0
	s_add_u32 s86, s86, 0x100
	s_addc_u32 s87, s87, 0
	s_cmp_gt_u32 s88, 29
	s_cbranch_scc0 .LBB0_545
	s_and_b64 vcc, exec, s[14:15]
	s_cbranch_vccz .LBB0_548
	s_barrier

; #define PG8_STAGE(bufoff, gbase, voff) do { _Pragma("unroll") for (int _i = 0; _i < 2; ++_i) \
;         __builtin_amdgcn_global_load_lds((const unsigned*)((const char*)(gbase) + (voff)[_i]), (PG8_LAS unsigned*)(lds + (bufoff) + ldsw + _i * 8192), 16, 0, 0); } while (0)
; #define PG8_LDA(dst, b, h) do { _Pragma("unroll") for (int m = 0; m < 4; ++m) _Pragma("unroll") for (int k = 0; k < 2; ++k) dst[m][k] = *(const PG8_LAS bf16x8*)(lds + PG8_SA(b, h) + aoff + m * 2048 + k * 1024); } while (0)
; #define PG8_LDB(dst, b, h) do { _Pragma("unroll") for (int n = 0; n < 2; ++n) _Pragma("unroll") for (int k = 0; k < 2; ++k) dst[n][k] = *(const PG8_LAS bf16x8*)(lds + PG8_SB(b, h) + boff + n * 2048 + k * 1024); } while (0)
; #define PG8_MMA(ai, bj, At, Bt) do { __builtin_amdgcn_s_setprio(1); _Pragma("unroll") for (int m = 0; m < 4; ++m) _Pragma("unroll") for (int n = 0; n < 2; ++n) _Pragma("unroll") for (int k = 0; k < 2; ++k) \
;         acc[ai][bj][m][n] = __builtin_amdgcn_mfma_f32_16x16x32_bf16(Bt[n][k], At[m][k], acc[ai][bj][m][n], 0, 0, 0); __builtin_amdgcn_s_setprio(0); } while (0)
; #define PG8_WAIT_V(n) asm volatile("s_waitcnt vmcnt(" #n ")" ::: "memory")
; #define PG8_WAIT_L(n) asm volatile("s_waitcnt lgkmcnt(" #n ")" ::: "memory")
; #define PG8_BAR __builtin_amdgcn_s_barrier()
; #define PG8_SCHED __builtin_amdgcn_sched_barrier(0)
; template <class Epi, class Sched, bool ALIGN_EPI = false, bool SP2 = false>
; __device__ __forceinline__ void gemm_phase(PG8_LAS unsigned char* lds, const Gemm g, const Sched& S, const Epi& E) {
;     ...
;             const char* a1 = cA + (size_t)(t + 1) * kstep;
;             const char* a2 = last ? nA : cA + (size_t)(t + 2) * kstep; const char* b2 = last ? nB : cB + (size_t)(t + 2) * kstep;
;             const char* a3 = a2 + kstep; const char* b3 = b2 + kstep;
;             if constexpr (SP2) {
;             PG8_LDB(B0, 0, 0); PG8_LDB(B1, 0, 1); PG8_SCHED; PG8_LDA(At, 0, 0); PG8_STAGE(PG8_SA(1, 1), a1 + hstep, voffA);
;             PG8_WAIT_V(8); PG8_WAIT_L(0); PG8_BAR; PG8_MMA(0, 0, At, B0); PG8_MMA(0, 1, At, B1); PG8_BAR; PG8_SCHED;
;             PG8_LDA(At, 0, 1); PG8_STAGE(PG8_SB(0, 0), b2, voffB); PG8_STAGE(PG8_SB(0, 1), b2 + hstep, voffB); PG8_STAGE(PG8_SA(0, 0), a2, voffA);
;             PG8_WAIT_V(8); PG8_WAIT_L(0); PG8_BAR; PG8_MMA(1, 0, At, B0); PG8_MMA(1, 1, At, B1); PG8_BAR; PG8_SCHED;
.LBB0_624:
	ds_read_b128 v[128:131], v214
	ds_read_b128 v[132:135], v214 offset:1024
	ds_read_b128 v[158:161], v214 offset:2048
	ds_read_b128 v[162:165], v214 offset:3072
	ds_read_b128 v[166:169], v215
	ds_read_b128 v[170:173], v215 offset:1024
	ds_read_b128 v[174:177], v215 offset:2048
	ds_read_b128 v[178:181], v215 offset:3072
	s_add_u32 s52, s74, 0xffe00080
	s_addc_u32 s53, s75, -1
	s_cmpk_eq_i32 vcc_hi, 0x7c
	s_cselect_b32 s79, s51, s53
	s_cselect_b32 s78, s71, s52
	s_cselect_b32 s77, s49, vcc_lo
	s_cselect_b32 s76, s73, s93
	v_lshl_add_u64 v[226:227], s[74:75], 0, v[150:151]
	s_add_i32 m0, s83, 0xc000
	ds_read_b128 v[182:185], v216
	ds_read_b128 v[186:189], v216 offset:1024
	ds_read_b128 v[190:193], v216 offset:2048
	ds_read_b128 v[194:197], v216 offset:3072
	ds_read_b128 v[198:201], v216 offset:4096
	ds_read_b128 v[202:205], v216 offset:5120
	ds_read_b128 v[218:221], v216 offset:6144
	ds_read_b128 v[222:225], v216 offset:7168
	global_load_lds_dwordx4 v[226:227], off
	v_lshl_add_u64 v[226:227], s[74:75], 0, v[152:153]
	s_add_i32 m0, s83, 0xe000
	s_nop 0
	global_load_lds_dwordx4 v[226:227], off
	s_waitcnt vmcnt(8)
	s_waitcnt lgkmcnt(0)
	s_barrier
	s_setprio 1
	s_waitcnt lgkmcnt(0)
	v_mfma_f32_16x16x32_bf16 v[124:127], v[128:131], v[182:185], v[124:127]
	v_mfma_f32_16x16x32_bf16 v[120:123], v[158:161], v[182:185], v[120:123]
	v_mfma_f32_16x16x32_bf16 v[116:119], v[128:131], v[190:193], v[116:119]
	v_mfma_f32_16x16x32_bf16 v[112:115], v[158:161], v[190:193], v[112:115]
	v_mfma_f32_16x16x32_bf16 v[108:111], v[128:131], v[198:201], v[108:111]
	v_mfma_f32_16x16x32_bf16 v[104:107], v[158:161], v[198:201], v[104:107]
	v_mfma_f32_16x16x32_bf16 v[100:103], v[128:131], v[218:221], v[100:103]
	v_mfma_f32_16x16x32_bf16 v[96:99], v[158:161], v[218:221], v[96:99]
	v_mfma_f32_16x16x32_bf16 v[124:127], v[132:135], v[186:189], v[124:127]
	v_mfma_f32_16x16x32_bf16 v[120:123], v[162:165], v[186:189], v[120:123]
	v_mfma_f32_16x16x32_bf16 v[116:119], v[132:135], v[194:197], v[116:119]
	v_mfma_f32_16x16x32_bf16 v[112:115], v[162:165], v[194:197], v[112:115]
	v_mfma_f32_16x16x32_bf16 v[108:111], v[132:135], v[202:205], v[108:111]
	v_mfma_f32_16x16x32_bf16 v[104:107], v[162:165], v[202:205], v[104:107]
	v_mfma_f32_16x16x32_bf16 v[100:103], v[132:135], v[222:225], v[100:103]
	v_mfma_f32_16x16x32_bf16 v[96:99], v[162:165], v[222:225], v[96:99]
	s_setprio 0
	s_setprio 1
	v_mfma_f32_16x16x32_bf16 v[60:63], v[166:169], v[182:185], v[60:63]
	v_mfma_f32_16x16x32_bf16 v[56:59], v[174:177], v[182:185], v[56:59]
	v_mfma_f32_16x16x32_bf16 v[52:55], v[166:169], v[190:193], v[52:55]
	v_mfma_f32_16x16x32_bf16 v[48:51], v[174:177], v[190:193], v[48:51]
	v_mfma_f32_16x16x32_bf16 v[44:47], v[166:169], v[198:201], v[44:47]
	v_mfma_f32_16x16x32_bf16 v[40:43], v[174:177], v[198:201], v[40:43]
	v_mfma_f32_16x16x32_bf16 v[36:39], v[166:169], v[218:221], v[36:39]
	v_mfma_f32_16x16x32_bf16 v[32:35], v[174:177], v[218:221], v[32:35]
	v_mfma_f32_16x16x32_bf16 v[60:63], v[170:173], v[186:189], v[60:63]
	v_mfma_f32_16x16x32_bf16 v[56:59], v[178:181], v[186:189], v[56:59]
	v_mfma_f32_16x16x32_bf16 v[52:55], v[170:173], v[194:197], v[52:55]
	v_mfma_f32_16x16x32_bf16 v[48:51], v[178:181], v[194:197], v[48:51]
	v_mfma_f32_16x16x32_bf16 v[44:47], v[170:173], v[202:205], v[44:47]
	v_mfma_f32_16x16x32_bf16 v[40:43], v[178:181], v[202:205], v[40:43]
	v_mfma_f32_16x16x32_bf16 v[36:39], v[170:173], v[222:225], v[36:39]
	s_barrier
	v_mfma_f32_16x16x32_bf16 v[32:35], v[178:181], v[222:225], v[32:35]
	s_setprio 0
	s_add_i32 s52, s33, s82
	v_lshl_add_u64 v[226:227], s[76:77], 0, v[138:139]
	s_mov_b32 m0, s52
	ds_read_b128 v[182:185], v216 offset:16384
	ds_read_b128 v[186:189], v216 offset:17408
	ds_read_b128 v[190:193], v216 offset:18432
	ds_read_b128 v[194:197], v216 offset:19456
	ds_read_b128 v[198:201], v216 offset:20480
	ds_read_b128 v[202:205], v216 offset:21504
	ds_read_b128 v[218:221], v216 offset:22528
	ds_read_b128 v[222:225], v216 offset:23552
	global_load_lds_dwordx4 v[226:227], off
	s_add_i32 m0, s52, 0x2000
	s_add_u32 s52, s76, 0x200000
	v_lshl_add_u64 v[228:229], s[76:77], 0, v[142:143]
	s_addc_u32 s53, s77, 0
	s_add_i32 s56, s92, s82
	global_load_lds_dwordx4 v[228:229], off
	v_lshl_add_u64 v[230:231], s[52:53], 0, v[138:139]
	s_mov_b32 m0, s56
	v_lshl_add_u64 v[232:233], s[78:79], 0, v[140:141]
	global_load_lds_dwordx4 v[230:231], off
	v_lshl_add_u64 v[230:231], s[52:53], 0, v[142:143]
	s_add_i32 m0, s56, 0x2000
	s_nop 0
	global_load_lds_dwordx4 v[230:231], off
	v_lshl_add_u64 v[230:231], s[78:79], 0, v[136:137]
	s_mov_b32 m0, s83
	s_nop 0
	global_load_lds_dwordx4 v[230:231], off
	s_mov_b32 m0, s84
	s_nop 0
	global_load_lds_dwordx4 v[232:233], off
	s_waitcnt vmcnt(8)
	s_waitcnt lgkmcnt(0)
	s_barrier
; #define PG8_STAGE(bufoff, gbase, voff) do { _Pragma("unroll") for (int _i = 0; _i < 2; ++_i) \
;         __builtin_amdgcn_global_load_lds((const unsigned*)((const char*)(gbase) + (voff)[_i]), (PG8_LAS unsigned*)(lds + (bufoff) + ldsw + _i * 8192), 16, 0, 0); } while (0)
; #define PG8_LDA(dst, b, h) do { _Pragma("unroll") for (int m = 0; m < 4; ++m) _Pragma("unroll") for (int k = 0; k < 2; ++k) dst[m][k] = *(const PG8_LAS bf16x8*)(lds + PG8_SA(b, h) + aoff + m * 2048 + k * 1024); } while (0)
; #define PG8_LDB(dst, b, h) do { _Pragma("unroll") for (int n = 0; n < 2; ++n) _Pragma("unroll") for (int k = 0; k < 2; ++k) dst[n][k] = *(const PG8_LAS bf16x8*)(lds + PG8_SB(b, h) + boff + n * 2048 + k * 1024); } while (0)
; #define PG8_MMA(ai, bj, At, Bt) do { __builtin_amdgcn_s_setprio(1); _Pragma("unroll") for (int m = 0; m < 4; ++m) _Pragma("unroll") for (int n = 0; n < 2; ++n) _Pragma("unroll") for (int k = 0; k < 2; ++k) \
;         acc[ai][bj][m][n] = __builtin_amdgcn_mfma_f32_16x16x32_bf16(Bt[n][k], At[m][k], acc[ai][bj][m][n], 0, 0, 0); __builtin_amdgcn_s_setprio(0); } while (0)
; #define PG8_WAIT_V(n) asm volatile("s_waitcnt vmcnt(" #n ")" ::: "memory")
; #define PG8_WAIT_L(n) asm volatile("s_waitcnt lgkmcnt(" #n ")" ::: "memory")
; #define PG8_BAR __builtin_amdgcn_s_barrier()
; #define PG8_SCHED __builtin_amdgcn_sched_barrier(0)
; template <class Epi, class Sched, bool ALIGN_EPI = false, bool SP2 = false>
; __device__ __forceinline__ void gemm_phase(PG8_LAS unsigned char* lds, const Gemm g, const Sched& S, const Epi& E) {
;     ...
;             PG8_WAIT_V(8); PG8_WAIT_L(0); PG8_BAR; PG8_MMA(1, 0, At, B0); PG8_MMA(1, 1, At, B1); PG8_BAR; PG8_SCHED;
;             PG8_LDB(B0, 1, 0); PG8_LDB(B1, 1, 1); PG8_SCHED; PG8_LDA(At, 1, 0); PG8_STAGE(PG8_SA(0, 1), a2 + hstep, voffA);
;             PG8_WAIT_V(8); PG8_WAIT_L(0); PG8_BAR; PG8_MMA(0, 0, At, B0); PG8_MMA(0, 1, At, B1); PG8_BAR; PG8_SCHED;
	s_setprio 1
	s_waitcnt lgkmcnt(0)
	v_mfma_f32_16x16x32_bf16 v[92:95], v[128:131], v[182:185], v[92:95]
	v_mfma_f32_16x16x32_bf16 v[88:91], v[158:161], v[182:185], v[88:91]
	v_mfma_f32_16x16x32_bf16 v[84:87], v[128:131], v[190:193], v[84:87]
	v_mfma_f32_16x16x32_bf16 v[80:83], v[158:161], v[190:193], v[80:83]
	v_mfma_f32_16x16x32_bf16 v[76:79], v[128:131], v[198:201], v[76:79]
	v_mfma_f32_16x16x32_bf16 v[72:75], v[158:161], v[198:201], v[72:75]
	v_mfma_f32_16x16x32_bf16 v[68:71], v[128:131], v[218:221], v[68:71]
	v_mfma_f32_16x16x32_bf16 v[64:67], v[158:161], v[218:221], v[64:67]
	v_mfma_f32_16x16x32_bf16 v[92:95], v[132:135], v[186:189], v[92:95]
	v_mfma_f32_16x16x32_bf16 v[88:91], v[162:165], v[186:189], v[88:91]
	v_mfma_f32_16x16x32_bf16 v[84:87], v[132:135], v[194:197], v[84:87]
	v_mfma_f32_16x16x32_bf16 v[80:83], v[162:165], v[194:197], v[80:83]
	v_mfma_f32_16x16x32_bf16 v[76:79], v[132:135], v[202:205], v[76:79]
	v_mfma_f32_16x16x32_bf16 v[72:75], v[162:165], v[202:205], v[72:75]
	v_mfma_f32_16x16x32_bf16 v[68:71], v[132:135], v[222:225], v[68:71]
	v_mfma_f32_16x16x32_bf16 v[64:67], v[162:165], v[222:225], v[64:67]
	s_setprio 0
	s_setprio 1
	v_mfma_f32_16x16x32_bf16 v[28:31], v[166:169], v[182:185], v[28:31]
	v_mfma_f32_16x16x32_bf16 v[24:27], v[174:177], v[182:185], v[24:27]
	v_mfma_f32_16x16x32_bf16 v[20:23], v[166:169], v[190:193], v[20:23]
	v_mfma_f32_16x16x32_bf16 v[16:19], v[174:177], v[190:193], v[16:19]
	v_mfma_f32_16x16x32_bf16 v[12:15], v[166:169], v[198:201], v[12:15]
	v_mfma_f32_16x16x32_bf16 v[8:11], v[174:177], v[198:201], v[8:11]
	v_mfma_f32_16x16x32_bf16 v[4:7], v[166:169], v[218:221], v[4:7]
	v_mfma_f32_16x16x32_bf16 v[0:3], v[174:177], v[218:221], v[0:3]
	v_mfma_f32_16x16x32_bf16 v[28:31], v[170:173], v[186:189], v[28:31]
	v_mfma_f32_16x16x32_bf16 v[24:27], v[178:181], v[186:189], v[24:27]
	v_mfma_f32_16x16x32_bf16 v[20:23], v[170:173], v[194:197], v[20:23]
	v_mfma_f32_16x16x32_bf16 v[16:19], v[178:181], v[194:197], v[16:19]
	v_mfma_f32_16x16x32_bf16 v[12:15], v[170:173], v[202:205], v[12:15]
	v_mfma_f32_16x16x32_bf16 v[8:11], v[178:181], v[202:205], v[8:11]
	v_mfma_f32_16x16x32_bf16 v[4:7], v[170:173], v[222:225], v[4:7]
	s_barrier
	v_mfma_f32_16x16x32_bf16 v[0:3], v[178:181], v[222:225], v[0:3]
	s_setprio 0
	s_add_i32 s56, 0, 0x18000
	s_add_i32 s57, 0, 0x1c000
	v_add_u32_e32 v162, s56, v212
	v_add_u32_e32 v178, s57, v212
	ds_read_b128 v[128:131], v162
	ds_read_b128 v[132:135], v162 offset:1024
	ds_read_b128 v[158:161], v162 offset:2048
	ds_read_b128 v[162:165], v162 offset:3072
	ds_read_b128 v[166:169], v178
	ds_read_b128 v[170:173], v178 offset:1024
	ds_read_b128 v[174:177], v178 offset:2048
	ds_read_b128 v[178:181], v178 offset:3072
	s_add_u32 s52, s78, 0x200000
	s_addc_u32 s53, s79, 0
	s_mov_b32 m0, s85
	v_lshl_add_u64 v[234:235], s[52:53], 0, v[136:137]
	ds_read_b128 v[182:185], v216 offset:32768
	ds_read_b128 v[186:189], v216 offset:33792
	ds_read_b128 v[190:193], v216 offset:34816
	ds_read_b128 v[194:197], v216 offset:35840
	ds_read_b128 v[198:201], v216 offset:36864
	ds_read_b128 v[202:205], v216 offset:37888
	ds_read_b128 v[218:221], v216 offset:38912
	ds_read_b128 v[222:225], v216 offset:39936
	global_load_lds_dwordx4 v[234:235], off
	v_lshl_add_u64 v[234:235], s[52:53], 0, v[140:141]
	s_mov_b32 m0, s86
	s_nop 0
	global_load_lds_dwordx4 v[234:235], off
	s_waitcnt vmcnt(8)
	s_waitcnt lgkmcnt(0)
	s_barrier
	s_setprio 1
	s_waitcnt lgkmcnt(0)
	v_mfma_f32_16x16x32_bf16 v[124:127], v[128:131], v[182:185], v[124:127]
	v_mfma_f32_16x16x32_bf16 v[120:123], v[158:161], v[182:185], v[120:123]
	v_mfma_f32_16x16x32_bf16 v[116:119], v[128:131], v[190:193], v[116:119]
	v_mfma_f32_16x16x32_bf16 v[112:115], v[158:161], v[190:193], v[112:115]
	v_mfma_f32_16x16x32_bf16 v[108:111], v[128:131], v[198:201], v[108:111]
	v_mfma_f32_16x16x32_bf16 v[104:107], v[158:161], v[198:201], v[104:107]
	v_mfma_f32_16x16x32_bf16 v[100:103], v[128:131], v[218:221], v[100:103]
	v_mfma_f32_16x16x32_bf16 v[96:99], v[158:161], v[218:221], v[96:99]
	v_mfma_f32_16x16x32_bf16 v[124:127], v[132:135], v[186:189], v[124:127]
	v_mfma_f32_16x16x32_bf16 v[120:123], v[162:165], v[186:189], v[120:123]
	v_mfma_f32_16x16x32_bf16 v[116:119], v[132:135], v[194:197], v[116:119]
	v_mfma_f32_16x16x32_bf16 v[112:115], v[162:165], v[194:197], v[112:115]
	v_mfma_f32_16x16x32_bf16 v[108:111], v[132:135], v[202:205], v[108:111]
	v_mfma_f32_16x16x32_bf16 v[104:107], v[162:165], v[202:205], v[104:107]
	v_mfma_f32_16x16x32_bf16 v[100:103], v[132:135], v[222:225], v[100:103]
	v_mfma_f32_16x16x32_bf16 v[96:99], v[162:165], v[222:225], v[96:99]
	s_setprio 0
	s_setprio 1
	v_mfma_f32_16x16x32_bf16 v[60:63], v[166:169], v[182:185], v[60:63]
	v_mfma_f32_16x16x32_bf16 v[56:59], v[174:177], v[182:185], v[56:59]
	v_mfma_f32_16x16x32_bf16 v[52:55], v[166:169], v[190:193], v[52:55]
	v_mfma_f32_16x16x32_bf16 v[48:51], v[174:177], v[190:193], v[48:51]
	v_mfma_f32_16x16x32_bf16 v[44:47], v[166:169], v[198:201], v[44:47]
	v_mfma_f32_16x16x32_bf16 v[40:43], v[174:177], v[198:201], v[40:43]
	v_mfma_f32_16x16x32_bf16 v[36:39], v[166:169], v[218:221], v[36:39]
	v_mfma_f32_16x16x32_bf16 v[32:35], v[174:177], v[218:221], v[32:35]
	v_mfma_f32_16x16x32_bf16 v[60:63], v[170:173], v[186:189], v[60:63]
	v_mfma_f32_16x16x32_bf16 v[56:59], v[178:181], v[186:189], v[56:59]
	v_mfma_f32_16x16x32_bf16 v[52:55], v[170:173], v[194:197], v[52:55]
	v_mfma_f32_16x16x32_bf16 v[48:51], v[178:181], v[194:197], v[48:51]
	v_mfma_f32_16x16x32_bf16 v[44:47], v[170:173], v[202:205], v[44:47]
	v_mfma_f32_16x16x32_bf16 v[40:43], v[178:181], v[202:205], v[40:43]
	v_mfma_f32_16x16x32_bf16 v[36:39], v[170:173], v[222:225], v[36:39]
	s_barrier
; #define PG8_STAGE(bufoff, gbase, voff) do { _Pragma("unroll") for (int _i = 0; _i < 2; ++_i) \
;         __builtin_amdgcn_global_load_lds((const unsigned*)((const char*)(gbase) + (voff)[_i]), (PG8_LAS unsigned*)(lds + (bufoff) + ldsw + _i * 8192), 16, 0, 0); } while (0)
; #define PG8_LDA(dst, b, h) do { _Pragma("unroll") for (int m = 0; m < 4; ++m) _Pragma("unroll") for (int k = 0; k < 2; ++k) dst[m][k] = *(const PG8_LAS bf16x8*)(lds + PG8_SA(b, h) + aoff + m * 2048 + k * 1024); } while (0)
; #define PG8_MMA(ai, bj, At, Bt) do { __builtin_amdgcn_s_setprio(1); _Pragma("unroll") for (int m = 0; m < 4; ++m) _Pragma("unroll") for (int n = 0; n < 2; ++n) _Pragma("unroll") for (int k = 0; k < 2; ++k) \
;         acc[ai][bj][m][n] = __builtin_amdgcn_mfma_f32_16x16x32_bf16(Bt[n][k], At[m][k], acc[ai][bj][m][n], 0, 0, 0); __builtin_amdgcn_s_setprio(0); } while (0)
; #define PG8_WAIT_V(n) asm volatile("s_waitcnt vmcnt(" #n ")" ::: "memory")
; #define PG8_WAIT_L(n) asm volatile("s_waitcnt lgkmcnt(" #n ")" ::: "memory")
; #define PG8_BAR __builtin_amdgcn_s_barrier()
; #define PG8_SCHED __builtin_amdgcn_sched_barrier(0)
; template <class Epi, class Sched, bool ALIGN_EPI = false, bool SP2 = false>
; __device__ __forceinline__ void gemm_phase(PG8_LAS unsigned char* lds, const Gemm g, const Sched& S, const Epi& E) {
;     ...
;             PG8_WAIT_V(8); PG8_WAIT_L(0); PG8_BAR; PG8_MMA(0, 0, At, B0); PG8_MMA(0, 1, At, B1); PG8_BAR; PG8_SCHED;
;             PG8_LDA(At, 1, 1); PG8_STAGE(PG8_SB(1, 0), b3, voffB); PG8_STAGE(PG8_SB(1, 1), b3 + hstep, voffB); PG8_STAGE(PG8_SA(1, 0), a3, voffA);
;             PG8_WAIT_V(8); PG8_WAIT_L(0); PG8_BAR; PG8_MMA(1, 0, At, B0); PG8_MMA(1, 1, At, B1); PG8_BAR; PG8_SCHED;
;     ...
;         if constexpr (ALIGN_EPI) { if (wr == 0) PG8_BAR; }
	v_mfma_f32_16x16x32_bf16 v[32:35], v[178:181], v[222:225], v[32:35]
	s_setprio 0
	s_add_i32 s52, s56, s82
	v_lshl_add_u64 v[226:227], v[226:227], 0, s[36:37]
	s_mov_b32 m0, s52
	ds_read_b128 v[182:185], v216 offset:49152
	ds_read_b128 v[186:189], v216 offset:50176
	ds_read_b128 v[190:193], v216 offset:51200
	ds_read_b128 v[194:197], v216 offset:52224
	ds_read_b128 v[198:201], v216 offset:53248
	ds_read_b128 v[202:205], v216 offset:54272
	ds_read_b128 v[218:221], v216 offset:55296
	ds_read_b128 v[222:225], v216 offset:56320
	global_load_lds_dwordx4 v[226:227], off
	s_add_i32 m0, s52, 0x2000
	s_add_u32 s52, s76, 0x200080
	v_lshl_add_u64 v[226:227], v[228:229], 0, s[36:37]
	s_addc_u32 s53, s77, 0
	s_add_i32 s56, s57, s82
	global_load_lds_dwordx4 v[226:227], off
	v_lshl_add_u64 v[226:227], s[52:53], 0, v[138:139]
	s_mov_b32 m0, s56
	s_nop 0
	global_load_lds_dwordx4 v[226:227], off
	v_lshl_add_u64 v[226:227], s[52:53], 0, v[142:143]
	s_add_i32 m0, s56, 0x2000
	s_nop 0
	global_load_lds_dwordx4 v[226:227], off
	v_lshl_add_u64 v[226:227], v[230:231], 0, s[36:37]
	s_mov_b32 m0, s94
	s_nop 0
	global_load_lds_dwordx4 v[226:227], off
	v_lshl_add_u64 v[226:227], v[232:233], 0, s[36:37]
	s_mov_b32 m0, s95
	s_nop 0
	global_load_lds_dwordx4 v[226:227], off
	s_waitcnt vmcnt(8)
	s_waitcnt lgkmcnt(0)
	s_barrier
	s_setprio 1
	s_waitcnt lgkmcnt(0)
	v_mfma_f32_16x16x32_bf16 v[92:95], v[128:131], v[182:185], v[92:95]
	v_mfma_f32_16x16x32_bf16 v[88:91], v[158:161], v[182:185], v[88:91]
	v_mfma_f32_16x16x32_bf16 v[84:87], v[128:131], v[190:193], v[84:87]
	v_mfma_f32_16x16x32_bf16 v[80:83], v[158:161], v[190:193], v[80:83]
	v_mfma_f32_16x16x32_bf16 v[76:79], v[128:131], v[198:201], v[76:79]
	v_mfma_f32_16x16x32_bf16 v[72:75], v[158:161], v[198:201], v[72:75]
	v_mfma_f32_16x16x32_bf16 v[68:71], v[128:131], v[218:221], v[68:71]
	v_mfma_f32_16x16x32_bf16 v[64:67], v[158:161], v[218:221], v[64:67]
	v_mfma_f32_16x16x32_bf16 v[92:95], v[132:135], v[186:189], v[92:95]
	v_mfma_f32_16x16x32_bf16 v[88:91], v[162:165], v[186:189], v[88:91]
	v_mfma_f32_16x16x32_bf16 v[84:87], v[132:135], v[194:197], v[84:87]
	v_mfma_f32_16x16x32_bf16 v[80:83], v[162:165], v[194:197], v[80:83]
	v_mfma_f32_16x16x32_bf16 v[76:79], v[132:135], v[202:205], v[76:79]
	v_mfma_f32_16x16x32_bf16 v[72:75], v[162:165], v[202:205], v[72:75]
	v_mfma_f32_16x16x32_bf16 v[68:71], v[132:135], v[222:225], v[68:71]
	v_mfma_f32_16x16x32_bf16 v[64:67], v[162:165], v[222:225], v[64:67]
	s_setprio 0
	s_setprio 1
	v_mfma_f32_16x16x32_bf16 v[28:31], v[166:169], v[182:185], v[28:31]
	v_mfma_f32_16x16x32_bf16 v[24:27], v[174:177], v[182:185], v[24:27]
	v_mfma_f32_16x16x32_bf16 v[20:23], v[166:169], v[190:193], v[20:23]
	v_mfma_f32_16x16x32_bf16 v[16:19], v[174:177], v[190:193], v[16:19]
	v_mfma_f32_16x16x32_bf16 v[12:15], v[166:169], v[198:201], v[12:15]
	v_mfma_f32_16x16x32_bf16 v[8:11], v[174:177], v[198:201], v[8:11]
	v_mfma_f32_16x16x32_bf16 v[4:7], v[166:169], v[218:221], v[4:7]
	v_mfma_f32_16x16x32_bf16 v[0:3], v[174:177], v[218:221], v[0:3]
	v_mfma_f32_16x16x32_bf16 v[28:31], v[170:173], v[186:189], v[28:31]
	v_mfma_f32_16x16x32_bf16 v[24:27], v[178:181], v[186:189], v[24:27]
	v_mfma_f32_16x16x32_bf16 v[20:23], v[170:173], v[194:197], v[20:23]
	v_mfma_f32_16x16x32_bf16 v[16:19], v[178:181], v[194:197], v[16:19]
	v_mfma_f32_16x16x32_bf16 v[12:15], v[170:173], v[202:205], v[12:15]
	v_mfma_f32_16x16x32_bf16 v[8:11], v[178:181], v[202:205], v[8:11]
	v_mfma_f32_16x16x32_bf16 v[4:7], v[170:173], v[222:225], v[4:7]
	s_barrier
	v_mfma_f32_16x16x32_bf16 v[0:3], v[178:181], v[222:225], v[0:3]
	s_setprio 0
	s_add_i32 vcc_hi, vcc_hi, 2
	s_add_u32 s74, s74, 0x100
	s_addc_u32 s75, s75, 0
	s_add_u32 s93, s93, 0x100
	s_addc_u32 vcc_lo, vcc_lo, 0
	s_cmpk_gt_u32 vcc_hi, 0x7d
	s_cbranch_scc0 .LBB0_624
	s_and_b64 vcc, exec, s[40:41]
	s_cbranch_vccz .LBB0_627
	s_barrier

; #define PG8_STAGE(bufoff, gbase, voff) do { _Pragma("unroll") for (int _i = 0; _i < 2; ++_i) \
;         __builtin_amdgcn_global_load_lds((const unsigned*)((const char*)(gbase) + (voff)[_i]), (PG8_LAS unsigned*)(lds + (bufoff) + ldsw + _i * 8192), 16, 0, 0); } while (0)
; #define PG8_LDA(dst, b, h) do { _Pragma("unroll") for (int m = 0; m < 4; ++m) _Pragma("unroll") for (int k = 0; k < 2; ++k) dst[m][k] = *(const PG8_LAS bf16x8*)(lds + PG8_SA(b, h) + aoff + m * 2048 + k * 1024); } while (0)
; #define PG8_LDB(dst, b, h) do { _Pragma("unroll") for (int n = 0; n < 2; ++n) _Pragma("unroll") for (int k = 0; k < 2; ++k) dst[n][k] = *(const PG8_LAS bf16x8*)(lds + PG8_SB(b, h) + boff + n * 2048 + k * 1024); } while (0)
; #define PG8_MMA(ai, bj, At, Bt) do { __builtin_amdgcn_s_setprio(1); _Pragma("unroll") for (int m = 0; m < 4; ++m) _Pragma("unroll") for (int n = 0; n < 2; ++n) _Pragma("unroll") for (int k = 0; k < 2; ++k) \
;         acc[ai][bj][m][n] = __builtin_amdgcn_mfma_f32_16x16x32_bf16(Bt[n][k], At[m][k], acc[ai][bj][m][n], 0, 0, 0); __builtin_amdgcn_s_setprio(0); } while (0)
; #define PG8_WAIT_V(n) asm volatile("s_waitcnt vmcnt(" #n ")" ::: "memory")
; #define PG8_WAIT_L(n) asm volatile("s_waitcnt lgkmcnt(" #n ")" ::: "memory")
; #define PG8_BAR __builtin_amdgcn_s_barrier()
; #define PG8_SCHED __builtin_amdgcn_sched_barrier(0)
; template <class Epi, class Sched, bool ALIGN_EPI = false, bool SP2 = false>
; __device__ __forceinline__ void gemm_phase(PG8_LAS unsigned char* lds, const Gemm g, const Sched& S, const Epi& E) {
;     ...
;             const char* a1 = cA + (size_t)(t + 1) * kstep;
;             const char* a2 = last ? nA : cA + (size_t)(t + 2) * kstep; const char* b2 = last ? nB : cB + (size_t)(t + 2) * kstep;
;             const char* a3 = a2 + kstep; const char* b3 = b2 + kstep;
;             if constexpr (SP2) {
;             PG8_LDB(B0, 0, 0); PG8_LDB(B1, 0, 1); PG8_SCHED; PG8_LDA(At, 0, 0); PG8_STAGE(PG8_SA(1, 1), a1 + hstep, voffA);
;             PG8_WAIT_V(8); PG8_WAIT_L(0); PG8_BAR; PG8_MMA(0, 0, At, B0); PG8_MMA(0, 1, At, B1); PG8_BAR; PG8_SCHED;
;             PG8_LDA(At, 0, 1); PG8_STAGE(PG8_SB(0, 0), b2, voffB); PG8_STAGE(PG8_SB(0, 1), b2 + hstep, voffB); PG8_STAGE(PG8_SA(0, 0), a2, voffA);
;             PG8_WAIT_V(8); PG8_WAIT_L(0); PG8_BAR; PG8_MMA(1, 0, At, B0); PG8_MMA(1, 1, At, B1); PG8_BAR; PG8_SCHED;
.LBB0_660:
	ds_read_b128 v[166:169], v145
	ds_read_b128 v[170:173], v145 offset:1024
	ds_read_b128 v[174:177], v145 offset:2048
	ds_read_b128 v[178:181], v145 offset:3072
	ds_read_b128 v[182:185], v149
	ds_read_b128 v[186:189], v149 offset:1024
	ds_read_b128 v[190:193], v149 offset:2048
	ds_read_b128 v[194:197], v149 offset:3072
	s_add_u32 s52, s72, 0xffe00080
	s_addc_u32 s53, s73, -1
	s_cmp_eq_u32 s49, 28
	s_cselect_b32 s77, s51, s53
	s_cselect_b32 s76, s50, s52
	s_cselect_b32 s75, s55, s41
	s_cselect_b32 s74, s54, s37
	s_mov_b32 m0, s82
	v_lshl_add_u64 v[230:231], s[72:73], 0, v[160:161]
	ds_read_b128 v[198:201], v164
	ds_read_b128 v[202:205], v164 offset:1024
	ds_read_b128 v[206:209], v164 offset:2048
	ds_read_b128 v[210:213], v164 offset:3072
	ds_read_b128 v[214:217], v164 offset:4096
	ds_read_b128 v[218:221], v164 offset:5120
	ds_read_b128 v[222:225], v164 offset:6144
	ds_read_b128 v[226:229], v164 offset:7168
	global_load_lds_dwordx4 v[230:231], off
	v_lshl_add_u64 v[230:231], s[72:73], 0, v[162:163]
	s_mov_b32 m0, s83
	s_nop 0
	global_load_lds_dwordx4 v[230:231], off
	s_waitcnt vmcnt(8)
	s_waitcnt lgkmcnt(0)
	s_barrier
	s_setprio 1
	s_waitcnt lgkmcnt(0)
	v_mfma_f32_16x16x32_bf16 v[124:127], v[166:169], v[198:201], v[124:127]
	v_mfma_f32_16x16x32_bf16 v[120:123], v[174:177], v[198:201], v[120:123]
	v_mfma_f32_16x16x32_bf16 v[116:119], v[166:169], v[206:209], v[116:119]
	v_mfma_f32_16x16x32_bf16 v[108:111], v[174:177], v[206:209], v[108:111]
	v_mfma_f32_16x16x32_bf16 v[100:103], v[166:169], v[214:217], v[100:103]
	v_mfma_f32_16x16x32_bf16 v[92:95], v[174:177], v[214:217], v[92:95]
	v_mfma_f32_16x16x32_bf16 v[84:87], v[166:169], v[222:225], v[84:87]
	v_mfma_f32_16x16x32_bf16 v[76:79], v[174:177], v[222:225], v[76:79]
	v_mfma_f32_16x16x32_bf16 v[124:127], v[170:173], v[202:205], v[124:127]
	v_mfma_f32_16x16x32_bf16 v[120:123], v[178:181], v[202:205], v[120:123]
	v_mfma_f32_16x16x32_bf16 v[116:119], v[170:173], v[210:213], v[116:119]
	v_mfma_f32_16x16x32_bf16 v[108:111], v[178:181], v[210:213], v[108:111]
	v_mfma_f32_16x16x32_bf16 v[100:103], v[170:173], v[218:221], v[100:103]
	v_mfma_f32_16x16x32_bf16 v[92:95], v[178:181], v[218:221], v[92:95]
	v_mfma_f32_16x16x32_bf16 v[84:87], v[170:173], v[226:229], v[84:87]
	v_mfma_f32_16x16x32_bf16 v[76:79], v[178:181], v[226:229], v[76:79]
	s_setprio 0
	s_setprio 1
	v_mfma_f32_16x16x32_bf16 v[112:115], v[182:185], v[198:201], v[112:115]
	v_mfma_f32_16x16x32_bf16 v[104:107], v[190:193], v[198:201], v[104:107]
	v_mfma_f32_16x16x32_bf16 v[96:99], v[182:185], v[206:209], v[96:99]
	v_mfma_f32_16x16x32_bf16 v[88:91], v[190:193], v[206:209], v[88:91]
	v_mfma_f32_16x16x32_bf16 v[80:83], v[182:185], v[214:217], v[80:83]
	v_mfma_f32_16x16x32_bf16 v[72:75], v[190:193], v[214:217], v[72:75]
	v_mfma_f32_16x16x32_bf16 v[68:71], v[182:185], v[222:225], v[68:71]
	v_mfma_f32_16x16x32_bf16 v[64:67], v[190:193], v[222:225], v[64:67]
	v_mfma_f32_16x16x32_bf16 v[112:115], v[186:189], v[202:205], v[112:115]
	v_mfma_f32_16x16x32_bf16 v[104:107], v[194:197], v[202:205], v[104:107]
	v_mfma_f32_16x16x32_bf16 v[96:99], v[186:189], v[210:213], v[96:99]
	v_mfma_f32_16x16x32_bf16 v[88:91], v[194:197], v[210:213], v[88:91]
	v_mfma_f32_16x16x32_bf16 v[80:83], v[186:189], v[218:221], v[80:83]
	v_mfma_f32_16x16x32_bf16 v[72:75], v[194:197], v[218:221], v[72:75]
	v_mfma_f32_16x16x32_bf16 v[68:71], v[186:189], v[226:229], v[68:71]
	s_barrier
	v_mfma_f32_16x16x32_bf16 v[64:67], v[194:197], v[226:229], v[64:67]
	s_setprio 0
	s_mov_b32 m0, s84
	v_lshl_add_u64 v[230:231], s[74:75], 0, v[138:139]
	s_add_u32 s52, s74, 0x200000
	ds_read_b128 v[198:201], v164 offset:16384
	ds_read_b128 v[202:205], v164 offset:17408
	ds_read_b128 v[206:209], v164 offset:18432
	ds_read_b128 v[210:213], v164 offset:19456
	ds_read_b128 v[214:217], v164 offset:20480
	ds_read_b128 v[218:221], v164 offset:21504
	ds_read_b128 v[222:225], v164 offset:22528
	ds_read_b128 v[226:229], v164 offset:23552
	global_load_lds_dwordx4 v[230:231], off
	v_lshl_add_u64 v[232:233], s[74:75], 0, v[142:143]
	s_mov_b32 m0, s85
	s_addc_u32 s53, s75, 0
	global_load_lds_dwordx4 v[232:233], off
	v_lshl_add_u64 v[234:235], s[52:53], 0, v[138:139]
	s_mov_b32 m0, s86
	v_lshl_add_u64 v[236:237], s[76:77], 0, v[140:141]
	global_load_lds_dwordx4 v[234:235], off
	v_lshl_add_u64 v[234:235], s[52:53], 0, v[142:143]
	s_mov_b32 m0, s87
	s_nop 0
	global_load_lds_dwordx4 v[234:235], off
	v_lshl_add_u64 v[234:235], s[76:77], 0, v[136:137]
	s_mov_b32 m0, s28
	s_nop 0
	global_load_lds_dwordx4 v[234:235], off
	s_mov_b32 m0, s29
	s_nop 0
	global_load_lds_dwordx4 v[236:237], off
	s_waitcnt vmcnt(8)
	s_waitcnt lgkmcnt(0)
	s_barrier
; #define PG8_STAGE(bufoff, gbase, voff) do { _Pragma("unroll") for (int _i = 0; _i < 2; ++_i) \
;         __builtin_amdgcn_global_load_lds((const unsigned*)((const char*)(gbase) + (voff)[_i]), (PG8_LAS unsigned*)(lds + (bufoff) + ldsw + _i * 8192), 16, 0, 0); } while (0)
; #define PG8_LDA(dst, b, h) do { _Pragma("unroll") for (int m = 0; m < 4; ++m) _Pragma("unroll") for (int k = 0; k < 2; ++k) dst[m][k] = *(const PG8_LAS bf16x8*)(lds + PG8_SA(b, h) + aoff + m * 2048 + k * 1024); } while (0)
; #define PG8_LDB(dst, b, h) do { _Pragma("unroll") for (int n = 0; n < 2; ++n) _Pragma("unroll") for (int k = 0; k < 2; ++k) dst[n][k] = *(const PG8_LAS bf16x8*)(lds + PG8_SB(b, h) + boff + n * 2048 + k * 1024); } while (0)
; #define PG8_MMA(ai, bj, At, Bt) do { __builtin_amdgcn_s_setprio(1); _Pragma("unroll") for (int m = 0; m < 4; ++m) _Pragma("unroll") for (int n = 0; n < 2; ++n) _Pragma("unroll") for (int k = 0; k < 2; ++k) \
;         acc[ai][bj][m][n] = __builtin_amdgcn_mfma_f32_16x16x32_bf16(Bt[n][k], At[m][k], acc[ai][bj][m][n], 0, 0, 0); __builtin_amdgcn_s_setprio(0); } while (0)
; #define PG8_WAIT_V(n) asm volatile("s_waitcnt vmcnt(" #n ")" ::: "memory")
; #define PG8_WAIT_L(n) asm volatile("s_waitcnt lgkmcnt(" #n ")" ::: "memory")
; #define PG8_BAR __builtin_amdgcn_s_barrier()
; #define PG8_SCHED __builtin_amdgcn_sched_barrier(0)
; template <class Epi, class Sched, bool ALIGN_EPI = false, bool SP2 = false>
; __device__ __forceinline__ void gemm_phase(PG8_LAS unsigned char* lds, const Gemm g, const Sched& S, const Epi& E) {
;     ...
;             PG8_WAIT_V(8); PG8_WAIT_L(0); PG8_BAR; PG8_MMA(1, 0, At, B0); PG8_MMA(1, 1, At, B1); PG8_BAR; PG8_SCHED;
;             PG8_LDB(B0, 1, 0); PG8_LDB(B1, 1, 1); PG8_SCHED; PG8_LDA(At, 1, 0); PG8_STAGE(PG8_SA(0, 1), a2 + hstep, voffA);
;             PG8_WAIT_V(8); PG8_WAIT_L(0); PG8_BAR; PG8_MMA(0, 0, At, B0); PG8_MMA(0, 1, At, B1); PG8_BAR; PG8_SCHED;
	s_setprio 1
	s_waitcnt lgkmcnt(0)
	v_mfma_f32_16x16x32_bf16 v[60:63], v[166:169], v[198:201], v[60:63]
	v_mfma_f32_16x16x32_bf16 v[56:59], v[174:177], v[198:201], v[56:59]
	v_mfma_f32_16x16x32_bf16 v[52:55], v[166:169], v[206:209], v[52:55]
	v_mfma_f32_16x16x32_bf16 v[44:47], v[174:177], v[206:209], v[44:47]
	v_mfma_f32_16x16x32_bf16 v[36:39], v[166:169], v[214:217], v[36:39]
	v_mfma_f32_16x16x32_bf16 v[28:31], v[174:177], v[214:217], v[28:31]
	v_mfma_f32_16x16x32_bf16 v[20:23], v[166:169], v[222:225], v[20:23]
	v_mfma_f32_16x16x32_bf16 v[12:15], v[174:177], v[222:225], v[12:15]
	v_mfma_f32_16x16x32_bf16 v[60:63], v[170:173], v[202:205], v[60:63]
	v_mfma_f32_16x16x32_bf16 v[56:59], v[178:181], v[202:205], v[56:59]
	v_mfma_f32_16x16x32_bf16 v[52:55], v[170:173], v[210:213], v[52:55]
	v_mfma_f32_16x16x32_bf16 v[44:47], v[178:181], v[210:213], v[44:47]
	v_mfma_f32_16x16x32_bf16 v[36:39], v[170:173], v[218:221], v[36:39]
	v_mfma_f32_16x16x32_bf16 v[28:31], v[178:181], v[218:221], v[28:31]
	v_mfma_f32_16x16x32_bf16 v[20:23], v[170:173], v[226:229], v[20:23]
	v_mfma_f32_16x16x32_bf16 v[12:15], v[178:181], v[226:229], v[12:15]
	s_setprio 0
	s_setprio 1
	v_mfma_f32_16x16x32_bf16 v[48:51], v[182:185], v[198:201], v[48:51]
	v_mfma_f32_16x16x32_bf16 v[40:43], v[190:193], v[198:201], v[40:43]
	v_mfma_f32_16x16x32_bf16 v[32:35], v[182:185], v[206:209], v[32:35]
	v_mfma_f32_16x16x32_bf16 v[24:27], v[190:193], v[206:209], v[24:27]
	v_mfma_f32_16x16x32_bf16 v[16:19], v[182:185], v[214:217], v[16:19]
	v_mfma_f32_16x16x32_bf16 v[8:11], v[190:193], v[214:217], v[8:11]
	v_mfma_f32_16x16x32_bf16 v[4:7], v[182:185], v[222:225], v[4:7]
	v_mfma_f32_16x16x32_bf16 v[0:3], v[190:193], v[222:225], v[0:3]
	v_mfma_f32_16x16x32_bf16 v[48:51], v[186:189], v[202:205], v[48:51]
	v_mfma_f32_16x16x32_bf16 v[40:43], v[194:197], v[202:205], v[40:43]
	v_mfma_f32_16x16x32_bf16 v[32:35], v[186:189], v[210:213], v[32:35]
	v_mfma_f32_16x16x32_bf16 v[24:27], v[194:197], v[210:213], v[24:27]
	v_mfma_f32_16x16x32_bf16 v[16:19], v[186:189], v[218:221], v[16:19]
	v_mfma_f32_16x16x32_bf16 v[8:11], v[194:197], v[218:221], v[8:11]
	v_mfma_f32_16x16x32_bf16 v[4:7], v[186:189], v[226:229], v[4:7]
	s_barrier
	v_mfma_f32_16x16x32_bf16 v[0:3], v[194:197], v[226:229], v[0:3]
	s_setprio 0
	ds_read_b128 v[166:169], v148
	ds_read_b128 v[170:173], v148 offset:1024
	ds_read_b128 v[174:177], v148 offset:2048
	ds_read_b128 v[178:181], v148 offset:3072
	ds_read_b128 v[182:185], v165
	ds_read_b128 v[186:189], v165 offset:1024
	ds_read_b128 v[190:193], v165 offset:2048
	ds_read_b128 v[194:197], v165 offset:3072
	s_add_u32 s52, s76, 0x200000
	s_addc_u32 s53, s77, 0
	s_mov_b32 m0, s33
	v_lshl_add_u64 v[238:239], s[52:53], 0, v[136:137]
	ds_read_b128 v[198:201], v164 offset:32768
	ds_read_b128 v[202:205], v164 offset:33792
	ds_read_b128 v[206:209], v164 offset:34816
	ds_read_b128 v[210:213], v164 offset:35840
	ds_read_b128 v[214:217], v164 offset:36864
	ds_read_b128 v[218:221], v164 offset:37888
	ds_read_b128 v[222:225], v164 offset:38912
	ds_read_b128 v[226:229], v164 offset:39936
	global_load_lds_dwordx4 v[238:239], off
	v_lshl_add_u64 v[238:239], s[52:53], 0, v[140:141]
	s_mov_b32 m0, s38
	s_nop 0
	global_load_lds_dwordx4 v[238:239], off
	s_waitcnt vmcnt(8)
	s_waitcnt lgkmcnt(0)
	s_barrier
	s_setprio 1
	s_waitcnt lgkmcnt(0)
	v_mfma_f32_16x16x32_bf16 v[124:127], v[166:169], v[198:201], v[124:127]
	v_mfma_f32_16x16x32_bf16 v[120:123], v[174:177], v[198:201], v[120:123]
	v_mfma_f32_16x16x32_bf16 v[116:119], v[166:169], v[206:209], v[116:119]
	v_mfma_f32_16x16x32_bf16 v[108:111], v[174:177], v[206:209], v[108:111]
	v_mfma_f32_16x16x32_bf16 v[100:103], v[166:169], v[214:217], v[100:103]
	v_mfma_f32_16x16x32_bf16 v[92:95], v[174:177], v[214:217], v[92:95]
	v_mfma_f32_16x16x32_bf16 v[84:87], v[166:169], v[222:225], v[84:87]
	v_mfma_f32_16x16x32_bf16 v[76:79], v[174:177], v[222:225], v[76:79]
	v_mfma_f32_16x16x32_bf16 v[124:127], v[170:173], v[202:205], v[124:127]
	v_mfma_f32_16x16x32_bf16 v[120:123], v[178:181], v[202:205], v[120:123]
	v_mfma_f32_16x16x32_bf16 v[116:119], v[170:173], v[210:213], v[116:119]
	v_mfma_f32_16x16x32_bf16 v[108:111], v[178:181], v[210:213], v[108:111]
	v_mfma_f32_16x16x32_bf16 v[100:103], v[170:173], v[218:221], v[100:103]
	v_mfma_f32_16x16x32_bf16 v[92:95], v[178:181], v[218:221], v[92:95]
	v_mfma_f32_16x16x32_bf16 v[84:87], v[170:173], v[226:229], v[84:87]
	v_mfma_f32_16x16x32_bf16 v[76:79], v[178:181], v[226:229], v[76:79]
	s_setprio 0
	s_setprio 1
	v_mfma_f32_16x16x32_bf16 v[112:115], v[182:185], v[198:201], v[112:115]
	v_mfma_f32_16x16x32_bf16 v[104:107], v[190:193], v[198:201], v[104:107]
	v_mfma_f32_16x16x32_bf16 v[96:99], v[182:185], v[206:209], v[96:99]
	v_mfma_f32_16x16x32_bf16 v[88:91], v[190:193], v[206:209], v[88:91]
	v_mfma_f32_16x16x32_bf16 v[80:83], v[182:185], v[214:217], v[80:83]
	v_mfma_f32_16x16x32_bf16 v[72:75], v[190:193], v[214:217], v[72:75]
	v_mfma_f32_16x16x32_bf16 v[68:71], v[182:185], v[222:225], v[68:71]
	v_mfma_f32_16x16x32_bf16 v[64:67], v[190:193], v[222:225], v[64:67]
	v_mfma_f32_16x16x32_bf16 v[112:115], v[186:189], v[202:205], v[112:115]
	v_mfma_f32_16x16x32_bf16 v[104:107], v[194:197], v[202:205], v[104:107]
	v_mfma_f32_16x16x32_bf16 v[96:99], v[186:189], v[210:213], v[96:99]
	v_mfma_f32_16x16x32_bf16 v[88:91], v[194:197], v[210:213], v[88:91]
	v_mfma_f32_16x16x32_bf16 v[80:83], v[186:189], v[218:221], v[80:83]
	v_mfma_f32_16x16x32_bf16 v[72:75], v[194:197], v[218:221], v[72:75]
	v_mfma_f32_16x16x32_bf16 v[68:71], v[186:189], v[226:229], v[68:71]
	s_barrier
; #define PG8_STAGE(bufoff, gbase, voff) do { _Pragma("unroll") for (int _i = 0; _i < 2; ++_i) \
;         __builtin_amdgcn_global_load_lds((const unsigned*)((const char*)(gbase) + (voff)[_i]), (PG8_LAS unsigned*)(lds + (bufoff) + ldsw + _i * 8192), 16, 0, 0); } while (0)
; #define PG8_LDA(dst, b, h) do { _Pragma("unroll") for (int m = 0; m < 4; ++m) _Pragma("unroll") for (int k = 0; k < 2; ++k) dst[m][k] = *(const PG8_LAS bf16x8*)(lds + PG8_SA(b, h) + aoff + m * 2048 + k * 1024); } while (0)
; #define PG8_MMA(ai, bj, At, Bt) do { __builtin_amdgcn_s_setprio(1); _Pragma("unroll") for (int m = 0; m < 4; ++m) _Pragma("unroll") for (int n = 0; n < 2; ++n) _Pragma("unroll") for (int k = 0; k < 2; ++k) \
;         acc[ai][bj][m][n] = __builtin_amdgcn_mfma_f32_16x16x32_bf16(Bt[n][k], At[m][k], acc[ai][bj][m][n], 0, 0, 0); __builtin_amdgcn_s_setprio(0); } while (0)
; #define PG8_WAIT_V(n) asm volatile("s_waitcnt vmcnt(" #n ")" ::: "memory")
; #define PG8_WAIT_L(n) asm volatile("s_waitcnt lgkmcnt(" #n ")" ::: "memory")
; #define PG8_BAR __builtin_amdgcn_s_barrier()
; #define PG8_SCHED __builtin_amdgcn_sched_barrier(0)
; template <class Epi, class Sched, bool ALIGN_EPI = false, bool SP2 = false>
; __device__ __forceinline__ void gemm_phase(PG8_LAS unsigned char* lds, const Gemm g, const Sched& S, const Epi& E) {
;     ...
;             PG8_WAIT_V(8); PG8_WAIT_L(0); PG8_BAR; PG8_MMA(0, 0, At, B0); PG8_MMA(0, 1, At, B1); PG8_BAR; PG8_SCHED;
;             PG8_LDA(At, 1, 1); PG8_STAGE(PG8_SB(1, 0), b3, voffB); PG8_STAGE(PG8_SB(1, 1), b3 + hstep, voffB); PG8_STAGE(PG8_SA(1, 0), a3, voffA);
;             PG8_WAIT_V(8); PG8_WAIT_L(0); PG8_BAR; PG8_MMA(1, 0, At, B0); PG8_MMA(1, 1, At, B1); PG8_BAR; PG8_SCHED;
;     ...
;         if constexpr (ALIGN_EPI) { if (wr == 0) PG8_BAR; }
	v_mfma_f32_16x16x32_bf16 v[64:67], v[194:197], v[226:229], v[64:67]
	s_setprio 0
	s_mov_b32 m0, s89
	v_lshl_add_u64 v[230:231], v[230:231], 0, s[12:13]
	ds_read_b128 v[198:201], v164 offset:49152
	ds_read_b128 v[202:205], v164 offset:50176
	ds_read_b128 v[206:209], v164 offset:51200
	ds_read_b128 v[210:213], v164 offset:52224
	ds_read_b128 v[214:217], v164 offset:53248
	ds_read_b128 v[218:221], v164 offset:54272
	ds_read_b128 v[222:225], v164 offset:55296
	ds_read_b128 v[226:229], v164 offset:56320
	global_load_lds_dwordx4 v[230:231], off
	s_add_i32 m0, s89, 0x2000
	s_add_u32 s52, s74, 0x200080
	v_lshl_add_u64 v[230:231], v[232:233], 0, s[12:13]
	s_addc_u32 s53, s75, 0
	s_add_i32 s56, s88, s3
	global_load_lds_dwordx4 v[230:231], off
	v_lshl_add_u64 v[230:231], s[52:53], 0, v[138:139]
	s_mov_b32 m0, s56
	s_nop 0
	global_load_lds_dwordx4 v[230:231], off
	v_lshl_add_u64 v[230:231], s[52:53], 0, v[142:143]
	s_add_i32 m0, s56, 0x2000
	s_nop 0
	global_load_lds_dwordx4 v[230:231], off
	v_lshl_add_u64 v[230:231], v[234:235], 0, s[12:13]
	s_mov_b32 m0, s71
	s_nop 0
	global_load_lds_dwordx4 v[230:231], off
	v_lshl_add_u64 v[230:231], v[236:237], 0, s[12:13]
	s_mov_b32 m0, s78
	s_nop 0
	global_load_lds_dwordx4 v[230:231], off
	s_waitcnt vmcnt(8)
	s_waitcnt lgkmcnt(0)
	s_barrier
	s_setprio 1
	s_waitcnt lgkmcnt(0)
	v_mfma_f32_16x16x32_bf16 v[60:63], v[166:169], v[198:201], v[60:63]
	v_mfma_f32_16x16x32_bf16 v[56:59], v[174:177], v[198:201], v[56:59]
	v_mfma_f32_16x16x32_bf16 v[52:55], v[166:169], v[206:209], v[52:55]
	v_mfma_f32_16x16x32_bf16 v[44:47], v[174:177], v[206:209], v[44:47]
	v_mfma_f32_16x16x32_bf16 v[36:39], v[166:169], v[214:217], v[36:39]
	v_mfma_f32_16x16x32_bf16 v[28:31], v[174:177], v[214:217], v[28:31]
	v_mfma_f32_16x16x32_bf16 v[20:23], v[166:169], v[222:225], v[20:23]
	v_mfma_f32_16x16x32_bf16 v[12:15], v[174:177], v[222:225], v[12:15]
	v_mfma_f32_16x16x32_bf16 v[60:63], v[170:173], v[202:205], v[60:63]
	v_mfma_f32_16x16x32_bf16 v[56:59], v[178:181], v[202:205], v[56:59]
	v_mfma_f32_16x16x32_bf16 v[52:55], v[170:173], v[210:213], v[52:55]
	v_mfma_f32_16x16x32_bf16 v[44:47], v[178:181], v[210:213], v[44:47]
	v_mfma_f32_16x16x32_bf16 v[36:39], v[170:173], v[218:221], v[36:39]
	v_mfma_f32_16x16x32_bf16 v[28:31], v[178:181], v[218:221], v[28:31]
	v_mfma_f32_16x16x32_bf16 v[20:23], v[170:173], v[226:229], v[20:23]
	v_mfma_f32_16x16x32_bf16 v[12:15], v[178:181], v[226:229], v[12:15]
	s_setprio 0
	s_setprio 1
	v_mfma_f32_16x16x32_bf16 v[48:51], v[182:185], v[198:201], v[48:51]
	v_mfma_f32_16x16x32_bf16 v[40:43], v[190:193], v[198:201], v[40:43]
	v_mfma_f32_16x16x32_bf16 v[32:35], v[182:185], v[206:209], v[32:35]
	v_mfma_f32_16x16x32_bf16 v[24:27], v[190:193], v[206:209], v[24:27]
	v_mfma_f32_16x16x32_bf16 v[16:19], v[182:185], v[214:217], v[16:19]
	v_mfma_f32_16x16x32_bf16 v[8:11], v[190:193], v[214:217], v[8:11]
	v_mfma_f32_16x16x32_bf16 v[4:7], v[182:185], v[222:225], v[4:7]
	v_mfma_f32_16x16x32_bf16 v[0:3], v[190:193], v[222:225], v[0:3]
	v_mfma_f32_16x16x32_bf16 v[48:51], v[186:189], v[202:205], v[48:51]
	v_mfma_f32_16x16x32_bf16 v[40:43], v[194:197], v[202:205], v[40:43]
	v_mfma_f32_16x16x32_bf16 v[32:35], v[186:189], v[210:213], v[32:35]
	v_mfma_f32_16x16x32_bf16 v[24:27], v[194:197], v[210:213], v[24:27]
	v_mfma_f32_16x16x32_bf16 v[16:19], v[186:189], v[218:221], v[16:19]
	v_mfma_f32_16x16x32_bf16 v[8:11], v[194:197], v[218:221], v[8:11]
	v_mfma_f32_16x16x32_bf16 v[4:7], v[186:189], v[226:229], v[4:7]
	s_barrier
	v_mfma_f32_16x16x32_bf16 v[0:3], v[194:197], v[226:229], v[0:3]
	s_setprio 0
	s_add_i32 s49, s49, 2
	s_add_u32 s72, s72, 0x100
	s_addc_u32 s73, s73, 0
	s_add_u32 s37, s37, 0x100
	s_addc_u32 s41, s41, 0
	s_cmp_gt_u32 s49, 29
	s_cbranch_scc0 .LBB0_660
	s_and_b64 vcc, exec, s[14:15]
	s_cbranch_vccz .LBB0_663
	s_barrier

; #define PG8_STAGE(bufoff, gbase, voff) do { _Pragma("unroll") for (int _i = 0; _i < 2; ++_i) \
;         __builtin_amdgcn_global_load_lds((const unsigned*)((const char*)(gbase) + (voff)[_i]), (PG8_LAS unsigned*)(lds + (bufoff) + ldsw + _i * 8192), 16, 0, 0); } while (0)
; #define PG8_LDA(dst, b, h) do { _Pragma("unroll") for (int m = 0; m < 4; ++m) _Pragma("unroll") for (int k = 0; k < 2; ++k) dst[m][k] = *(const PG8_LAS bf16x8*)(lds + PG8_SA(b, h) + aoff + m * 2048 + k * 1024); } while (0)
; #define PG8_LDB(dst, b, h) do { _Pragma("unroll") for (int n = 0; n < 2; ++n) _Pragma("unroll") for (int k = 0; k < 2; ++k) dst[n][k] = *(const PG8_LAS bf16x8*)(lds + PG8_SB(b, h) + boff + n * 2048 + k * 1024); } while (0)
; #define PG8_MMA(ai, bj, At, Bt) do { __builtin_amdgcn_s_setprio(1); _Pragma("unroll") for (int m = 0; m < 4; ++m) _Pragma("unroll") for (int n = 0; n < 2; ++n) _Pragma("unroll") for (int k = 0; k < 2; ++k) \
;         acc[ai][bj][m][n] = __builtin_amdgcn_mfma_f32_16x16x32_bf16(Bt[n][k], At[m][k], acc[ai][bj][m][n], 0, 0, 0); __builtin_amdgcn_s_setprio(0); } while (0)
; #define PG8_WAIT_V(n) asm volatile("s_waitcnt vmcnt(" #n ")" ::: "memory")
; #define PG8_WAIT_L(n) asm volatile("s_waitcnt lgkmcnt(" #n ")" ::: "memory")
; #define PG8_BAR __builtin_amdgcn_s_barrier()
; #define PG8_SCHED __builtin_amdgcn_sched_barrier(0)
; template <class Epi, class Sched, bool ALIGN_EPI = false, bool SP2 = false>
; __device__ __forceinline__ void gemm_phase(PG8_LAS unsigned char* lds, const Gemm g, const Sched& S, const Epi& E) {
;     ...
;             const char* a1 = cA + (size_t)(t + 1) * kstep;
;             const char* a2 = last ? nA : cA + (size_t)(t + 2) * kstep; const char* b2 = last ? nB : cB + (size_t)(t + 2) * kstep;
;             const char* a3 = a2 + kstep; const char* b3 = b2 + kstep;
;             if constexpr (SP2) {
;             PG8_LDB(B0, 0, 0); PG8_LDB(B1, 0, 1); PG8_SCHED; PG8_LDA(At, 0, 0); PG8_STAGE(PG8_SA(1, 1), a1 + hstep, voffA);
;             PG8_WAIT_V(8); PG8_WAIT_L(0); PG8_BAR; PG8_MMA(0, 0, At, B0); PG8_MMA(0, 1, At, B1); PG8_BAR; PG8_SCHED;
;             PG8_LDA(At, 0, 1); PG8_STAGE(PG8_SB(0, 0), b2, voffB); PG8_STAGE(PG8_SB(0, 1), b2 + hstep, voffB); PG8_STAGE(PG8_SA(0, 0), a2, voffA);
;             PG8_WAIT_V(8); PG8_WAIT_L(0); PG8_BAR; PG8_MMA(1, 0, At, B0); PG8_MMA(1, 1, At, B1); PG8_BAR; PG8_SCHED;
.LBB0_809:
	ds_read_b128 v[128:131], v180
	ds_read_b128 v[132:135], v180 offset:1024
	ds_read_b128 v[136:139], v180 offset:2048
	ds_read_b128 v[140:143], v180 offset:3072
	ds_read_b128 v[160:163], v181
	ds_read_b128 v[164:167], v181 offset:1024
	ds_read_b128 v[184:187], v181 offset:2048
	ds_read_b128 v[188:191], v181 offset:3072
	s_add_u32 s52, s72, 0xfff80080
	s_addc_u32 s53, s73, -1
	s_cmp_eq_u32 s92, 28
	s_cselect_b32 s77, s5, s53
	s_cselect_b32 s76, s49, s52
	s_cselect_b32 s75, s45, s91
	s_cselect_b32 s74, s89, s90
	v_lshl_add_u64 v[168:169], s[72:73], 0, v[154:155]
	s_add_i32 m0, s71, 0xc000
	ds_read_b128 v[192:195], v182
	ds_read_b128 v[196:199], v182 offset:1024
	ds_read_b128 v[200:203], v182 offset:2048
	ds_read_b128 v[204:207], v182 offset:3072
	ds_read_b128 v[208:211], v182 offset:4096
	ds_read_b128 v[212:215], v182 offset:5120
	ds_read_b128 v[216:219], v182 offset:6144
	ds_read_b128 v[220:223], v182 offset:7168
	global_load_lds_dwordx4 v[168:169], off
	v_lshl_add_u64 v[168:169], s[72:73], 0, v[156:157]
	s_add_i32 m0, s71, 0xe000
	s_nop 0
	global_load_lds_dwordx4 v[168:169], off
	s_waitcnt vmcnt(8)
	s_waitcnt lgkmcnt(0)
	s_barrier
	s_setprio 1
	s_waitcnt lgkmcnt(0)
	v_mfma_f32_16x16x32_bf16 v[124:127], v[128:131], v[192:195], v[124:127]
	v_mfma_f32_16x16x32_bf16 v[120:123], v[136:139], v[192:195], v[120:123]
	v_mfma_f32_16x16x32_bf16 v[108:111], v[128:131], v[200:203], v[108:111]
	v_mfma_f32_16x16x32_bf16 v[104:107], v[136:139], v[200:203], v[104:107]
	v_mfma_f32_16x16x32_bf16 v[92:95], v[128:131], v[208:211], v[92:95]
	v_mfma_f32_16x16x32_bf16 v[88:91], v[136:139], v[208:211], v[88:91]
	v_mfma_f32_16x16x32_bf16 v[76:79], v[128:131], v[216:219], v[76:79]
	v_mfma_f32_16x16x32_bf16 v[72:75], v[136:139], v[216:219], v[72:75]
	v_mfma_f32_16x16x32_bf16 v[124:127], v[132:135], v[196:199], v[124:127]
	v_mfma_f32_16x16x32_bf16 v[120:123], v[140:143], v[196:199], v[120:123]
	v_mfma_f32_16x16x32_bf16 v[108:111], v[132:135], v[204:207], v[108:111]
	v_mfma_f32_16x16x32_bf16 v[104:107], v[140:143], v[204:207], v[104:107]
	v_mfma_f32_16x16x32_bf16 v[92:95], v[132:135], v[212:215], v[92:95]
	v_mfma_f32_16x16x32_bf16 v[88:91], v[140:143], v[212:215], v[88:91]
	v_mfma_f32_16x16x32_bf16 v[76:79], v[132:135], v[220:223], v[76:79]
	v_mfma_f32_16x16x32_bf16 v[72:75], v[140:143], v[220:223], v[72:75]
	s_setprio 0
	s_setprio 1
	v_mfma_f32_16x16x32_bf16 v[116:119], v[160:163], v[192:195], v[116:119]
	v_mfma_f32_16x16x32_bf16 v[112:115], v[184:187], v[192:195], v[112:115]
	v_mfma_f32_16x16x32_bf16 v[100:103], v[160:163], v[200:203], v[100:103]
	v_mfma_f32_16x16x32_bf16 v[96:99], v[184:187], v[200:203], v[96:99]
	v_mfma_f32_16x16x32_bf16 v[84:87], v[160:163], v[208:211], v[84:87]
	v_mfma_f32_16x16x32_bf16 v[80:83], v[184:187], v[208:211], v[80:83]
	v_mfma_f32_16x16x32_bf16 v[68:71], v[160:163], v[216:219], v[68:71]
	v_mfma_f32_16x16x32_bf16 v[64:67], v[184:187], v[216:219], v[64:67]
	v_mfma_f32_16x16x32_bf16 v[116:119], v[164:167], v[196:199], v[116:119]
	v_mfma_f32_16x16x32_bf16 v[112:115], v[188:191], v[196:199], v[112:115]
	v_mfma_f32_16x16x32_bf16 v[100:103], v[164:167], v[204:207], v[100:103]
	v_mfma_f32_16x16x32_bf16 v[96:99], v[188:191], v[204:207], v[96:99]
	v_mfma_f32_16x16x32_bf16 v[84:87], v[164:167], v[212:215], v[84:87]
	v_mfma_f32_16x16x32_bf16 v[80:83], v[188:191], v[212:215], v[80:83]
	v_mfma_f32_16x16x32_bf16 v[68:71], v[164:167], v[220:223], v[68:71]
	s_barrier
	v_mfma_f32_16x16x32_bf16 v[64:67], v[188:191], v[220:223], v[64:67]
	s_setprio 0
	s_add_i32 s52, s83, s78
	v_lshl_add_u64 v[168:169], s[74:75], 0, v[148:149]
	s_mov_b32 m0, s52
	ds_read_b128 v[192:195], v182 offset:16384
	ds_read_b128 v[196:199], v182 offset:17408
	ds_read_b128 v[200:203], v182 offset:18432
	ds_read_b128 v[204:207], v182 offset:19456
	ds_read_b128 v[208:211], v182 offset:20480
	ds_read_b128 v[212:215], v182 offset:21504
	ds_read_b128 v[216:219], v182 offset:22528
	ds_read_b128 v[220:223], v182 offset:23552
	global_load_lds_dwordx4 v[168:169], off
	s_add_i32 m0, s52, 0x2000
	s_add_u32 s52, s74, 0x80000
	v_lshl_add_u64 v[224:225], s[74:75], 0, v[152:153]
	s_addc_u32 s53, s75, 0
	s_add_i32 s56, s84, s78
	global_load_lds_dwordx4 v[224:225], off
	v_lshl_add_u64 v[226:227], s[52:53], 0, v[148:149]
	s_mov_b32 m0, s56
	v_lshl_add_u64 v[228:229], s[76:77], 0, v[150:151]
	global_load_lds_dwordx4 v[226:227], off
	v_lshl_add_u64 v[226:227], s[52:53], 0, v[152:153]
	s_add_i32 m0, s56, 0x2000
	s_nop 0
	global_load_lds_dwordx4 v[226:227], off
	v_lshl_add_u64 v[226:227], s[76:77], 0, v[144:145]
	s_mov_b32 m0, s71
	s_nop 0
	global_load_lds_dwordx4 v[226:227], off
	s_mov_b32 m0, s79
	s_nop 0
	global_load_lds_dwordx4 v[228:229], off
	s_waitcnt vmcnt(8)
	s_waitcnt lgkmcnt(0)
	s_barrier
; #define PG8_STAGE(bufoff, gbase, voff) do { _Pragma("unroll") for (int _i = 0; _i < 2; ++_i) \
;         __builtin_amdgcn_global_load_lds((const unsigned*)((const char*)(gbase) + (voff)[_i]), (PG8_LAS unsigned*)(lds + (bufoff) + ldsw + _i * 8192), 16, 0, 0); } while (0)
; #define PG8_LDA(dst, b, h) do { _Pragma("unroll") for (int m = 0; m < 4; ++m) _Pragma("unroll") for (int k = 0; k < 2; ++k) dst[m][k] = *(const PG8_LAS bf16x8*)(lds + PG8_SA(b, h) + aoff + m * 2048 + k * 1024); } while (0)
; #define PG8_LDB(dst, b, h) do { _Pragma("unroll") for (int n = 0; n < 2; ++n) _Pragma("unroll") for (int k = 0; k < 2; ++k) dst[n][k] = *(const PG8_LAS bf16x8*)(lds + PG8_SB(b, h) + boff + n * 2048 + k * 1024); } while (0)
; #define PG8_MMA(ai, bj, At, Bt) do { __builtin_amdgcn_s_setprio(1); _Pragma("unroll") for (int m = 0; m < 4; ++m) _Pragma("unroll") for (int n = 0; n < 2; ++n) _Pragma("unroll") for (int k = 0; k < 2; ++k) \
;         acc[ai][bj][m][n] = __builtin_amdgcn_mfma_f32_16x16x32_bf16(Bt[n][k], At[m][k], acc[ai][bj][m][n], 0, 0, 0); __builtin_amdgcn_s_setprio(0); } while (0)
; #define PG8_WAIT_V(n) asm volatile("s_waitcnt vmcnt(" #n ")" ::: "memory")
; #define PG8_WAIT_L(n) asm volatile("s_waitcnt lgkmcnt(" #n ")" ::: "memory")
; #define PG8_BAR __builtin_amdgcn_s_barrier()
; #define PG8_SCHED __builtin_amdgcn_sched_barrier(0)
; template <class Epi, class Sched, bool ALIGN_EPI = false, bool SP2 = false>
; __device__ __forceinline__ void gemm_phase(PG8_LAS unsigned char* lds, const Gemm g, const Sched& S, const Epi& E) {
;     ...
;             PG8_WAIT_V(8); PG8_WAIT_L(0); PG8_BAR; PG8_MMA(1, 0, At, B0); PG8_MMA(1, 1, At, B1); PG8_BAR; PG8_SCHED;
;             PG8_LDB(B0, 1, 0); PG8_LDB(B1, 1, 1); PG8_SCHED; PG8_LDA(At, 1, 0); PG8_STAGE(PG8_SA(0, 1), a2 + hstep, voffA);
;             PG8_WAIT_V(8); PG8_WAIT_L(0); PG8_BAR; PG8_MMA(0, 0, At, B0); PG8_MMA(0, 1, At, B1); PG8_BAR; PG8_SCHED;
	s_setprio 1
	s_waitcnt lgkmcnt(0)
	v_mfma_f32_16x16x32_bf16 v[60:63], v[128:131], v[192:195], v[60:63]
	v_mfma_f32_16x16x32_bf16 v[56:59], v[136:139], v[192:195], v[56:59]
	v_mfma_f32_16x16x32_bf16 v[44:47], v[128:131], v[200:203], v[44:47]
	v_mfma_f32_16x16x32_bf16 v[40:43], v[136:139], v[200:203], v[40:43]
	v_mfma_f32_16x16x32_bf16 v[28:31], v[128:131], v[208:211], v[28:31]
	v_mfma_f32_16x16x32_bf16 v[24:27], v[136:139], v[208:211], v[24:27]
	v_mfma_f32_16x16x32_bf16 v[12:15], v[128:131], v[216:219], v[12:15]
	v_mfma_f32_16x16x32_bf16 v[8:11], v[136:139], v[216:219], v[8:11]
	v_mfma_f32_16x16x32_bf16 v[60:63], v[132:135], v[196:199], v[60:63]
	v_mfma_f32_16x16x32_bf16 v[56:59], v[140:143], v[196:199], v[56:59]
	v_mfma_f32_16x16x32_bf16 v[44:47], v[132:135], v[204:207], v[44:47]
	v_mfma_f32_16x16x32_bf16 v[40:43], v[140:143], v[204:207], v[40:43]
	v_mfma_f32_16x16x32_bf16 v[28:31], v[132:135], v[212:215], v[28:31]
	v_mfma_f32_16x16x32_bf16 v[24:27], v[140:143], v[212:215], v[24:27]
	v_mfma_f32_16x16x32_bf16 v[12:15], v[132:135], v[220:223], v[12:15]
	v_mfma_f32_16x16x32_bf16 v[8:11], v[140:143], v[220:223], v[8:11]
	s_setprio 0
	s_setprio 1
	v_mfma_f32_16x16x32_bf16 v[52:55], v[160:163], v[192:195], v[52:55]
	v_mfma_f32_16x16x32_bf16 v[48:51], v[184:187], v[192:195], v[48:51]
	v_mfma_f32_16x16x32_bf16 v[36:39], v[160:163], v[200:203], v[36:39]
	v_mfma_f32_16x16x32_bf16 v[32:35], v[184:187], v[200:203], v[32:35]
	v_mfma_f32_16x16x32_bf16 v[20:23], v[160:163], v[208:211], v[20:23]
	v_mfma_f32_16x16x32_bf16 v[16:19], v[184:187], v[208:211], v[16:19]
	v_mfma_f32_16x16x32_bf16 v[4:7], v[160:163], v[216:219], v[4:7]
	v_mfma_f32_16x16x32_bf16 v[0:3], v[184:187], v[216:219], v[0:3]
	v_mfma_f32_16x16x32_bf16 v[52:55], v[164:167], v[196:199], v[52:55]
	v_mfma_f32_16x16x32_bf16 v[48:51], v[188:191], v[196:199], v[48:51]
	v_mfma_f32_16x16x32_bf16 v[36:39], v[164:167], v[204:207], v[36:39]
	v_mfma_f32_16x16x32_bf16 v[32:35], v[188:191], v[204:207], v[32:35]
	v_mfma_f32_16x16x32_bf16 v[20:23], v[164:167], v[212:215], v[20:23]
	v_mfma_f32_16x16x32_bf16 v[16:19], v[188:191], v[212:215], v[16:19]
	v_mfma_f32_16x16x32_bf16 v[4:7], v[164:167], v[220:223], v[4:7]
	s_barrier
	v_mfma_f32_16x16x32_bf16 v[0:3], v[188:191], v[220:223], v[0:3]
	s_setprio 0
	s_add_i32 s56, 0, 0x18000
	s_add_i32 s57, 0, 0x1c000
	v_add_u32_e32 v140, s56, v171
	v_add_u32_e32 v188, s57, v171
	ds_read_b128 v[128:131], v140
	ds_read_b128 v[132:135], v140 offset:1024
	ds_read_b128 v[136:139], v140 offset:2048
	ds_read_b128 v[140:143], v140 offset:3072
	ds_read_b128 v[160:163], v188
	ds_read_b128 v[164:167], v188 offset:1024
	ds_read_b128 v[184:187], v188 offset:2048
	ds_read_b128 v[188:191], v188 offset:3072
	s_add_u32 s52, s76, 0x80000
	s_addc_u32 s53, s77, 0
	s_mov_b32 m0, s80
	v_lshl_add_u64 v[230:231], s[52:53], 0, v[144:145]
	ds_read_b128 v[192:195], v182 offset:32768
	ds_read_b128 v[196:199], v182 offset:33792
	ds_read_b128 v[200:203], v182 offset:34816
	ds_read_b128 v[204:207], v182 offset:35840
	ds_read_b128 v[208:211], v182 offset:36864
	ds_read_b128 v[212:215], v182 offset:37888
	ds_read_b128 v[216:219], v182 offset:38912
	ds_read_b128 v[220:223], v182 offset:39936
	global_load_lds_dwordx4 v[230:231], off
	v_lshl_add_u64 v[230:231], s[52:53], 0, v[150:151]
	s_mov_b32 m0, s81
	s_nop 0
	global_load_lds_dwordx4 v[230:231], off
	s_waitcnt vmcnt(8)
	s_waitcnt lgkmcnt(0)
	s_barrier
	s_setprio 1
	s_waitcnt lgkmcnt(0)
	v_mfma_f32_16x16x32_bf16 v[124:127], v[128:131], v[192:195], v[124:127]
	v_mfma_f32_16x16x32_bf16 v[120:123], v[136:139], v[192:195], v[120:123]
	v_mfma_f32_16x16x32_bf16 v[108:111], v[128:131], v[200:203], v[108:111]
	v_mfma_f32_16x16x32_bf16 v[104:107], v[136:139], v[200:203], v[104:107]
	v_mfma_f32_16x16x32_bf16 v[92:95], v[128:131], v[208:211], v[92:95]
	v_mfma_f32_16x16x32_bf16 v[88:91], v[136:139], v[208:211], v[88:91]
	v_mfma_f32_16x16x32_bf16 v[76:79], v[128:131], v[216:219], v[76:79]
	v_mfma_f32_16x16x32_bf16 v[72:75], v[136:139], v[216:219], v[72:75]
	v_mfma_f32_16x16x32_bf16 v[124:127], v[132:135], v[196:199], v[124:127]
	v_mfma_f32_16x16x32_bf16 v[120:123], v[140:143], v[196:199], v[120:123]
	v_mfma_f32_16x16x32_bf16 v[108:111], v[132:135], v[204:207], v[108:111]
	v_mfma_f32_16x16x32_bf16 v[104:107], v[140:143], v[204:207], v[104:107]
	v_mfma_f32_16x16x32_bf16 v[92:95], v[132:135], v[212:215], v[92:95]
	v_mfma_f32_16x16x32_bf16 v[88:91], v[140:143], v[212:215], v[88:91]
	v_mfma_f32_16x16x32_bf16 v[76:79], v[132:135], v[220:223], v[76:79]
	v_mfma_f32_16x16x32_bf16 v[72:75], v[140:143], v[220:223], v[72:75]
	s_setprio 0
	s_setprio 1
	v_mfma_f32_16x16x32_bf16 v[116:119], v[160:163], v[192:195], v[116:119]
	v_mfma_f32_16x16x32_bf16 v[112:115], v[184:187], v[192:195], v[112:115]
	v_mfma_f32_16x16x32_bf16 v[100:103], v[160:163], v[200:203], v[100:103]
	v_mfma_f32_16x16x32_bf16 v[96:99], v[184:187], v[200:203], v[96:99]
	v_mfma_f32_16x16x32_bf16 v[84:87], v[160:163], v[208:211], v[84:87]
	v_mfma_f32_16x16x32_bf16 v[80:83], v[184:187], v[208:211], v[80:83]
	v_mfma_f32_16x16x32_bf16 v[68:71], v[160:163], v[216:219], v[68:71]
	v_mfma_f32_16x16x32_bf16 v[64:67], v[184:187], v[216:219], v[64:67]
	v_mfma_f32_16x16x32_bf16 v[116:119], v[164:167], v[196:199], v[116:119]
	v_mfma_f32_16x16x32_bf16 v[112:115], v[188:191], v[196:199], v[112:115]
	v_mfma_f32_16x16x32_bf16 v[100:103], v[164:167], v[204:207], v[100:103]
	v_mfma_f32_16x16x32_bf16 v[96:99], v[188:191], v[204:207], v[96:99]
	v_mfma_f32_16x16x32_bf16 v[84:87], v[164:167], v[212:215], v[84:87]
	v_mfma_f32_16x16x32_bf16 v[80:83], v[188:191], v[212:215], v[80:83]
	v_mfma_f32_16x16x32_bf16 v[68:71], v[164:167], v[220:223], v[68:71]
	s_barrier
; #define PG8_STAGE(bufoff, gbase, voff) do { _Pragma("unroll") for (int _i = 0; _i < 2; ++_i) \
;         __builtin_amdgcn_global_load_lds((const unsigned*)((const char*)(gbase) + (voff)[_i]), (PG8_LAS unsigned*)(lds + (bufoff) + ldsw + _i * 8192), 16, 0, 0); } while (0)
; #define PG8_LDA(dst, b, h) do { _Pragma("unroll") for (int m = 0; m < 4; ++m) _Pragma("unroll") for (int k = 0; k < 2; ++k) dst[m][k] = *(const PG8_LAS bf16x8*)(lds + PG8_SA(b, h) + aoff + m * 2048 + k * 1024); } while (0)
; #define PG8_MMA(ai, bj, At, Bt) do { __builtin_amdgcn_s_setprio(1); _Pragma("unroll") for (int m = 0; m < 4; ++m) _Pragma("unroll") for (int n = 0; n < 2; ++n) _Pragma("unroll") for (int k = 0; k < 2; ++k) \
;         acc[ai][bj][m][n] = __builtin_amdgcn_mfma_f32_16x16x32_bf16(Bt[n][k], At[m][k], acc[ai][bj][m][n], 0, 0, 0); __builtin_amdgcn_s_setprio(0); } while (0)
; #define PG8_WAIT_V(n) asm volatile("s_waitcnt vmcnt(" #n ")" ::: "memory")
; #define PG8_WAIT_L(n) asm volatile("s_waitcnt lgkmcnt(" #n ")" ::: "memory")
; #define PG8_BAR __builtin_amdgcn_s_barrier()
; #define PG8_SCHED __builtin_amdgcn_sched_barrier(0)
; template <class Epi, class Sched, bool ALIGN_EPI = false, bool SP2 = false>
; __device__ __forceinline__ void gemm_phase(PG8_LAS unsigned char* lds, const Gemm g, const Sched& S, const Epi& E) {
;     ...
;             PG8_WAIT_V(8); PG8_WAIT_L(0); PG8_BAR; PG8_MMA(0, 0, At, B0); PG8_MMA(0, 1, At, B1); PG8_BAR; PG8_SCHED;
;             PG8_LDA(At, 1, 1); PG8_STAGE(PG8_SB(1, 0), b3, voffB); PG8_STAGE(PG8_SB(1, 1), b3 + hstep, voffB); PG8_STAGE(PG8_SA(1, 0), a3, voffA);
;             PG8_WAIT_V(8); PG8_WAIT_L(0); PG8_BAR; PG8_MMA(1, 0, At, B0); PG8_MMA(1, 1, At, B1); PG8_BAR; PG8_SCHED;
;     ...
;         if constexpr (ALIGN_EPI) { if (wr == 0) PG8_BAR; }
	v_mfma_f32_16x16x32_bf16 v[64:67], v[188:191], v[220:223], v[64:67]
	s_setprio 0
	s_add_i32 s52, s56, s78
	v_lshl_add_u64 v[168:169], v[168:169], 0, s[40:41]
	s_mov_b32 m0, s52
	ds_read_b128 v[192:195], v182 offset:49152
	ds_read_b128 v[196:199], v182 offset:50176
	ds_read_b128 v[200:203], v182 offset:51200
	ds_read_b128 v[204:207], v182 offset:52224
	ds_read_b128 v[208:211], v182 offset:53248
	ds_read_b128 v[212:215], v182 offset:54272
	ds_read_b128 v[216:219], v182 offset:55296
	ds_read_b128 v[220:223], v182 offset:56320
	global_load_lds_dwordx4 v[168:169], off
	s_add_i32 m0, s52, 0x2000
	s_add_u32 s52, s74, 0x80080
	v_lshl_add_u64 v[168:169], v[224:225], 0, s[40:41]
	s_addc_u32 s53, s75, 0
	s_add_i32 s56, s57, s78
	global_load_lds_dwordx4 v[168:169], off
	v_lshl_add_u64 v[168:169], s[52:53], 0, v[148:149]
	s_mov_b32 m0, s56
	s_nop 0
	global_load_lds_dwordx4 v[168:169], off
	v_lshl_add_u64 v[168:169], s[52:53], 0, v[152:153]
	s_add_i32 m0, s56, 0x2000
	s_nop 0
	global_load_lds_dwordx4 v[168:169], off
	v_lshl_add_u64 v[168:169], v[226:227], 0, s[40:41]
	s_mov_b32 m0, s3
	s_nop 0
	global_load_lds_dwordx4 v[168:169], off
	v_lshl_add_u64 v[168:169], v[228:229], 0, s[40:41]
	s_mov_b32 m0, s28
	s_nop 0
	global_load_lds_dwordx4 v[168:169], off
	s_waitcnt vmcnt(8)
	s_waitcnt lgkmcnt(0)
	s_barrier
	s_setprio 1
	s_waitcnt lgkmcnt(0)
	v_mfma_f32_16x16x32_bf16 v[60:63], v[128:131], v[192:195], v[60:63]
	v_mfma_f32_16x16x32_bf16 v[56:59], v[136:139], v[192:195], v[56:59]
	v_mfma_f32_16x16x32_bf16 v[44:47], v[128:131], v[200:203], v[44:47]
	v_mfma_f32_16x16x32_bf16 v[40:43], v[136:139], v[200:203], v[40:43]
	v_mfma_f32_16x16x32_bf16 v[28:31], v[128:131], v[208:211], v[28:31]
	v_mfma_f32_16x16x32_bf16 v[24:27], v[136:139], v[208:211], v[24:27]
	v_mfma_f32_16x16x32_bf16 v[12:15], v[128:131], v[216:219], v[12:15]
	v_mfma_f32_16x16x32_bf16 v[8:11], v[136:139], v[216:219], v[8:11]
	v_mfma_f32_16x16x32_bf16 v[60:63], v[132:135], v[196:199], v[60:63]
	v_mfma_f32_16x16x32_bf16 v[56:59], v[140:143], v[196:199], v[56:59]
	v_mfma_f32_16x16x32_bf16 v[44:47], v[132:135], v[204:207], v[44:47]
	v_mfma_f32_16x16x32_bf16 v[40:43], v[140:143], v[204:207], v[40:43]
	v_mfma_f32_16x16x32_bf16 v[28:31], v[132:135], v[212:215], v[28:31]
	v_mfma_f32_16x16x32_bf16 v[24:27], v[140:143], v[212:215], v[24:27]
	v_mfma_f32_16x16x32_bf16 v[12:15], v[132:135], v[220:223], v[12:15]
	v_mfma_f32_16x16x32_bf16 v[8:11], v[140:143], v[220:223], v[8:11]
	s_setprio 0
	s_setprio 1
	v_mfma_f32_16x16x32_bf16 v[52:55], v[160:163], v[192:195], v[52:55]
	v_mfma_f32_16x16x32_bf16 v[48:51], v[184:187], v[192:195], v[48:51]
	v_mfma_f32_16x16x32_bf16 v[36:39], v[160:163], v[200:203], v[36:39]
	v_mfma_f32_16x16x32_bf16 v[32:35], v[184:187], v[200:203], v[32:35]
	v_mfma_f32_16x16x32_bf16 v[20:23], v[160:163], v[208:211], v[20:23]
	v_mfma_f32_16x16x32_bf16 v[16:19], v[184:187], v[208:211], v[16:19]
	v_mfma_f32_16x16x32_bf16 v[4:7], v[160:163], v[216:219], v[4:7]
	v_mfma_f32_16x16x32_bf16 v[0:3], v[184:187], v[216:219], v[0:3]
	v_mfma_f32_16x16x32_bf16 v[52:55], v[164:167], v[196:199], v[52:55]
	v_mfma_f32_16x16x32_bf16 v[48:51], v[188:191], v[196:199], v[48:51]
	v_mfma_f32_16x16x32_bf16 v[36:39], v[164:167], v[204:207], v[36:39]
	v_mfma_f32_16x16x32_bf16 v[32:35], v[188:191], v[204:207], v[32:35]
	v_mfma_f32_16x16x32_bf16 v[20:23], v[164:167], v[212:215], v[20:23]
	v_mfma_f32_16x16x32_bf16 v[16:19], v[188:191], v[212:215], v[16:19]
	v_mfma_f32_16x16x32_bf16 v[4:7], v[164:167], v[220:223], v[4:7]
	s_barrier
	v_mfma_f32_16x16x32_bf16 v[0:3], v[188:191], v[220:223], v[0:3]
	s_setprio 0
	s_add_i32 s92, s92, 2
	s_add_u32 s72, s72, 0x100
	s_addc_u32 s73, s73, 0
	s_add_u32 s90, s90, 0x100
	s_addc_u32 s91, s91, 0
	s_cmp_gt_u32 s92, 29
	s_cbranch_scc0 .LBB0_809
	s_and_b64 vcc, exec, s[42:43]
	s_cbranch_vccz .LBB0_812
	s_barrier

; #define PG8_STAGE(bufoff, gbase, voff) do { _Pragma("unroll") for (int _i = 0; _i < 2; ++_i) \
;         __builtin_amdgcn_global_load_lds((const unsigned*)((const char*)(gbase) + (voff)[_i]), (PG8_LAS unsigned*)(lds + (bufoff) + ldsw + _i * 8192), 16, 0, 0); } while (0)
; #define PG8_LDA(dst, b, h) do { _Pragma("unroll") for (int m = 0; m < 4; ++m) _Pragma("unroll") for (int k = 0; k < 2; ++k) dst[m][k] = *(const PG8_LAS bf16x8*)(lds + PG8_SA(b, h) + aoff + m * 2048 + k * 1024); } while (0)
; #define PG8_LDB(dst, b, h) do { _Pragma("unroll") for (int n = 0; n < 2; ++n) _Pragma("unroll") for (int k = 0; k < 2; ++k) dst[n][k] = *(const PG8_LAS bf16x8*)(lds + PG8_SB(b, h) + boff + n * 2048 + k * 1024); } while (0)
; #define PG8_MMA(ai, bj, At, Bt) do { __builtin_amdgcn_s_setprio(1); _Pragma("unroll") for (int m = 0; m < 4; ++m) _Pragma("unroll") for (int n = 0; n < 2; ++n) _Pragma("unroll") for (int k = 0; k < 2; ++k) \
;         acc[ai][bj][m][n] = __builtin_amdgcn_mfma_f32_16x16x32_bf16(Bt[n][k], At[m][k], acc[ai][bj][m][n], 0, 0, 0); __builtin_amdgcn_s_setprio(0); } while (0)
; #define PG8_WAIT_V(n) asm volatile("s_waitcnt vmcnt(" #n ")" ::: "memory")
; #define PG8_WAIT_L(n) asm volatile("s_waitcnt lgkmcnt(" #n ")" ::: "memory")
; #define PG8_BAR __builtin_amdgcn_s_barrier()
; #define PG8_SCHED __builtin_amdgcn_sched_barrier(0)
; template <class Epi, class Sched, bool ALIGN_EPI = false, bool SP2 = false>
; __device__ __forceinline__ void gemm_phase(PG8_LAS unsigned char* lds, const Gemm g, const Sched& S, const Epi& E) {
;     ...
;             const char* a1 = cA + (size_t)(t + 1) * kstep;
;             const char* a2 = last ? nA : cA + (size_t)(t + 2) * kstep; const char* b2 = last ? nB : cB + (size_t)(t + 2) * kstep;
;             const char* a3 = a2 + kstep; const char* b3 = b2 + kstep;
;             if constexpr (SP2) {
;             PG8_LDB(B0, 0, 0); PG8_LDB(B1, 0, 1); PG8_SCHED; PG8_LDA(At, 0, 0); PG8_STAGE(PG8_SA(1, 1), a1 + hstep, voffA);
;             PG8_WAIT_V(8); PG8_WAIT_L(0); PG8_BAR; PG8_MMA(0, 0, At, B0); PG8_MMA(0, 1, At, B1); PG8_BAR; PG8_SCHED;
;             PG8_LDA(At, 0, 1); PG8_STAGE(PG8_SB(0, 0), b2, voffB); PG8_STAGE(PG8_SB(0, 1), b2 + hstep, voffB); PG8_STAGE(PG8_SA(0, 0), a2, voffA);
;             PG8_WAIT_V(8); PG8_WAIT_L(0); PG8_BAR; PG8_MMA(1, 0, At, B0); PG8_MMA(1, 1, At, B1); PG8_BAR; PG8_SCHED;
.LBB0_1051:
	ds_read_b128 v[128:131], v205
	ds_read_b128 v[132:135], v205 offset:1024
	ds_read_b128 v[154:157], v205 offset:2048
	ds_read_b128 v[158:161], v205 offset:3072
	ds_read_b128 v[162:165], v206
	ds_read_b128 v[166:169], v206 offset:1024
	ds_read_b128 v[170:173], v206 offset:2048
	ds_read_b128 v[174:177], v206 offset:3072
	s_add_u32 s54, s52, 0xfff80080
	s_addc_u32 s55, s53, -1
	s_cmp_eq_u32 s77, 28
	s_cselect_b32 s57, s43, s55
	s_cselect_b32 s56, s49, s54
	s_cselect_b32 s55, s37, s76
	s_cselect_b32 s54, s51, s75
	v_lshl_add_u64 v[218:219], s[52:53], 0, v[144:145]
	s_add_i32 m0, s61, 0xc000
	ds_read_b128 v[178:181], v207
	ds_read_b128 v[182:185], v207 offset:1024
	ds_read_b128 v[186:189], v207 offset:2048
	ds_read_b128 v[190:193], v207 offset:3072
	ds_read_b128 v[194:197], v207 offset:4096
	ds_read_b128 v[198:201], v207 offset:5120
	ds_read_b128 v[210:213], v207 offset:6144
	ds_read_b128 v[214:217], v207 offset:7168
	global_load_lds_dwordx4 v[218:219], off
	v_lshl_add_u64 v[218:219], s[52:53], 0, v[148:149]
	s_add_i32 m0, s61, 0xe000
	s_nop 0
	global_load_lds_dwordx4 v[218:219], off
	s_waitcnt vmcnt(8)
	s_waitcnt lgkmcnt(0)
	s_barrier
	s_setprio 1
	s_waitcnt lgkmcnt(0)
	v_mfma_f32_16x16x32_bf16 v[124:127], v[128:131], v[178:181], v[124:127]
	v_mfma_f32_16x16x32_bf16 v[120:123], v[154:157], v[178:181], v[120:123]
	v_mfma_f32_16x16x32_bf16 v[116:119], v[128:131], v[186:189], v[116:119]
	v_mfma_f32_16x16x32_bf16 v[112:115], v[154:157], v[186:189], v[112:115]
	v_mfma_f32_16x16x32_bf16 v[108:111], v[128:131], v[194:197], v[108:111]
	v_mfma_f32_16x16x32_bf16 v[104:107], v[154:157], v[194:197], v[104:107]
	v_mfma_f32_16x16x32_bf16 v[100:103], v[128:131], v[210:213], v[100:103]
	v_mfma_f32_16x16x32_bf16 v[96:99], v[154:157], v[210:213], v[96:99]
	v_mfma_f32_16x16x32_bf16 v[124:127], v[132:135], v[182:185], v[124:127]
	v_mfma_f32_16x16x32_bf16 v[120:123], v[158:161], v[182:185], v[120:123]
	v_mfma_f32_16x16x32_bf16 v[116:119], v[132:135], v[190:193], v[116:119]
	v_mfma_f32_16x16x32_bf16 v[112:115], v[158:161], v[190:193], v[112:115]
	v_mfma_f32_16x16x32_bf16 v[108:111], v[132:135], v[198:201], v[108:111]
	v_mfma_f32_16x16x32_bf16 v[104:107], v[158:161], v[198:201], v[104:107]
	v_mfma_f32_16x16x32_bf16 v[100:103], v[132:135], v[214:217], v[100:103]
	v_mfma_f32_16x16x32_bf16 v[96:99], v[158:161], v[214:217], v[96:99]
	s_setprio 0
	s_setprio 1
	v_mfma_f32_16x16x32_bf16 v[60:63], v[162:165], v[178:181], v[60:63]
	v_mfma_f32_16x16x32_bf16 v[56:59], v[170:173], v[178:181], v[56:59]
	v_mfma_f32_16x16x32_bf16 v[52:55], v[162:165], v[186:189], v[52:55]
	v_mfma_f32_16x16x32_bf16 v[48:51], v[170:173], v[186:189], v[48:51]
	v_mfma_f32_16x16x32_bf16 v[44:47], v[162:165], v[194:197], v[44:47]
	v_mfma_f32_16x16x32_bf16 v[40:43], v[170:173], v[194:197], v[40:43]
	v_mfma_f32_16x16x32_bf16 v[36:39], v[162:165], v[210:213], v[36:39]
	v_mfma_f32_16x16x32_bf16 v[32:35], v[170:173], v[210:213], v[32:35]
	v_mfma_f32_16x16x32_bf16 v[60:63], v[166:169], v[182:185], v[60:63]
	v_mfma_f32_16x16x32_bf16 v[56:59], v[174:177], v[182:185], v[56:59]
	v_mfma_f32_16x16x32_bf16 v[52:55], v[166:169], v[190:193], v[52:55]
	v_mfma_f32_16x16x32_bf16 v[48:51], v[174:177], v[190:193], v[48:51]
	v_mfma_f32_16x16x32_bf16 v[44:47], v[166:169], v[198:201], v[44:47]
	v_mfma_f32_16x16x32_bf16 v[40:43], v[174:177], v[198:201], v[40:43]
	v_mfma_f32_16x16x32_bf16 v[36:39], v[166:169], v[214:217], v[36:39]
	s_barrier
	v_mfma_f32_16x16x32_bf16 v[32:35], v[174:177], v[214:217], v[32:35]
	s_setprio 0
	s_add_i32 s78, s33, s60
	v_lshl_add_u64 v[218:219], s[54:55], 0, v[138:139]
	s_mov_b32 m0, s78
	ds_read_b128 v[178:181], v207 offset:16384
	ds_read_b128 v[182:185], v207 offset:17408
	ds_read_b128 v[186:189], v207 offset:18432
	ds_read_b128 v[190:193], v207 offset:19456
	ds_read_b128 v[194:197], v207 offset:20480
	ds_read_b128 v[198:201], v207 offset:21504
	ds_read_b128 v[210:213], v207 offset:22528
	ds_read_b128 v[214:217], v207 offset:23552
	global_load_lds_dwordx4 v[218:219], off
	s_add_i32 m0, s78, 0x2000
	s_add_u32 s78, s54, 0x80000
	v_lshl_add_u64 v[220:221], s[54:55], 0, v[142:143]
	s_addc_u32 s79, s55, 0
	s_add_i32 s80, s74, s60
	global_load_lds_dwordx4 v[220:221], off
	v_lshl_add_u64 v[222:223], s[78:79], 0, v[138:139]
	s_mov_b32 m0, s80
	v_lshl_add_u64 v[224:225], s[56:57], 0, v[140:141]
	global_load_lds_dwordx4 v[222:223], off
	v_lshl_add_u64 v[222:223], s[78:79], 0, v[142:143]
	s_add_i32 m0, s80, 0x2000
	s_nop 0
	global_load_lds_dwordx4 v[222:223], off
	v_lshl_add_u64 v[222:223], s[56:57], 0, v[136:137]
	s_mov_b32 m0, s61
	s_nop 0
	global_load_lds_dwordx4 v[222:223], off
	s_mov_b32 m0, s62
	s_nop 0
	global_load_lds_dwordx4 v[224:225], off
	s_waitcnt vmcnt(8)
	s_waitcnt lgkmcnt(0)
	s_barrier
; #define PG8_STAGE(bufoff, gbase, voff) do { _Pragma("unroll") for (int _i = 0; _i < 2; ++_i) \
;         __builtin_amdgcn_global_load_lds((const unsigned*)((const char*)(gbase) + (voff)[_i]), (PG8_LAS unsigned*)(lds + (bufoff) + ldsw + _i * 8192), 16, 0, 0); } while (0)
; #define PG8_LDA(dst, b, h) do { _Pragma("unroll") for (int m = 0; m < 4; ++m) _Pragma("unroll") for (int k = 0; k < 2; ++k) dst[m][k] = *(const PG8_LAS bf16x8*)(lds + PG8_SA(b, h) + aoff + m * 2048 + k * 1024); } while (0)
; #define PG8_LDB(dst, b, h) do { _Pragma("unroll") for (int n = 0; n < 2; ++n) _Pragma("unroll") for (int k = 0; k < 2; ++k) dst[n][k] = *(const PG8_LAS bf16x8*)(lds + PG8_SB(b, h) + boff + n * 2048 + k * 1024); } while (0)
; #define PG8_MMA(ai, bj, At, Bt) do { __builtin_amdgcn_s_setprio(1); _Pragma("unroll") for (int m = 0; m < 4; ++m) _Pragma("unroll") for (int n = 0; n < 2; ++n) _Pragma("unroll") for (int k = 0; k < 2; ++k) \
;         acc[ai][bj][m][n] = __builtin_amdgcn_mfma_f32_16x16x32_bf16(Bt[n][k], At[m][k], acc[ai][bj][m][n], 0, 0, 0); __builtin_amdgcn_s_setprio(0); } while (0)
; #define PG8_WAIT_V(n) asm volatile("s_waitcnt vmcnt(" #n ")" ::: "memory")
; #define PG8_WAIT_L(n) asm volatile("s_waitcnt lgkmcnt(" #n ")" ::: "memory")
; #define PG8_BAR __builtin_amdgcn_s_barrier()
; #define PG8_SCHED __builtin_amdgcn_sched_barrier(0)
; template <class Epi, class Sched, bool ALIGN_EPI = false, bool SP2 = false>
; __device__ __forceinline__ void gemm_phase(PG8_LAS unsigned char* lds, const Gemm g, const Sched& S, const Epi& E) {
;     ...
;             PG8_WAIT_V(8); PG8_WAIT_L(0); PG8_BAR; PG8_MMA(1, 0, At, B0); PG8_MMA(1, 1, At, B1); PG8_BAR; PG8_SCHED;
;             PG8_LDB(B0, 1, 0); PG8_LDB(B1, 1, 1); PG8_SCHED; PG8_LDA(At, 1, 0); PG8_STAGE(PG8_SA(0, 1), a2 + hstep, voffA);
;             PG8_WAIT_V(8); PG8_WAIT_L(0); PG8_BAR; PG8_MMA(0, 0, At, B0); PG8_MMA(0, 1, At, B1); PG8_BAR; PG8_SCHED;
	s_setprio 1
	s_waitcnt lgkmcnt(0)
	v_mfma_f32_16x16x32_bf16 v[92:95], v[128:131], v[178:181], v[92:95]
	v_mfma_f32_16x16x32_bf16 v[88:91], v[154:157], v[178:181], v[88:91]
	v_mfma_f32_16x16x32_bf16 v[84:87], v[128:131], v[186:189], v[84:87]
	v_mfma_f32_16x16x32_bf16 v[80:83], v[154:157], v[186:189], v[80:83]
	v_mfma_f32_16x16x32_bf16 v[76:79], v[128:131], v[194:197], v[76:79]
	v_mfma_f32_16x16x32_bf16 v[72:75], v[154:157], v[194:197], v[72:75]
	v_mfma_f32_16x16x32_bf16 v[68:71], v[128:131], v[210:213], v[68:71]
	v_mfma_f32_16x16x32_bf16 v[64:67], v[154:157], v[210:213], v[64:67]
	v_mfma_f32_16x16x32_bf16 v[92:95], v[132:135], v[182:185], v[92:95]
	v_mfma_f32_16x16x32_bf16 v[88:91], v[158:161], v[182:185], v[88:91]
	v_mfma_f32_16x16x32_bf16 v[84:87], v[132:135], v[190:193], v[84:87]
	v_mfma_f32_16x16x32_bf16 v[80:83], v[158:161], v[190:193], v[80:83]
	v_mfma_f32_16x16x32_bf16 v[76:79], v[132:135], v[198:201], v[76:79]
	v_mfma_f32_16x16x32_bf16 v[72:75], v[158:161], v[198:201], v[72:75]
	v_mfma_f32_16x16x32_bf16 v[68:71], v[132:135], v[214:217], v[68:71]
	v_mfma_f32_16x16x32_bf16 v[64:67], v[158:161], v[214:217], v[64:67]
	s_setprio 0
	s_setprio 1
	v_mfma_f32_16x16x32_bf16 v[28:31], v[162:165], v[178:181], v[28:31]
	v_mfma_f32_16x16x32_bf16 v[24:27], v[170:173], v[178:181], v[24:27]
	v_mfma_f32_16x16x32_bf16 v[20:23], v[162:165], v[186:189], v[20:23]
	v_mfma_f32_16x16x32_bf16 v[16:19], v[170:173], v[186:189], v[16:19]
	v_mfma_f32_16x16x32_bf16 v[12:15], v[162:165], v[194:197], v[12:15]
	v_mfma_f32_16x16x32_bf16 v[8:11], v[170:173], v[194:197], v[8:11]
	v_mfma_f32_16x16x32_bf16 v[4:7], v[162:165], v[210:213], v[4:7]
	v_mfma_f32_16x16x32_bf16 v[0:3], v[170:173], v[210:213], v[0:3]
	v_mfma_f32_16x16x32_bf16 v[28:31], v[166:169], v[182:185], v[28:31]
	v_mfma_f32_16x16x32_bf16 v[24:27], v[174:177], v[182:185], v[24:27]
	v_mfma_f32_16x16x32_bf16 v[20:23], v[166:169], v[190:193], v[20:23]
	v_mfma_f32_16x16x32_bf16 v[16:19], v[174:177], v[190:193], v[16:19]
	v_mfma_f32_16x16x32_bf16 v[12:15], v[166:169], v[198:201], v[12:15]
	v_mfma_f32_16x16x32_bf16 v[8:11], v[174:177], v[198:201], v[8:11]
	v_mfma_f32_16x16x32_bf16 v[4:7], v[166:169], v[214:217], v[4:7]
	s_barrier
	v_mfma_f32_16x16x32_bf16 v[0:3], v[174:177], v[214:217], v[0:3]
	s_setprio 0
	s_add_i32 s78, 0, 0x18000
	s_add_i32 s79, 0, 0x1c000
	v_add_u32_e32 v158, s78, v203
	v_add_u32_e32 v174, s79, v203
	ds_read_b128 v[128:131], v158
	ds_read_b128 v[132:135], v158 offset:1024
	ds_read_b128 v[154:157], v158 offset:2048
	ds_read_b128 v[158:161], v158 offset:3072
	ds_read_b128 v[162:165], v174
	ds_read_b128 v[166:169], v174 offset:1024
	ds_read_b128 v[170:173], v174 offset:2048
	ds_read_b128 v[174:177], v174 offset:3072
	s_add_u32 s56, s56, 0x80000
	s_addc_u32 s57, s57, 0
	s_mov_b32 m0, s63
	v_lshl_add_u64 v[226:227], s[56:57], 0, v[136:137]
	ds_read_b128 v[178:181], v207 offset:32768
	ds_read_b128 v[182:185], v207 offset:33792
	ds_read_b128 v[186:189], v207 offset:34816
	ds_read_b128 v[190:193], v207 offset:35840
	ds_read_b128 v[194:197], v207 offset:36864
	ds_read_b128 v[198:201], v207 offset:37888
	ds_read_b128 v[210:213], v207 offset:38912
	ds_read_b128 v[214:217], v207 offset:39936
	global_load_lds_dwordx4 v[226:227], off
	v_lshl_add_u64 v[226:227], s[56:57], 0, v[140:141]
	s_mov_b32 m0, s64
	s_nop 0
	global_load_lds_dwordx4 v[226:227], off
	s_waitcnt vmcnt(8)
	s_waitcnt lgkmcnt(0)
	s_barrier
	s_setprio 1
	s_waitcnt lgkmcnt(0)
	v_mfma_f32_16x16x32_bf16 v[124:127], v[128:131], v[178:181], v[124:127]
	v_mfma_f32_16x16x32_bf16 v[120:123], v[154:157], v[178:181], v[120:123]
	v_mfma_f32_16x16x32_bf16 v[116:119], v[128:131], v[186:189], v[116:119]
	v_mfma_f32_16x16x32_bf16 v[112:115], v[154:157], v[186:189], v[112:115]
	v_mfma_f32_16x16x32_bf16 v[108:111], v[128:131], v[194:197], v[108:111]
	v_mfma_f32_16x16x32_bf16 v[104:107], v[154:157], v[194:197], v[104:107]
	v_mfma_f32_16x16x32_bf16 v[100:103], v[128:131], v[210:213], v[100:103]
	v_mfma_f32_16x16x32_bf16 v[96:99], v[154:157], v[210:213], v[96:99]
	v_mfma_f32_16x16x32_bf16 v[124:127], v[132:135], v[182:185], v[124:127]
	v_mfma_f32_16x16x32_bf16 v[120:123], v[158:161], v[182:185], v[120:123]
	v_mfma_f32_16x16x32_bf16 v[116:119], v[132:135], v[190:193], v[116:119]
	v_mfma_f32_16x16x32_bf16 v[112:115], v[158:161], v[190:193], v[112:115]
	v_mfma_f32_16x16x32_bf16 v[108:111], v[132:135], v[198:201], v[108:111]
	v_mfma_f32_16x16x32_bf16 v[104:107], v[158:161], v[198:201], v[104:107]
	v_mfma_f32_16x16x32_bf16 v[100:103], v[132:135], v[214:217], v[100:103]
	v_mfma_f32_16x16x32_bf16 v[96:99], v[158:161], v[214:217], v[96:99]
	s_setprio 0
	s_setprio 1
	v_mfma_f32_16x16x32_bf16 v[60:63], v[162:165], v[178:181], v[60:63]
	v_mfma_f32_16x16x32_bf16 v[56:59], v[170:173], v[178:181], v[56:59]
	v_mfma_f32_16x16x32_bf16 v[52:55], v[162:165], v[186:189], v[52:55]
	v_mfma_f32_16x16x32_bf16 v[48:51], v[170:173], v[186:189], v[48:51]
	v_mfma_f32_16x16x32_bf16 v[44:47], v[162:165], v[194:197], v[44:47]
	v_mfma_f32_16x16x32_bf16 v[40:43], v[170:173], v[194:197], v[40:43]
	v_mfma_f32_16x16x32_bf16 v[36:39], v[162:165], v[210:213], v[36:39]
	v_mfma_f32_16x16x32_bf16 v[32:35], v[170:173], v[210:213], v[32:35]
	v_mfma_f32_16x16x32_bf16 v[60:63], v[166:169], v[182:185], v[60:63]
	v_mfma_f32_16x16x32_bf16 v[56:59], v[174:177], v[182:185], v[56:59]
	v_mfma_f32_16x16x32_bf16 v[52:55], v[166:169], v[190:193], v[52:55]
	v_mfma_f32_16x16x32_bf16 v[48:51], v[174:177], v[190:193], v[48:51]
	v_mfma_f32_16x16x32_bf16 v[44:47], v[166:169], v[198:201], v[44:47]
	v_mfma_f32_16x16x32_bf16 v[40:43], v[174:177], v[198:201], v[40:43]
	v_mfma_f32_16x16x32_bf16 v[36:39], v[166:169], v[214:217], v[36:39]
	s_barrier
; #define PG8_STAGE(bufoff, gbase, voff) do { _Pragma("unroll") for (int _i = 0; _i < 2; ++_i) \
;         __builtin_amdgcn_global_load_lds((const unsigned*)((const char*)(gbase) + (voff)[_i]), (PG8_LAS unsigned*)(lds + (bufoff) + ldsw + _i * 8192), 16, 0, 0); } while (0)
; #define PG8_LDA(dst, b, h) do { _Pragma("unroll") for (int m = 0; m < 4; ++m) _Pragma("unroll") for (int k = 0; k < 2; ++k) dst[m][k] = *(const PG8_LAS bf16x8*)(lds + PG8_SA(b, h) + aoff + m * 2048 + k * 1024); } while (0)
; #define PG8_MMA(ai, bj, At, Bt) do { __builtin_amdgcn_s_setprio(1); _Pragma("unroll") for (int m = 0; m < 4; ++m) _Pragma("unroll") for (int n = 0; n < 2; ++n) _Pragma("unroll") for (int k = 0; k < 2; ++k) \
;         acc[ai][bj][m][n] = __builtin_amdgcn_mfma_f32_16x16x32_bf16(Bt[n][k], At[m][k], acc[ai][bj][m][n], 0, 0, 0); __builtin_amdgcn_s_setprio(0); } while (0)
; #define PG8_WAIT_V(n) asm volatile("s_waitcnt vmcnt(" #n ")" ::: "memory")
; #define PG8_WAIT_L(n) asm volatile("s_waitcnt lgkmcnt(" #n ")" ::: "memory")
; #define PG8_BAR __builtin_amdgcn_s_barrier()
; #define PG8_SCHED __builtin_amdgcn_sched_barrier(0)
; template <class Epi, class Sched, bool ALIGN_EPI = false, bool SP2 = false>
; __device__ __forceinline__ void gemm_phase(PG8_LAS unsigned char* lds, const Gemm g, const Sched& S, const Epi& E) {
;     ...
;             PG8_WAIT_V(8); PG8_WAIT_L(0); PG8_BAR; PG8_MMA(0, 0, At, B0); PG8_MMA(0, 1, At, B1); PG8_BAR; PG8_SCHED;
;             PG8_LDA(At, 1, 1); PG8_STAGE(PG8_SB(1, 0), b3, voffB); PG8_STAGE(PG8_SB(1, 1), b3 + hstep, voffB); PG8_STAGE(PG8_SA(1, 0), a3, voffA);
;             PG8_WAIT_V(8); PG8_WAIT_L(0); PG8_BAR; PG8_MMA(1, 0, At, B0); PG8_MMA(1, 1, At, B1); PG8_BAR; PG8_SCHED;
;     ...
;         if constexpr (ALIGN_EPI) { if (wr == 0) PG8_BAR; }
	v_mfma_f32_16x16x32_bf16 v[32:35], v[174:177], v[214:217], v[32:35]
	s_setprio 0
	s_add_i32 s56, s78, s60
	v_lshl_add_u64 v[218:219], v[218:219], 0, s[12:13]
	s_mov_b32 m0, s56
	ds_read_b128 v[178:181], v207 offset:49152
	ds_read_b128 v[182:185], v207 offset:50176
	ds_read_b128 v[186:189], v207 offset:51200
	ds_read_b128 v[190:193], v207 offset:52224
	ds_read_b128 v[194:197], v207 offset:53248
	ds_read_b128 v[198:201], v207 offset:54272
	ds_read_b128 v[210:213], v207 offset:55296
	ds_read_b128 v[214:217], v207 offset:56320
	global_load_lds_dwordx4 v[218:219], off
	s_add_i32 m0, s56, 0x2000
	s_add_u32 s54, s54, 0x80080
	v_lshl_add_u64 v[218:219], v[220:221], 0, s[12:13]
	s_addc_u32 s55, s55, 0
	s_add_i32 s56, s79, s60
	global_load_lds_dwordx4 v[218:219], off
	v_lshl_add_u64 v[218:219], s[54:55], 0, v[138:139]
	s_mov_b32 m0, s56
	s_nop 0
	global_load_lds_dwordx4 v[218:219], off
	v_lshl_add_u64 v[218:219], s[54:55], 0, v[142:143]
	s_add_i32 m0, s56, 0x2000
	s_nop 0
	global_load_lds_dwordx4 v[218:219], off
	v_lshl_add_u64 v[218:219], v[222:223], 0, s[12:13]
	s_mov_b32 m0, s70
	s_nop 0
	global_load_lds_dwordx4 v[218:219], off
	v_lshl_add_u64 v[218:219], v[224:225], 0, s[12:13]
	s_mov_b32 m0, s71
	s_nop 0
	global_load_lds_dwordx4 v[218:219], off
	s_waitcnt vmcnt(8)
	s_waitcnt lgkmcnt(0)
	s_barrier
	s_setprio 1
	s_waitcnt lgkmcnt(0)
	v_mfma_f32_16x16x32_bf16 v[92:95], v[128:131], v[178:181], v[92:95]
	v_mfma_f32_16x16x32_bf16 v[88:91], v[154:157], v[178:181], v[88:91]
	v_mfma_f32_16x16x32_bf16 v[84:87], v[128:131], v[186:189], v[84:87]
	v_mfma_f32_16x16x32_bf16 v[80:83], v[154:157], v[186:189], v[80:83]
	v_mfma_f32_16x16x32_bf16 v[76:79], v[128:131], v[194:197], v[76:79]
	v_mfma_f32_16x16x32_bf16 v[72:75], v[154:157], v[194:197], v[72:75]
	v_mfma_f32_16x16x32_bf16 v[68:71], v[128:131], v[210:213], v[68:71]
	v_mfma_f32_16x16x32_bf16 v[64:67], v[154:157], v[210:213], v[64:67]
	v_mfma_f32_16x16x32_bf16 v[92:95], v[132:135], v[182:185], v[92:95]
	v_mfma_f32_16x16x32_bf16 v[88:91], v[158:161], v[182:185], v[88:91]
	v_mfma_f32_16x16x32_bf16 v[84:87], v[132:135], v[190:193], v[84:87]
	v_mfma_f32_16x16x32_bf16 v[80:83], v[158:161], v[190:193], v[80:83]
	v_mfma_f32_16x16x32_bf16 v[76:79], v[132:135], v[198:201], v[76:79]
	v_mfma_f32_16x16x32_bf16 v[72:75], v[158:161], v[198:201], v[72:75]
	v_mfma_f32_16x16x32_bf16 v[68:71], v[132:135], v[214:217], v[68:71]
	v_mfma_f32_16x16x32_bf16 v[64:67], v[158:161], v[214:217], v[64:67]
	s_setprio 0
	s_setprio 1
	v_mfma_f32_16x16x32_bf16 v[28:31], v[162:165], v[178:181], v[28:31]
	v_mfma_f32_16x16x32_bf16 v[24:27], v[170:173], v[178:181], v[24:27]
	v_mfma_f32_16x16x32_bf16 v[20:23], v[162:165], v[186:189], v[20:23]
	v_mfma_f32_16x16x32_bf16 v[16:19], v[170:173], v[186:189], v[16:19]
	v_mfma_f32_16x16x32_bf16 v[12:15], v[162:165], v[194:197], v[12:15]
	v_mfma_f32_16x16x32_bf16 v[8:11], v[170:173], v[194:197], v[8:11]
	v_mfma_f32_16x16x32_bf16 v[4:7], v[162:165], v[210:213], v[4:7]
	v_mfma_f32_16x16x32_bf16 v[0:3], v[170:173], v[210:213], v[0:3]
	v_mfma_f32_16x16x32_bf16 v[28:31], v[166:169], v[182:185], v[28:31]
	v_mfma_f32_16x16x32_bf16 v[24:27], v[174:177], v[182:185], v[24:27]
	v_mfma_f32_16x16x32_bf16 v[20:23], v[166:169], v[190:193], v[20:23]
	v_mfma_f32_16x16x32_bf16 v[16:19], v[174:177], v[190:193], v[16:19]
	v_mfma_f32_16x16x32_bf16 v[12:15], v[166:169], v[198:201], v[12:15]
	v_mfma_f32_16x16x32_bf16 v[8:11], v[174:177], v[198:201], v[8:11]
	v_mfma_f32_16x16x32_bf16 v[4:7], v[166:169], v[214:217], v[4:7]
	s_barrier
	v_mfma_f32_16x16x32_bf16 v[0:3], v[174:177], v[214:217], v[0:3]
	s_setprio 0
	s_add_i32 s77, s77, 2
	s_add_u32 s52, s52, 0x100
	s_addc_u32 s53, s53, 0
	s_add_u32 s75, s75, 0x100
	s_addc_u32 s76, s76, 0
	s_cmp_gt_u32 s77, 29
	s_cbranch_scc0 .LBB0_1051
	s_and_b64 vcc, exec, s[14:15]
	s_cbranch_vccz .LBB0_1054
	s_barrier

; #define PG8_STAGE(bufoff, gbase, voff) do { _Pragma("unroll") for (int _i = 0; _i < 2; ++_i) \
;         __builtin_amdgcn_global_load_lds((const unsigned*)((const char*)(gbase) + (voff)[_i]), (PG8_LAS unsigned*)(lds + (bufoff) + ldsw + _i * 8192), 16, 0, 0); } while (0)
; #define PG8_LDA(dst, b, h) do { _Pragma("unroll") for (int m = 0; m < 4; ++m) _Pragma("unroll") for (int k = 0; k < 2; ++k) dst[m][k] = *(const PG8_LAS bf16x8*)(lds + PG8_SA(b, h) + aoff + m * 2048 + k * 1024); } while (0)
; #define PG8_LDB(dst, b, h) do { _Pragma("unroll") for (int n = 0; n < 2; ++n) _Pragma("unroll") for (int k = 0; k < 2; ++k) dst[n][k] = *(const PG8_LAS bf16x8*)(lds + PG8_SB(b, h) + boff + n * 2048 + k * 1024); } while (0)
; #define PG8_MMA(ai, bj, At, Bt) do { __builtin_amdgcn_s_setprio(1); _Pragma("unroll") for (int m = 0; m < 4; ++m) _Pragma("unroll") for (int n = 0; n < 2; ++n) _Pragma("unroll") for (int k = 0; k < 2; ++k) \
;         acc[ai][bj][m][n] = __builtin_amdgcn_mfma_f32_16x16x32_bf16(Bt[n][k], At[m][k], acc[ai][bj][m][n], 0, 0, 0); __builtin_amdgcn_s_setprio(0); } while (0)
; #define PG8_WAIT_V(n) asm volatile("s_waitcnt vmcnt(" #n ")" ::: "memory")
; #define PG8_WAIT_L(n) asm volatile("s_waitcnt lgkmcnt(" #n ")" ::: "memory")
; #define PG8_BAR __builtin_amdgcn_s_barrier()
; #define PG8_SCHED __builtin_amdgcn_sched_barrier(0)
; template <class Epi, class Sched, bool ALIGN_EPI = false, bool SP2 = false>
; __device__ __forceinline__ void gemm_phase(PG8_LAS unsigned char* lds, const Gemm g, const Sched& S, const Epi& E) {
;     ...
;             const char* a1 = cA + (size_t)(t + 1) * kstep;
;             const char* a2 = last ? nA : cA + (size_t)(t + 2) * kstep; const char* b2 = last ? nB : cB + (size_t)(t + 2) * kstep;
;             const char* a3 = a2 + kstep; const char* b3 = b2 + kstep;
;             if constexpr (SP2) {
;             PG8_LDB(B0, 0, 0); PG8_LDB(B1, 0, 1); PG8_SCHED; PG8_LDA(At, 0, 0); PG8_STAGE(PG8_SA(1, 1), a1 + hstep, voffA);
;             PG8_WAIT_V(8); PG8_WAIT_L(0); PG8_BAR; PG8_MMA(0, 0, At, B0); PG8_MMA(0, 1, At, B1); PG8_BAR; PG8_SCHED;
;             PG8_LDA(At, 0, 1); PG8_STAGE(PG8_SB(0, 0), b2, voffB); PG8_STAGE(PG8_SB(0, 1), b2 + hstep, voffB); PG8_STAGE(PG8_SA(0, 0), a2, voffA);
;             PG8_WAIT_V(8); PG8_WAIT_L(0); PG8_BAR; PG8_MMA(1, 0, At, B0); PG8_MMA(1, 1, At, B1); PG8_BAR; PG8_SCHED;
.LBB0_1142:
	ds_read_b128 v[80:83], v171
	ds_read_b128 v[84:87], v171 offset:1024
	ds_read_b128 v[88:91], v171 offset:2048
	ds_read_b128 v[92:95], v171 offset:3072
	ds_read_b128 v[164:167], v172
	ds_read_b128 v[176:179], v172 offset:1024
	ds_read_b128 v[180:183], v172 offset:2048
	ds_read_b128 v[184:187], v172 offset:3072
	s_add_u32 s44, s42, 0xfff80080
	s_addc_u32 s45, s43, -1
	s_cmp_eq_u32 s64, 28
	s_cselect_b32 s47, s15, s45
	s_cselect_b32 s46, s60, s44
	s_cselect_b32 s45, s13, s63
	s_cselect_b32 s44, s61, s62
	v_lshl_add_u64 v[220:221], s[42:43], 0, v[156:157]
	s_add_i32 m0, s41, 0xc000
	ds_read_b128 v[188:191], v173
	ds_read_b128 v[192:195], v173 offset:1024
	ds_read_b128 v[196:199], v173 offset:2048
	ds_read_b128 v[200:203], v173 offset:3072
	ds_read_b128 v[204:207], v173 offset:4096
	ds_read_b128 v[208:211], v173 offset:5120
	ds_read_b128 v[212:215], v173 offset:6144
	ds_read_b128 v[216:219], v173 offset:7168
	global_load_lds_dwordx4 v[220:221], off
	v_lshl_add_u64 v[220:221], s[42:43], 0, v[158:159]
	s_add_i32 m0, s41, 0xe000
	s_nop 0
	global_load_lds_dwordx4 v[220:221], off
	s_waitcnt vmcnt(8)
	s_waitcnt lgkmcnt(0)
	s_barrier
	s_setprio 1
	s_waitcnt lgkmcnt(0)
	v_mfma_f32_16x16x32_bf16 v[140:143], v[80:83], v[188:191], v[140:143]
	v_mfma_f32_16x16x32_bf16 v[136:139], v[88:91], v[188:191], v[136:139]
	v_mfma_f32_16x16x32_bf16 v[124:127], v[80:83], v[196:199], v[124:127]
	v_mfma_f32_16x16x32_bf16 v[120:123], v[88:91], v[196:199], v[120:123]
	v_mfma_f32_16x16x32_bf16 v[108:111], v[80:83], v[204:207], v[108:111]
	v_mfma_f32_16x16x32_bf16 v[104:107], v[88:91], v[204:207], v[104:107]
	v_mfma_f32_16x16x32_bf16 v[76:79], v[80:83], v[212:215], v[76:79]
	v_mfma_f32_16x16x32_bf16 v[72:75], v[88:91], v[212:215], v[72:75]
	v_mfma_f32_16x16x32_bf16 v[140:143], v[84:87], v[192:195], v[140:143]
	v_mfma_f32_16x16x32_bf16 v[136:139], v[92:95], v[192:195], v[136:139]
	v_mfma_f32_16x16x32_bf16 v[124:127], v[84:87], v[200:203], v[124:127]
	v_mfma_f32_16x16x32_bf16 v[120:123], v[92:95], v[200:203], v[120:123]
	v_mfma_f32_16x16x32_bf16 v[108:111], v[84:87], v[208:211], v[108:111]
	v_mfma_f32_16x16x32_bf16 v[104:107], v[92:95], v[208:211], v[104:107]
	v_mfma_f32_16x16x32_bf16 v[76:79], v[84:87], v[216:219], v[76:79]
	v_mfma_f32_16x16x32_bf16 v[72:75], v[92:95], v[216:219], v[72:75]
	s_setprio 0
	s_setprio 1
	v_mfma_f32_16x16x32_bf16 v[132:135], v[164:167], v[188:191], v[132:135]
	v_mfma_f32_16x16x32_bf16 v[128:131], v[180:183], v[188:191], v[128:131]
	v_mfma_f32_16x16x32_bf16 v[116:119], v[164:167], v[196:199], v[116:119]
	v_mfma_f32_16x16x32_bf16 v[112:115], v[180:183], v[196:199], v[112:115]
	v_mfma_f32_16x16x32_bf16 v[100:103], v[164:167], v[204:207], v[100:103]
	v_mfma_f32_16x16x32_bf16 v[96:99], v[180:183], v[204:207], v[96:99]
	v_mfma_f32_16x16x32_bf16 v[68:71], v[164:167], v[212:215], v[68:71]
	v_mfma_f32_16x16x32_bf16 v[64:67], v[180:183], v[212:215], v[64:67]
	v_mfma_f32_16x16x32_bf16 v[132:135], v[176:179], v[192:195], v[132:135]
	v_mfma_f32_16x16x32_bf16 v[128:131], v[184:187], v[192:195], v[128:131]
	v_mfma_f32_16x16x32_bf16 v[116:119], v[176:179], v[200:203], v[116:119]
	v_mfma_f32_16x16x32_bf16 v[112:115], v[184:187], v[200:203], v[112:115]
	v_mfma_f32_16x16x32_bf16 v[100:103], v[176:179], v[208:211], v[100:103]
	v_mfma_f32_16x16x32_bf16 v[96:99], v[184:187], v[208:211], v[96:99]
	v_mfma_f32_16x16x32_bf16 v[68:71], v[176:179], v[216:219], v[68:71]
	s_barrier
	v_mfma_f32_16x16x32_bf16 v[64:67], v[184:187], v[216:219], v[64:67]
	s_setprio 0
	s_add_i32 s65, s56, s33
	v_lshl_add_u64 v[220:221], s[44:45], 0, v[148:149]
	s_mov_b32 m0, s65
	ds_read_b128 v[188:191], v173 offset:16384
	ds_read_b128 v[192:195], v173 offset:17408
	ds_read_b128 v[196:199], v173 offset:18432
	ds_read_b128 v[200:203], v173 offset:19456
	ds_read_b128 v[204:207], v173 offset:20480
	ds_read_b128 v[208:211], v173 offset:21504
	ds_read_b128 v[212:215], v173 offset:22528
	ds_read_b128 v[216:219], v173 offset:23552
	global_load_lds_dwordx4 v[220:221], off
	s_add_i32 m0, s65, 0x2000
	s_add_u32 s66, s44, 0x80000
	v_lshl_add_u64 v[222:223], s[44:45], 0, v[152:153]
	s_addc_u32 s67, s45, 0
	s_add_i32 s65, s57, s33
	global_load_lds_dwordx4 v[222:223], off
	v_lshl_add_u64 v[224:225], s[66:67], 0, v[148:149]
	s_mov_b32 m0, s65
	v_lshl_add_u64 v[226:227], s[46:47], 0, v[150:151]
	global_load_lds_dwordx4 v[224:225], off
	v_lshl_add_u64 v[224:225], s[66:67], 0, v[152:153]
	s_add_i32 m0, s65, 0x2000
	s_nop 0
	global_load_lds_dwordx4 v[224:225], off
	v_lshl_add_u64 v[224:225], s[46:47], 0, v[144:145]
	s_mov_b32 m0, s41
	s_nop 0
	global_load_lds_dwordx4 v[224:225], off
	s_mov_b32 m0, s48
	s_nop 0
	global_load_lds_dwordx4 v[226:227], off
	s_waitcnt vmcnt(8)
	s_waitcnt lgkmcnt(0)
	s_barrier
; #define PG8_STAGE(bufoff, gbase, voff) do { _Pragma("unroll") for (int _i = 0; _i < 2; ++_i) \
;         __builtin_amdgcn_global_load_lds((const unsigned*)((const char*)(gbase) + (voff)[_i]), (PG8_LAS unsigned*)(lds + (bufoff) + ldsw + _i * 8192), 16, 0, 0); } while (0)
; #define PG8_LDA(dst, b, h) do { _Pragma("unroll") for (int m = 0; m < 4; ++m) _Pragma("unroll") for (int k = 0; k < 2; ++k) dst[m][k] = *(const PG8_LAS bf16x8*)(lds + PG8_SA(b, h) + aoff + m * 2048 + k * 1024); } while (0)
; #define PG8_LDB(dst, b, h) do { _Pragma("unroll") for (int n = 0; n < 2; ++n) _Pragma("unroll") for (int k = 0; k < 2; ++k) dst[n][k] = *(const PG8_LAS bf16x8*)(lds + PG8_SB(b, h) + boff + n * 2048 + k * 1024); } while (0)
; #define PG8_MMA(ai, bj, At, Bt) do { __builtin_amdgcn_s_setprio(1); _Pragma("unroll") for (int m = 0; m < 4; ++m) _Pragma("unroll") for (int n = 0; n < 2; ++n) _Pragma("unroll") for (int k = 0; k < 2; ++k) \
;         acc[ai][bj][m][n] = __builtin_amdgcn_mfma_f32_16x16x32_bf16(Bt[n][k], At[m][k], acc[ai][bj][m][n], 0, 0, 0); __builtin_amdgcn_s_setprio(0); } while (0)
; #define PG8_WAIT_V(n) asm volatile("s_waitcnt vmcnt(" #n ")" ::: "memory")
; #define PG8_WAIT_L(n) asm volatile("s_waitcnt lgkmcnt(" #n ")" ::: "memory")
; #define PG8_BAR __builtin_amdgcn_s_barrier()
; #define PG8_SCHED __builtin_amdgcn_sched_barrier(0)
; template <class Epi, class Sched, bool ALIGN_EPI = false, bool SP2 = false>
; __device__ __forceinline__ void gemm_phase(PG8_LAS unsigned char* lds, const Gemm g, const Sched& S, const Epi& E) {
;     ...
;             PG8_WAIT_V(8); PG8_WAIT_L(0); PG8_BAR; PG8_MMA(1, 0, At, B0); PG8_MMA(1, 1, At, B1); PG8_BAR; PG8_SCHED;
;             PG8_LDB(B0, 1, 0); PG8_LDB(B1, 1, 1); PG8_SCHED; PG8_LDA(At, 1, 0); PG8_STAGE(PG8_SA(0, 1), a2 + hstep, voffA);
;             PG8_WAIT_V(8); PG8_WAIT_L(0); PG8_BAR; PG8_MMA(0, 0, At, B0); PG8_MMA(0, 1, At, B1); PG8_BAR; PG8_SCHED;
	s_setprio 1
	s_waitcnt lgkmcnt(0)
	v_mfma_f32_16x16x32_bf16 v[60:63], v[80:83], v[188:191], v[60:63]
	v_mfma_f32_16x16x32_bf16 v[56:59], v[88:91], v[188:191], v[56:59]
	v_mfma_f32_16x16x32_bf16 v[44:47], v[80:83], v[196:199], v[44:47]
	v_mfma_f32_16x16x32_bf16 v[40:43], v[88:91], v[196:199], v[40:43]
	v_mfma_f32_16x16x32_bf16 v[28:31], v[80:83], v[204:207], v[28:31]
	v_mfma_f32_16x16x32_bf16 v[24:27], v[88:91], v[204:207], v[24:27]
	v_mfma_f32_16x16x32_bf16 v[12:15], v[80:83], v[212:215], v[12:15]
	v_mfma_f32_16x16x32_bf16 v[8:11], v[88:91], v[212:215], v[8:11]
	v_mfma_f32_16x16x32_bf16 v[60:63], v[84:87], v[192:195], v[60:63]
	v_mfma_f32_16x16x32_bf16 v[56:59], v[92:95], v[192:195], v[56:59]
	v_mfma_f32_16x16x32_bf16 v[44:47], v[84:87], v[200:203], v[44:47]
	v_mfma_f32_16x16x32_bf16 v[40:43], v[92:95], v[200:203], v[40:43]
	v_mfma_f32_16x16x32_bf16 v[28:31], v[84:87], v[208:211], v[28:31]
	v_mfma_f32_16x16x32_bf16 v[24:27], v[92:95], v[208:211], v[24:27]
	v_mfma_f32_16x16x32_bf16 v[12:15], v[84:87], v[216:219], v[12:15]
	v_mfma_f32_16x16x32_bf16 v[8:11], v[92:95], v[216:219], v[8:11]
	s_setprio 0
	s_setprio 1
	v_mfma_f32_16x16x32_bf16 v[52:55], v[164:167], v[188:191], v[52:55]
	v_mfma_f32_16x16x32_bf16 v[48:51], v[180:183], v[188:191], v[48:51]
	v_mfma_f32_16x16x32_bf16 v[36:39], v[164:167], v[196:199], v[36:39]
	v_mfma_f32_16x16x32_bf16 v[32:35], v[180:183], v[196:199], v[32:35]
	v_mfma_f32_16x16x32_bf16 v[20:23], v[164:167], v[204:207], v[20:23]
	v_mfma_f32_16x16x32_bf16 v[16:19], v[180:183], v[204:207], v[16:19]
	v_mfma_f32_16x16x32_bf16 v[4:7], v[164:167], v[212:215], v[4:7]
	v_mfma_f32_16x16x32_bf16 v[0:3], v[180:183], v[212:215], v[0:3]
	v_mfma_f32_16x16x32_bf16 v[52:55], v[176:179], v[192:195], v[52:55]
	v_mfma_f32_16x16x32_bf16 v[48:51], v[184:187], v[192:195], v[48:51]
	v_mfma_f32_16x16x32_bf16 v[36:39], v[176:179], v[200:203], v[36:39]
	v_mfma_f32_16x16x32_bf16 v[32:35], v[184:187], v[200:203], v[32:35]
	v_mfma_f32_16x16x32_bf16 v[20:23], v[176:179], v[208:211], v[20:23]
	v_mfma_f32_16x16x32_bf16 v[16:19], v[184:187], v[208:211], v[16:19]
	v_mfma_f32_16x16x32_bf16 v[4:7], v[176:179], v[216:219], v[4:7]
	s_barrier
	v_mfma_f32_16x16x32_bf16 v[0:3], v[184:187], v[216:219], v[0:3]
	s_setprio 0
	s_add_i32 s65, 0, 0x18000
	s_add_i32 s66, 0, 0x1c000
	v_add_u32_e32 v92, s65, v169
	v_add_u32_e32 v184, s66, v169
	ds_read_b128 v[80:83], v92
	ds_read_b128 v[84:87], v92 offset:1024
	ds_read_b128 v[88:91], v92 offset:2048
	ds_read_b128 v[92:95], v92 offset:3072
	ds_read_b128 v[164:167], v184
	ds_read_b128 v[176:179], v184 offset:1024
	ds_read_b128 v[180:183], v184 offset:2048
	ds_read_b128 v[184:187], v184 offset:3072
	s_add_u32 s46, s46, 0x80000
	s_addc_u32 s47, s47, 0
	s_mov_b32 m0, s49
	v_lshl_add_u64 v[228:229], s[46:47], 0, v[144:145]
	ds_read_b128 v[188:191], v173 offset:32768
	ds_read_b128 v[192:195], v173 offset:33792
	ds_read_b128 v[196:199], v173 offset:34816
	ds_read_b128 v[200:203], v173 offset:35840
	ds_read_b128 v[204:207], v173 offset:36864
	ds_read_b128 v[208:211], v173 offset:37888
	ds_read_b128 v[212:215], v173 offset:38912
	ds_read_b128 v[216:219], v173 offset:39936
	global_load_lds_dwordx4 v[228:229], off
	v_lshl_add_u64 v[228:229], s[46:47], 0, v[150:151]
	s_mov_b32 m0, s50
	s_nop 0
	global_load_lds_dwordx4 v[228:229], off
	s_waitcnt vmcnt(8)
	s_waitcnt lgkmcnt(0)
	s_barrier
	s_setprio 1
	s_waitcnt lgkmcnt(0)
	v_mfma_f32_16x16x32_bf16 v[140:143], v[80:83], v[188:191], v[140:143]
	v_mfma_f32_16x16x32_bf16 v[136:139], v[88:91], v[188:191], v[136:139]
	v_mfma_f32_16x16x32_bf16 v[124:127], v[80:83], v[196:199], v[124:127]
	v_mfma_f32_16x16x32_bf16 v[120:123], v[88:91], v[196:199], v[120:123]
	v_mfma_f32_16x16x32_bf16 v[108:111], v[80:83], v[204:207], v[108:111]
	v_mfma_f32_16x16x32_bf16 v[104:107], v[88:91], v[204:207], v[104:107]
	v_mfma_f32_16x16x32_bf16 v[76:79], v[80:83], v[212:215], v[76:79]
	v_mfma_f32_16x16x32_bf16 v[72:75], v[88:91], v[212:215], v[72:75]
	v_mfma_f32_16x16x32_bf16 v[140:143], v[84:87], v[192:195], v[140:143]
	v_mfma_f32_16x16x32_bf16 v[136:139], v[92:95], v[192:195], v[136:139]
	v_mfma_f32_16x16x32_bf16 v[124:127], v[84:87], v[200:203], v[124:127]
	v_mfma_f32_16x16x32_bf16 v[120:123], v[92:95], v[200:203], v[120:123]
	v_mfma_f32_16x16x32_bf16 v[108:111], v[84:87], v[208:211], v[108:111]
	v_mfma_f32_16x16x32_bf16 v[104:107], v[92:95], v[208:211], v[104:107]
	v_mfma_f32_16x16x32_bf16 v[76:79], v[84:87], v[216:219], v[76:79]
	v_mfma_f32_16x16x32_bf16 v[72:75], v[92:95], v[216:219], v[72:75]
	s_setprio 0
	s_setprio 1
	v_mfma_f32_16x16x32_bf16 v[132:135], v[164:167], v[188:191], v[132:135]
	v_mfma_f32_16x16x32_bf16 v[128:131], v[180:183], v[188:191], v[128:131]
	v_mfma_f32_16x16x32_bf16 v[116:119], v[164:167], v[196:199], v[116:119]
	v_mfma_f32_16x16x32_bf16 v[112:115], v[180:183], v[196:199], v[112:115]
	v_mfma_f32_16x16x32_bf16 v[100:103], v[164:167], v[204:207], v[100:103]
	v_mfma_f32_16x16x32_bf16 v[96:99], v[180:183], v[204:207], v[96:99]
	v_mfma_f32_16x16x32_bf16 v[68:71], v[164:167], v[212:215], v[68:71]
	v_mfma_f32_16x16x32_bf16 v[64:67], v[180:183], v[212:215], v[64:67]
	v_mfma_f32_16x16x32_bf16 v[132:135], v[176:179], v[192:195], v[132:135]
	v_mfma_f32_16x16x32_bf16 v[128:131], v[184:187], v[192:195], v[128:131]
	v_mfma_f32_16x16x32_bf16 v[116:119], v[176:179], v[200:203], v[116:119]
	v_mfma_f32_16x16x32_bf16 v[112:115], v[184:187], v[200:203], v[112:115]
	v_mfma_f32_16x16x32_bf16 v[100:103], v[176:179], v[208:211], v[100:103]
	v_mfma_f32_16x16x32_bf16 v[96:99], v[184:187], v[208:211], v[96:99]
	v_mfma_f32_16x16x32_bf16 v[68:71], v[176:179], v[216:219], v[68:71]
	s_barrier
; #define PG8_STAGE(bufoff, gbase, voff) do { _Pragma("unroll") for (int _i = 0; _i < 2; ++_i) \
;         __builtin_amdgcn_global_load_lds((const unsigned*)((const char*)(gbase) + (voff)[_i]), (PG8_LAS unsigned*)(lds + (bufoff) + ldsw + _i * 8192), 16, 0, 0); } while (0)
; #define PG8_LDA(dst, b, h) do { _Pragma("unroll") for (int m = 0; m < 4; ++m) _Pragma("unroll") for (int k = 0; k < 2; ++k) dst[m][k] = *(const PG8_LAS bf16x8*)(lds + PG8_SA(b, h) + aoff + m * 2048 + k * 1024); } while (0)
; #define PG8_MMA(ai, bj, At, Bt) do { __builtin_amdgcn_s_setprio(1); _Pragma("unroll") for (int m = 0; m < 4; ++m) _Pragma("unroll") for (int n = 0; n < 2; ++n) _Pragma("unroll") for (int k = 0; k < 2; ++k) \
;         acc[ai][bj][m][n] = __builtin_amdgcn_mfma_f32_16x16x32_bf16(Bt[n][k], At[m][k], acc[ai][bj][m][n], 0, 0, 0); __builtin_amdgcn_s_setprio(0); } while (0)
; #define PG8_WAIT_V(n) asm volatile("s_waitcnt vmcnt(" #n ")" ::: "memory")
; #define PG8_WAIT_L(n) asm volatile("s_waitcnt lgkmcnt(" #n ")" ::: "memory")
; #define PG8_BAR __builtin_amdgcn_s_barrier()
; #define PG8_SCHED __builtin_amdgcn_sched_barrier(0)
; template <class Epi, class Sched, bool ALIGN_EPI = false, bool SP2 = false>
; __device__ __forceinline__ void gemm_phase(PG8_LAS unsigned char* lds, const Gemm g, const Sched& S, const Epi& E) {
;     ...
;             PG8_WAIT_V(8); PG8_WAIT_L(0); PG8_BAR; PG8_MMA(0, 0, At, B0); PG8_MMA(0, 1, At, B1); PG8_BAR; PG8_SCHED;
;             PG8_LDA(At, 1, 1); PG8_STAGE(PG8_SB(1, 0), b3, voffB); PG8_STAGE(PG8_SB(1, 1), b3 + hstep, voffB); PG8_STAGE(PG8_SA(1, 0), a3, voffA);
;             PG8_WAIT_V(8); PG8_WAIT_L(0); PG8_BAR; PG8_MMA(1, 0, At, B0); PG8_MMA(1, 1, At, B1); PG8_BAR; PG8_SCHED;
;     ...
;         if constexpr (ALIGN_EPI) { if (wr == 0) PG8_BAR; }
	v_mfma_f32_16x16x32_bf16 v[64:67], v[184:187], v[216:219], v[64:67]
	s_setprio 0
	s_add_i32 s46, s65, s33
	v_lshl_add_u64 v[220:221], v[220:221], 0, s[8:9]
	s_mov_b32 m0, s46
	ds_read_b128 v[188:191], v173 offset:49152
	ds_read_b128 v[192:195], v173 offset:50176
	ds_read_b128 v[196:199], v173 offset:51200
	ds_read_b128 v[200:203], v173 offset:52224
	ds_read_b128 v[204:207], v173 offset:53248
	ds_read_b128 v[208:211], v173 offset:54272
	ds_read_b128 v[212:215], v173 offset:55296
	ds_read_b128 v[216:219], v173 offset:56320
	global_load_lds_dwordx4 v[220:221], off
	s_add_i32 m0, s46, 0x2000
	s_add_u32 s44, s44, 0x80080
	v_lshl_add_u64 v[220:221], v[222:223], 0, s[8:9]
	s_addc_u32 s45, s45, 0
	s_add_i32 s46, s66, s33
	global_load_lds_dwordx4 v[220:221], off
	v_lshl_add_u64 v[220:221], s[44:45], 0, v[148:149]
	s_mov_b32 m0, s46
	s_nop 0
	global_load_lds_dwordx4 v[220:221], off
	v_lshl_add_u64 v[220:221], s[44:45], 0, v[152:153]
	s_add_i32 m0, s46, 0x2000
	s_nop 0
	global_load_lds_dwordx4 v[220:221], off
	v_lshl_add_u64 v[220:221], v[224:225], 0, s[8:9]
	s_mov_b32 m0, s52
	s_nop 0
	global_load_lds_dwordx4 v[220:221], off
	v_lshl_add_u64 v[220:221], v[226:227], 0, s[8:9]
	s_mov_b32 m0, s53
	s_nop 0
	global_load_lds_dwordx4 v[220:221], off
	s_waitcnt vmcnt(8)
	s_waitcnt lgkmcnt(0)
	s_barrier
	s_setprio 1
	s_waitcnt lgkmcnt(0)
	v_mfma_f32_16x16x32_bf16 v[60:63], v[80:83], v[188:191], v[60:63]
	v_mfma_f32_16x16x32_bf16 v[56:59], v[88:91], v[188:191], v[56:59]
	v_mfma_f32_16x16x32_bf16 v[44:47], v[80:83], v[196:199], v[44:47]
	v_mfma_f32_16x16x32_bf16 v[40:43], v[88:91], v[196:199], v[40:43]
	v_mfma_f32_16x16x32_bf16 v[28:31], v[80:83], v[204:207], v[28:31]
	v_mfma_f32_16x16x32_bf16 v[24:27], v[88:91], v[204:207], v[24:27]
	v_mfma_f32_16x16x32_bf16 v[12:15], v[80:83], v[212:215], v[12:15]
	v_mfma_f32_16x16x32_bf16 v[8:11], v[88:91], v[212:215], v[8:11]
	v_mfma_f32_16x16x32_bf16 v[60:63], v[84:87], v[192:195], v[60:63]
	v_mfma_f32_16x16x32_bf16 v[56:59], v[92:95], v[192:195], v[56:59]
	v_mfma_f32_16x16x32_bf16 v[44:47], v[84:87], v[200:203], v[44:47]
	v_mfma_f32_16x16x32_bf16 v[40:43], v[92:95], v[200:203], v[40:43]
	v_mfma_f32_16x16x32_bf16 v[28:31], v[84:87], v[208:211], v[28:31]
	v_mfma_f32_16x16x32_bf16 v[24:27], v[92:95], v[208:211], v[24:27]
	v_mfma_f32_16x16x32_bf16 v[12:15], v[84:87], v[216:219], v[12:15]
	v_mfma_f32_16x16x32_bf16 v[8:11], v[92:95], v[216:219], v[8:11]
	s_setprio 0
	s_setprio 1
	v_mfma_f32_16x16x32_bf16 v[52:55], v[164:167], v[188:191], v[52:55]
	v_mfma_f32_16x16x32_bf16 v[48:51], v[180:183], v[188:191], v[48:51]
	v_mfma_f32_16x16x32_bf16 v[36:39], v[164:167], v[196:199], v[36:39]
	v_mfma_f32_16x16x32_bf16 v[32:35], v[180:183], v[196:199], v[32:35]
	v_mfma_f32_16x16x32_bf16 v[20:23], v[164:167], v[204:207], v[20:23]
	v_mfma_f32_16x16x32_bf16 v[16:19], v[180:183], v[204:207], v[16:19]
	v_mfma_f32_16x16x32_bf16 v[4:7], v[164:167], v[212:215], v[4:7]
	v_mfma_f32_16x16x32_bf16 v[0:3], v[180:183], v[212:215], v[0:3]
	v_mfma_f32_16x16x32_bf16 v[52:55], v[176:179], v[192:195], v[52:55]
	v_mfma_f32_16x16x32_bf16 v[48:51], v[184:187], v[192:195], v[48:51]
	v_mfma_f32_16x16x32_bf16 v[36:39], v[176:179], v[200:203], v[36:39]
	v_mfma_f32_16x16x32_bf16 v[32:35], v[184:187], v[200:203], v[32:35]
	v_mfma_f32_16x16x32_bf16 v[20:23], v[176:179], v[208:211], v[20:23]
	v_mfma_f32_16x16x32_bf16 v[16:19], v[184:187], v[208:211], v[16:19]
	v_mfma_f32_16x16x32_bf16 v[4:7], v[176:179], v[216:219], v[4:7]
	s_barrier
	v_mfma_f32_16x16x32_bf16 v[0:3], v[184:187], v[216:219], v[0:3]
	s_setprio 0
	s_add_i32 s64, s64, 2
	s_add_u32 s42, s42, 0x100
	s_addc_u32 s43, s43, 0
	s_add_u32 s62, s62, 0x100
	s_addc_u32 s63, s63, 0
	s_cmp_gt_u32 s64, 29
	s_cbranch_scc0 .LBB0_1142
	s_and_b64 vcc, exec, s[10:11]
	s_cbranch_vccz .LBB0_1145
	s_barrier

; #define PG8_STAGE(bufoff, gbase, voff) do { _Pragma("unroll") for (int _i = 0; _i < 2; ++_i) \
;         __builtin_amdgcn_global_load_lds((const unsigned*)((const char*)(gbase) + (voff)[_i]), (PG8_LAS unsigned*)(lds + (bufoff) + ldsw + _i * 8192), 16, 0, 0); } while (0)
; #define PG8_LDA(dst, b, h) do { _Pragma("unroll") for (int m = 0; m < 4; ++m) _Pragma("unroll") for (int k = 0; k < 2; ++k) dst[m][k] = *(const PG8_LAS bf16x8*)(lds + PG8_SA(b, h) + aoff + m * 2048 + k * 1024); } while (0)
; #define PG8_LDB(dst, b, h) do { _Pragma("unroll") for (int n = 0; n < 2; ++n) _Pragma("unroll") for (int k = 0; k < 2; ++k) dst[n][k] = *(const PG8_LAS bf16x8*)(lds + PG8_SB(b, h) + boff + n * 2048 + k * 1024); } while (0)
; #define PG8_MMA(ai, bj, At, Bt) do { __builtin_amdgcn_s_setprio(1); _Pragma("unroll") for (int m = 0; m < 4; ++m) _Pragma("unroll") for (int n = 0; n < 2; ++n) _Pragma("unroll") for (int k = 0; k < 2; ++k) \
;         acc[ai][bj][m][n] = __builtin_amdgcn_mfma_f32_16x16x32_bf16(Bt[n][k], At[m][k], acc[ai][bj][m][n], 0, 0, 0); __builtin_amdgcn_s_setprio(0); } while (0)
; #define PG8_WAIT_V(n) asm volatile("s_waitcnt vmcnt(" #n ")" ::: "memory")
; #define PG8_WAIT_L(n) asm volatile("s_waitcnt lgkmcnt(" #n ")" ::: "memory")
; #define PG8_BAR __builtin_amdgcn_s_barrier()
; #define PG8_SCHED __builtin_amdgcn_sched_barrier(0)
; template <class Epi, class Sched, bool ALIGN_EPI = false, bool SP2 = false>
; __device__ __forceinline__ void gemm_phase(PG8_LAS unsigned char* lds, const Gemm g, const Sched& S, const Epi& E) {
;     ...
;             const char* a1 = cA + (size_t)(t + 1) * kstep;
;             const char* a2 = last ? nA : cA + (size_t)(t + 2) * kstep; const char* b2 = last ? nB : cB + (size_t)(t + 2) * kstep;
;             const char* a3 = a2 + kstep; const char* b3 = b2 + kstep;
;             if constexpr (SP2) {
;             PG8_LDB(B0, 0, 0); PG8_LDB(B1, 0, 1); PG8_SCHED; PG8_LDA(At, 0, 0); PG8_STAGE(PG8_SA(1, 1), a1 + hstep, voffA);
;             PG8_WAIT_V(8); PG8_WAIT_L(0); PG8_BAR; PG8_MMA(0, 0, At, B0); PG8_MMA(0, 1, At, B1); PG8_BAR; PG8_SCHED;
;             PG8_LDA(At, 0, 1); PG8_STAGE(PG8_SB(0, 0), b2, voffB); PG8_STAGE(PG8_SB(0, 1), b2 + hstep, voffB); PG8_STAGE(PG8_SA(0, 0), a2, voffA);
;             PG8_WAIT_V(8); PG8_WAIT_L(0); PG8_BAR; PG8_MMA(1, 0, At, B0); PG8_MMA(1, 1, At, B1); PG8_BAR; PG8_SCHED;
.LBB0_1219:
	ds_read_b128 v[128:131], v167
	ds_read_b128 v[132:135], v167 offset:1024
	ds_read_b128 v[154:157], v167 offset:2048
	ds_read_b128 v[158:161], v167 offset:3072
	ds_read_b128 v[170:173], v168
	ds_read_b128 v[174:177], v168 offset:1024
	ds_read_b128 v[178:181], v168 offset:2048
	ds_read_b128 v[182:185], v168 offset:3072
	s_add_u32 s42, s40, 0xffe00080
	s_addc_u32 s43, s41, -1
	s_cmpk_eq_i32 s63, 0x7c
	s_cselect_b32 s45, s15, s43
	s_cselect_b32 s44, s59, s42
	s_cselect_b32 s43, s13, s62
	s_cselect_b32 s42, s60, s61
	v_lshl_add_u64 v[162:163], s[40:41], 0, v[144:145]
	s_add_i32 m0, s39, 0xc000
	ds_read_b128 v[186:189], v169
	ds_read_b128 v[190:193], v169 offset:1024
	ds_read_b128 v[194:197], v169 offset:2048
	ds_read_b128 v[198:201], v169 offset:3072
	ds_read_b128 v[202:205], v169 offset:4096
	ds_read_b128 v[206:209], v169 offset:5120
	ds_read_b128 v[210:213], v169 offset:6144
	ds_read_b128 v[214:217], v169 offset:7168
	global_load_lds_dwordx4 v[162:163], off
	v_lshl_add_u64 v[162:163], s[40:41], 0, v[148:149]
	s_add_i32 m0, s39, 0xe000
	s_nop 0
	global_load_lds_dwordx4 v[162:163], off
	s_waitcnt vmcnt(8)
	s_waitcnt lgkmcnt(0)
	s_barrier
	s_setprio 1
	s_waitcnt lgkmcnt(0)
	v_mfma_f32_16x16x32_bf16 v[124:127], v[128:131], v[186:189], v[124:127]
	v_mfma_f32_16x16x32_bf16 v[120:123], v[154:157], v[186:189], v[120:123]
	v_mfma_f32_16x16x32_bf16 v[116:119], v[128:131], v[194:197], v[116:119]
	v_mfma_f32_16x16x32_bf16 v[112:115], v[154:157], v[194:197], v[112:115]
	v_mfma_f32_16x16x32_bf16 v[108:111], v[128:131], v[202:205], v[108:111]
	v_mfma_f32_16x16x32_bf16 v[104:107], v[154:157], v[202:205], v[104:107]
	v_mfma_f32_16x16x32_bf16 v[100:103], v[128:131], v[210:213], v[100:103]
	v_mfma_f32_16x16x32_bf16 v[96:99], v[154:157], v[210:213], v[96:99]
	v_mfma_f32_16x16x32_bf16 v[124:127], v[132:135], v[190:193], v[124:127]
	v_mfma_f32_16x16x32_bf16 v[120:123], v[158:161], v[190:193], v[120:123]
	v_mfma_f32_16x16x32_bf16 v[116:119], v[132:135], v[198:201], v[116:119]
	v_mfma_f32_16x16x32_bf16 v[112:115], v[158:161], v[198:201], v[112:115]
	v_mfma_f32_16x16x32_bf16 v[108:111], v[132:135], v[206:209], v[108:111]
	v_mfma_f32_16x16x32_bf16 v[104:107], v[158:161], v[206:209], v[104:107]
	v_mfma_f32_16x16x32_bf16 v[100:103], v[132:135], v[214:217], v[100:103]
	v_mfma_f32_16x16x32_bf16 v[96:99], v[158:161], v[214:217], v[96:99]
	s_setprio 0
	s_setprio 1
	v_mfma_f32_16x16x32_bf16 v[68:71], v[170:173], v[186:189], v[68:71]
	v_mfma_f32_16x16x32_bf16 v[60:63], v[178:181], v[186:189], v[60:63]
	v_mfma_f32_16x16x32_bf16 v[52:55], v[170:173], v[194:197], v[52:55]
	v_mfma_f32_16x16x32_bf16 v[48:51], v[178:181], v[194:197], v[48:51]
	v_mfma_f32_16x16x32_bf16 v[44:47], v[170:173], v[202:205], v[44:47]
	v_mfma_f32_16x16x32_bf16 v[40:43], v[178:181], v[202:205], v[40:43]
	v_mfma_f32_16x16x32_bf16 v[36:39], v[170:173], v[210:213], v[36:39]
	v_mfma_f32_16x16x32_bf16 v[32:35], v[178:181], v[210:213], v[32:35]
	v_mfma_f32_16x16x32_bf16 v[68:71], v[174:177], v[190:193], v[68:71]
	v_mfma_f32_16x16x32_bf16 v[60:63], v[182:185], v[190:193], v[60:63]
	v_mfma_f32_16x16x32_bf16 v[52:55], v[174:177], v[198:201], v[52:55]
	v_mfma_f32_16x16x32_bf16 v[48:51], v[182:185], v[198:201], v[48:51]
	v_mfma_f32_16x16x32_bf16 v[44:47], v[174:177], v[206:209], v[44:47]
	v_mfma_f32_16x16x32_bf16 v[40:43], v[182:185], v[206:209], v[40:43]
	v_mfma_f32_16x16x32_bf16 v[36:39], v[174:177], v[214:217], v[36:39]
	s_barrier
	v_mfma_f32_16x16x32_bf16 v[32:35], v[182:185], v[214:217], v[32:35]
	s_setprio 0
	s_add_i32 s64, s56, s33
	v_lshl_add_u64 v[162:163], s[42:43], 0, v[138:139]
	s_mov_b32 m0, s64
	ds_read_b128 v[186:189], v169 offset:16384
	ds_read_b128 v[190:193], v169 offset:17408
	ds_read_b128 v[194:197], v169 offset:18432
	ds_read_b128 v[198:201], v169 offset:19456
	ds_read_b128 v[202:205], v169 offset:20480
	ds_read_b128 v[206:209], v169 offset:21504
	ds_read_b128 v[210:213], v169 offset:22528
	ds_read_b128 v[214:217], v169 offset:23552
	global_load_lds_dwordx4 v[162:163], off
	s_add_i32 m0, s64, 0x2000
	s_add_u32 s64, s42, 0x200000
	v_lshl_add_u64 v[218:219], s[42:43], 0, v[142:143]
	s_addc_u32 s65, s43, 0
	s_add_i32 s66, s57, s33
	global_load_lds_dwordx4 v[218:219], off
	v_lshl_add_u64 v[220:221], s[64:65], 0, v[138:139]
	s_mov_b32 m0, s66
	v_lshl_add_u64 v[222:223], s[44:45], 0, v[140:141]
	global_load_lds_dwordx4 v[220:221], off
	v_lshl_add_u64 v[220:221], s[64:65], 0, v[142:143]
	s_add_i32 m0, s66, 0x2000
	s_nop 0
	global_load_lds_dwordx4 v[220:221], off
	v_lshl_add_u64 v[220:221], s[44:45], 0, v[136:137]
	s_mov_b32 m0, s39
	s_nop 0
	global_load_lds_dwordx4 v[220:221], off
	s_mov_b32 m0, s46
	s_nop 0
	global_load_lds_dwordx4 v[222:223], off
	s_waitcnt vmcnt(8)
	s_waitcnt lgkmcnt(0)
	s_barrier
; #define PG8_STAGE(bufoff, gbase, voff) do { _Pragma("unroll") for (int _i = 0; _i < 2; ++_i) \
;         __builtin_amdgcn_global_load_lds((const unsigned*)((const char*)(gbase) + (voff)[_i]), (PG8_LAS unsigned*)(lds + (bufoff) + ldsw + _i * 8192), 16, 0, 0); } while (0)
; #define PG8_LDA(dst, b, h) do { _Pragma("unroll") for (int m = 0; m < 4; ++m) _Pragma("unroll") for (int k = 0; k < 2; ++k) dst[m][k] = *(const PG8_LAS bf16x8*)(lds + PG8_SA(b, h) + aoff + m * 2048 + k * 1024); } while (0)
; #define PG8_LDB(dst, b, h) do { _Pragma("unroll") for (int n = 0; n < 2; ++n) _Pragma("unroll") for (int k = 0; k < 2; ++k) dst[n][k] = *(const PG8_LAS bf16x8*)(lds + PG8_SB(b, h) + boff + n * 2048 + k * 1024); } while (0)
; #define PG8_MMA(ai, bj, At, Bt) do { __builtin_amdgcn_s_setprio(1); _Pragma("unroll") for (int m = 0; m < 4; ++m) _Pragma("unroll") for (int n = 0; n < 2; ++n) _Pragma("unroll") for (int k = 0; k < 2; ++k) \
;         acc[ai][bj][m][n] = __builtin_amdgcn_mfma_f32_16x16x32_bf16(Bt[n][k], At[m][k], acc[ai][bj][m][n], 0, 0, 0); __builtin_amdgcn_s_setprio(0); } while (0)
; #define PG8_WAIT_V(n) asm volatile("s_waitcnt vmcnt(" #n ")" ::: "memory")
; #define PG8_WAIT_L(n) asm volatile("s_waitcnt lgkmcnt(" #n ")" ::: "memory")
; #define PG8_BAR __builtin_amdgcn_s_barrier()
; #define PG8_SCHED __builtin_amdgcn_sched_barrier(0)
; template <class Epi, class Sched, bool ALIGN_EPI = false, bool SP2 = false>
; __device__ __forceinline__ void gemm_phase(PG8_LAS unsigned char* lds, const Gemm g, const Sched& S, const Epi& E) {
;     ...
;             PG8_WAIT_V(8); PG8_WAIT_L(0); PG8_BAR; PG8_MMA(1, 0, At, B0); PG8_MMA(1, 1, At, B1); PG8_BAR; PG8_SCHED;
;             PG8_LDB(B0, 1, 0); PG8_LDB(B1, 1, 1); PG8_SCHED; PG8_LDA(At, 1, 0); PG8_STAGE(PG8_SA(0, 1), a2 + hstep, voffA);
;             PG8_WAIT_V(8); PG8_WAIT_L(0); PG8_BAR; PG8_MMA(0, 0, At, B0); PG8_MMA(0, 1, At, B1); PG8_BAR; PG8_SCHED;
	s_setprio 1
	s_waitcnt lgkmcnt(0)
	v_mfma_f32_16x16x32_bf16 v[92:95], v[128:131], v[186:189], v[92:95]
	v_mfma_f32_16x16x32_bf16 v[88:91], v[154:157], v[186:189], v[88:91]
	v_mfma_f32_16x16x32_bf16 v[84:87], v[128:131], v[194:197], v[84:87]
	v_mfma_f32_16x16x32_bf16 v[80:83], v[154:157], v[194:197], v[80:83]
	v_mfma_f32_16x16x32_bf16 v[76:79], v[128:131], v[202:205], v[76:79]
	v_mfma_f32_16x16x32_bf16 v[72:75], v[154:157], v[202:205], v[72:75]
	v_mfma_f32_16x16x32_bf16 v[64:67], v[128:131], v[210:213], v[64:67]
	v_mfma_f32_16x16x32_bf16 v[56:59], v[154:157], v[210:213], v[56:59]
	v_mfma_f32_16x16x32_bf16 v[92:95], v[132:135], v[190:193], v[92:95]
	v_mfma_f32_16x16x32_bf16 v[88:91], v[158:161], v[190:193], v[88:91]
	v_mfma_f32_16x16x32_bf16 v[84:87], v[132:135], v[198:201], v[84:87]
	v_mfma_f32_16x16x32_bf16 v[80:83], v[158:161], v[198:201], v[80:83]
	v_mfma_f32_16x16x32_bf16 v[76:79], v[132:135], v[206:209], v[76:79]
	v_mfma_f32_16x16x32_bf16 v[72:75], v[158:161], v[206:209], v[72:75]
	v_mfma_f32_16x16x32_bf16 v[64:67], v[132:135], v[214:217], v[64:67]
	v_mfma_f32_16x16x32_bf16 v[56:59], v[158:161], v[214:217], v[56:59]
	s_setprio 0
	s_setprio 1
	v_mfma_f32_16x16x32_bf16 v[28:31], v[170:173], v[186:189], v[28:31]
	v_mfma_f32_16x16x32_bf16 v[24:27], v[178:181], v[186:189], v[24:27]
	v_mfma_f32_16x16x32_bf16 v[20:23], v[170:173], v[194:197], v[20:23]
	v_mfma_f32_16x16x32_bf16 v[16:19], v[178:181], v[194:197], v[16:19]
	v_mfma_f32_16x16x32_bf16 v[12:15], v[170:173], v[202:205], v[12:15]
	v_mfma_f32_16x16x32_bf16 v[8:11], v[178:181], v[202:205], v[8:11]
	v_mfma_f32_16x16x32_bf16 v[4:7], v[170:173], v[210:213], v[4:7]
	v_mfma_f32_16x16x32_bf16 v[0:3], v[178:181], v[210:213], v[0:3]
	v_mfma_f32_16x16x32_bf16 v[28:31], v[174:177], v[190:193], v[28:31]
	v_mfma_f32_16x16x32_bf16 v[24:27], v[182:185], v[190:193], v[24:27]
	v_mfma_f32_16x16x32_bf16 v[20:23], v[174:177], v[198:201], v[20:23]
	v_mfma_f32_16x16x32_bf16 v[16:19], v[182:185], v[198:201], v[16:19]
	v_mfma_f32_16x16x32_bf16 v[12:15], v[174:177], v[206:209], v[12:15]
	v_mfma_f32_16x16x32_bf16 v[8:11], v[182:185], v[206:209], v[8:11]
	v_mfma_f32_16x16x32_bf16 v[4:7], v[174:177], v[214:217], v[4:7]
	s_barrier
	v_mfma_f32_16x16x32_bf16 v[0:3], v[182:185], v[214:217], v[0:3]
	s_setprio 0
	s_add_i32 s64, 0, 0x18000
	s_add_i32 s65, 0, 0x1c000
	v_add_u32_e32 v158, s64, v165
	v_add_u32_e32 v182, s65, v165
	ds_read_b128 v[128:131], v158
	ds_read_b128 v[132:135], v158 offset:1024
	ds_read_b128 v[154:157], v158 offset:2048
	ds_read_b128 v[158:161], v158 offset:3072
	ds_read_b128 v[170:173], v182
	ds_read_b128 v[174:177], v182 offset:1024
	ds_read_b128 v[178:181], v182 offset:2048
	ds_read_b128 v[182:185], v182 offset:3072
	s_add_u32 s44, s44, 0x200000
	s_addc_u32 s45, s45, 0
	s_mov_b32 m0, s47
	v_lshl_add_u64 v[224:225], s[44:45], 0, v[136:137]
	ds_read_b128 v[186:189], v169 offset:32768
	ds_read_b128 v[190:193], v169 offset:33792
	ds_read_b128 v[194:197], v169 offset:34816
	ds_read_b128 v[198:201], v169 offset:35840
	ds_read_b128 v[202:205], v169 offset:36864
	ds_read_b128 v[206:209], v169 offset:37888
	ds_read_b128 v[210:213], v169 offset:38912
	ds_read_b128 v[214:217], v169 offset:39936
	global_load_lds_dwordx4 v[224:225], off
	v_lshl_add_u64 v[224:225], s[44:45], 0, v[140:141]
	s_mov_b32 m0, s48
	s_nop 0
	global_load_lds_dwordx4 v[224:225], off
	s_waitcnt vmcnt(8)
	s_waitcnt lgkmcnt(0)
	s_barrier
	s_setprio 1
	s_waitcnt lgkmcnt(0)
	v_mfma_f32_16x16x32_bf16 v[124:127], v[128:131], v[186:189], v[124:127]
	v_mfma_f32_16x16x32_bf16 v[120:123], v[154:157], v[186:189], v[120:123]
	v_mfma_f32_16x16x32_bf16 v[116:119], v[128:131], v[194:197], v[116:119]
	v_mfma_f32_16x16x32_bf16 v[112:115], v[154:157], v[194:197], v[112:115]
	v_mfma_f32_16x16x32_bf16 v[108:111], v[128:131], v[202:205], v[108:111]
	v_mfma_f32_16x16x32_bf16 v[104:107], v[154:157], v[202:205], v[104:107]
	v_mfma_f32_16x16x32_bf16 v[100:103], v[128:131], v[210:213], v[100:103]
	v_mfma_f32_16x16x32_bf16 v[96:99], v[154:157], v[210:213], v[96:99]
	v_mfma_f32_16x16x32_bf16 v[124:127], v[132:135], v[190:193], v[124:127]
	v_mfma_f32_16x16x32_bf16 v[120:123], v[158:161], v[190:193], v[120:123]
	v_mfma_f32_16x16x32_bf16 v[116:119], v[132:135], v[198:201], v[116:119]
	v_mfma_f32_16x16x32_bf16 v[112:115], v[158:161], v[198:201], v[112:115]
	v_mfma_f32_16x16x32_bf16 v[108:111], v[132:135], v[206:209], v[108:111]
	v_mfma_f32_16x16x32_bf16 v[104:107], v[158:161], v[206:209], v[104:107]
	v_mfma_f32_16x16x32_bf16 v[100:103], v[132:135], v[214:217], v[100:103]
	v_mfma_f32_16x16x32_bf16 v[96:99], v[158:161], v[214:217], v[96:99]
	s_setprio 0
	s_setprio 1
	v_mfma_f32_16x16x32_bf16 v[68:71], v[170:173], v[186:189], v[68:71]
	v_mfma_f32_16x16x32_bf16 v[60:63], v[178:181], v[186:189], v[60:63]
	v_mfma_f32_16x16x32_bf16 v[52:55], v[170:173], v[194:197], v[52:55]
	v_mfma_f32_16x16x32_bf16 v[48:51], v[178:181], v[194:197], v[48:51]
	v_mfma_f32_16x16x32_bf16 v[44:47], v[170:173], v[202:205], v[44:47]
	v_mfma_f32_16x16x32_bf16 v[40:43], v[178:181], v[202:205], v[40:43]
	v_mfma_f32_16x16x32_bf16 v[36:39], v[170:173], v[210:213], v[36:39]
	v_mfma_f32_16x16x32_bf16 v[32:35], v[178:181], v[210:213], v[32:35]
	v_mfma_f32_16x16x32_bf16 v[68:71], v[174:177], v[190:193], v[68:71]
	v_mfma_f32_16x16x32_bf16 v[60:63], v[182:185], v[190:193], v[60:63]
	v_mfma_f32_16x16x32_bf16 v[52:55], v[174:177], v[198:201], v[52:55]
	v_mfma_f32_16x16x32_bf16 v[48:51], v[182:185], v[198:201], v[48:51]
	v_mfma_f32_16x16x32_bf16 v[44:47], v[174:177], v[206:209], v[44:47]
	v_mfma_f32_16x16x32_bf16 v[40:43], v[182:185], v[206:209], v[40:43]
	v_mfma_f32_16x16x32_bf16 v[36:39], v[174:177], v[214:217], v[36:39]
	s_barrier
; #define PG8_STAGE(bufoff, gbase, voff) do { _Pragma("unroll") for (int _i = 0; _i < 2; ++_i) \
;         __builtin_amdgcn_global_load_lds((const unsigned*)((const char*)(gbase) + (voff)[_i]), (PG8_LAS unsigned*)(lds + (bufoff) + ldsw + _i * 8192), 16, 0, 0); } while (0)
; #define PG8_LDA(dst, b, h) do { _Pragma("unroll") for (int m = 0; m < 4; ++m) _Pragma("unroll") for (int k = 0; k < 2; ++k) dst[m][k] = *(const PG8_LAS bf16x8*)(lds + PG8_SA(b, h) + aoff + m * 2048 + k * 1024); } while (0)
; #define PG8_MMA(ai, bj, At, Bt) do { __builtin_amdgcn_s_setprio(1); _Pragma("unroll") for (int m = 0; m < 4; ++m) _Pragma("unroll") for (int n = 0; n < 2; ++n) _Pragma("unroll") for (int k = 0; k < 2; ++k) \
;         acc[ai][bj][m][n] = __builtin_amdgcn_mfma_f32_16x16x32_bf16(Bt[n][k], At[m][k], acc[ai][bj][m][n], 0, 0, 0); __builtin_amdgcn_s_setprio(0); } while (0)
; #define PG8_WAIT_V(n) asm volatile("s_waitcnt vmcnt(" #n ")" ::: "memory")
; #define PG8_WAIT_L(n) asm volatile("s_waitcnt lgkmcnt(" #n ")" ::: "memory")
; #define PG8_BAR __builtin_amdgcn_s_barrier()
; #define PG8_SCHED __builtin_amdgcn_sched_barrier(0)
; template <class Epi, class Sched, bool ALIGN_EPI = false, bool SP2 = false>
; __device__ __forceinline__ void gemm_phase(PG8_LAS unsigned char* lds, const Gemm g, const Sched& S, const Epi& E) {
;     ...
;             PG8_WAIT_V(8); PG8_WAIT_L(0); PG8_BAR; PG8_MMA(0, 0, At, B0); PG8_MMA(0, 1, At, B1); PG8_BAR; PG8_SCHED;
;             PG8_LDA(At, 1, 1); PG8_STAGE(PG8_SB(1, 0), b3, voffB); PG8_STAGE(PG8_SB(1, 1), b3 + hstep, voffB); PG8_STAGE(PG8_SA(1, 0), a3, voffA);
;             PG8_WAIT_V(8); PG8_WAIT_L(0); PG8_BAR; PG8_MMA(1, 0, At, B0); PG8_MMA(1, 1, At, B1); PG8_BAR; PG8_SCHED;
;     ...
;         if constexpr (ALIGN_EPI) { if (wr == 0) PG8_BAR; }
	v_mfma_f32_16x16x32_bf16 v[32:35], v[182:185], v[214:217], v[32:35]
	s_setprio 0
	s_add_i32 s44, s64, s33
	v_lshl_add_u64 v[162:163], v[162:163], 0, s[8:9]
	s_mov_b32 m0, s44
	ds_read_b128 v[186:189], v169 offset:49152
	ds_read_b128 v[190:193], v169 offset:50176
	ds_read_b128 v[194:197], v169 offset:51200
	ds_read_b128 v[198:201], v169 offset:52224
	ds_read_b128 v[202:205], v169 offset:53248
	ds_read_b128 v[206:209], v169 offset:54272
	ds_read_b128 v[210:213], v169 offset:55296
	ds_read_b128 v[214:217], v169 offset:56320
	global_load_lds_dwordx4 v[162:163], off
	s_add_i32 m0, s44, 0x2000
	s_add_u32 s42, s42, 0x200080
	v_lshl_add_u64 v[162:163], v[218:219], 0, s[8:9]
	s_addc_u32 s43, s43, 0
	s_add_i32 s44, s65, s33
	global_load_lds_dwordx4 v[162:163], off
	v_lshl_add_u64 v[162:163], s[42:43], 0, v[138:139]
	s_mov_b32 m0, s44
	s_nop 0
	global_load_lds_dwordx4 v[162:163], off
	v_lshl_add_u64 v[162:163], s[42:43], 0, v[142:143]
	s_add_i32 m0, s44, 0x2000
	s_nop 0
	global_load_lds_dwordx4 v[162:163], off
	v_lshl_add_u64 v[162:163], v[220:221], 0, s[8:9]
	s_mov_b32 m0, s52
	s_nop 0
	global_load_lds_dwordx4 v[162:163], off
	v_lshl_add_u64 v[162:163], v[222:223], 0, s[8:9]
	s_mov_b32 m0, s53
	s_nop 0
	global_load_lds_dwordx4 v[162:163], off
	s_waitcnt vmcnt(8)
	s_waitcnt lgkmcnt(0)
	s_barrier
	s_setprio 1
	s_waitcnt lgkmcnt(0)
	v_mfma_f32_16x16x32_bf16 v[92:95], v[128:131], v[186:189], v[92:95]
	v_mfma_f32_16x16x32_bf16 v[88:91], v[154:157], v[186:189], v[88:91]
	v_mfma_f32_16x16x32_bf16 v[84:87], v[128:131], v[194:197], v[84:87]
	v_mfma_f32_16x16x32_bf16 v[80:83], v[154:157], v[194:197], v[80:83]
	v_mfma_f32_16x16x32_bf16 v[76:79], v[128:131], v[202:205], v[76:79]
	v_mfma_f32_16x16x32_bf16 v[72:75], v[154:157], v[202:205], v[72:75]
	v_mfma_f32_16x16x32_bf16 v[64:67], v[128:131], v[210:213], v[64:67]
	v_mfma_f32_16x16x32_bf16 v[56:59], v[154:157], v[210:213], v[56:59]
	v_mfma_f32_16x16x32_bf16 v[92:95], v[132:135], v[190:193], v[92:95]
	v_mfma_f32_16x16x32_bf16 v[88:91], v[158:161], v[190:193], v[88:91]
	v_mfma_f32_16x16x32_bf16 v[84:87], v[132:135], v[198:201], v[84:87]
	v_mfma_f32_16x16x32_bf16 v[80:83], v[158:161], v[198:201], v[80:83]
	v_mfma_f32_16x16x32_bf16 v[76:79], v[132:135], v[206:209], v[76:79]
	v_mfma_f32_16x16x32_bf16 v[72:75], v[158:161], v[206:209], v[72:75]
	v_mfma_f32_16x16x32_bf16 v[64:67], v[132:135], v[214:217], v[64:67]
	v_mfma_f32_16x16x32_bf16 v[56:59], v[158:161], v[214:217], v[56:59]
	s_setprio 0
	s_setprio 1
	v_mfma_f32_16x16x32_bf16 v[28:31], v[170:173], v[186:189], v[28:31]
	v_mfma_f32_16x16x32_bf16 v[24:27], v[178:181], v[186:189], v[24:27]
	v_mfma_f32_16x16x32_bf16 v[20:23], v[170:173], v[194:197], v[20:23]
	v_mfma_f32_16x16x32_bf16 v[16:19], v[178:181], v[194:197], v[16:19]
	v_mfma_f32_16x16x32_bf16 v[12:15], v[170:173], v[202:205], v[12:15]
	v_mfma_f32_16x16x32_bf16 v[8:11], v[178:181], v[202:205], v[8:11]
	v_mfma_f32_16x16x32_bf16 v[4:7], v[170:173], v[210:213], v[4:7]
	v_mfma_f32_16x16x32_bf16 v[0:3], v[178:181], v[210:213], v[0:3]
	v_mfma_f32_16x16x32_bf16 v[28:31], v[174:177], v[190:193], v[28:31]
	v_mfma_f32_16x16x32_bf16 v[24:27], v[182:185], v[190:193], v[24:27]
	v_mfma_f32_16x16x32_bf16 v[20:23], v[174:177], v[198:201], v[20:23]
	v_mfma_f32_16x16x32_bf16 v[16:19], v[182:185], v[198:201], v[16:19]
	v_mfma_f32_16x16x32_bf16 v[12:15], v[174:177], v[206:209], v[12:15]
	v_mfma_f32_16x16x32_bf16 v[8:11], v[182:185], v[206:209], v[8:11]
	v_mfma_f32_16x16x32_bf16 v[4:7], v[174:177], v[214:217], v[4:7]
	s_barrier
	v_mfma_f32_16x16x32_bf16 v[0:3], v[182:185], v[214:217], v[0:3]
	s_setprio 0
	s_add_i32 s63, s63, 2
	s_add_u32 s40, s40, 0x100
	s_addc_u32 s41, s41, 0
	s_add_u32 s61, s61, 0x100
	s_addc_u32 s62, s62, 0
	s_cmpk_gt_u32 s63, 0x7d
	s_cbranch_scc0 .LBB0_1219
	s_and_b64 vcc, exec, s[10:11]
	s_cbranch_vccz .LBB0_1222
	s_barrier
